# v5 plus snake MFMA order inside each 8-MFMA k-block (one operand changes per step)
# speedup vs baseline: 1.0037x; 1.0037x over previous
; #define PG8_STAGE(bufoff, gbase, voff) do { _Pragma("unroll") for (int _i = 0; _i < 2; ++_i) \
;         __builtin_amdgcn_global_load_lds((const unsigned*)((const char*)(gbase) + (voff)[_i]), (PG8_LAS unsigned*)(lds + (bufoff) + ldsw + _i * 8192), 16, 0, 0); } while (0)
; #define PG8_LDA(dst, b, h) do { _Pragma("unroll") for (int m = 0; m < 4; ++m) _Pragma("unroll") for (int k = 0; k < 2; ++k) dst[m][k] = *(const PG8_LAS bf16x8*)(lds + PG8_SA(b, h) + aoff + m * 2048 + k * 1024); } while (0)
; #define PG8_LDB(dst, b, h) do { _Pragma("unroll") for (int n = 0; n < 2; ++n) _Pragma("unroll") for (int k = 0; k < 2; ++k) dst[n][k] = *(const PG8_LAS bf16x8*)(lds + PG8_SB(b, h) + boff + n * 2048 + k * 1024); } while (0)
; #define PG8_MMA(ai, bj, At, Bt) do { __builtin_amdgcn_s_setprio(1); _Pragma("unroll") for (int m = 0; m < 4; ++m) _Pragma("unroll") for (int n = 0; n < 2; ++n) _Pragma("unroll") for (int k = 0; k < 2; ++k) \
;         acc[ai][bj][m][n] = __builtin_amdgcn_mfma_f32_16x16x32_bf16(Bt[n][k], At[m][k], acc[ai][bj][m][n], 0, 0, 0); __builtin_amdgcn_s_setprio(0); } while (0)
; #define PG8_WAIT_V(n) asm volatile("s_waitcnt vmcnt(" #n ")" ::: "memory")
; #define PG8_WAIT_L(n) asm volatile("s_waitcnt lgkmcnt(" #n ")" ::: "memory")
; template <class Epi, class Sched, bool ALIGN_EPI = false, bool SP2 = false>
; __device__ __forceinline__ void gemm_phase(PG8_LAS unsigned char* lds, const Gemm g, const Sched& S, const Epi& E) {
;     ...
;             const bool last = (t == nt - 2);
;             const char* a1 = cA + (size_t)(t + 1) * kstep;
;             const char* a2 = last ? nA : cA + (size_t)(t + 2) * kstep; const char* b2 = last ? nB : cB + (size_t)(t + 2) * kstep;
;             const char* a3 = a2 + kstep; const char* b3 = b2 + kstep;
;             if (last && has_next) S.a_ready(nxt);
;             if constexpr (SP2) {
;             PG8_LDB(B0, 0, 0); PG8_LDB(B1, 0, 1); PG8_SCHED; PG8_LDA(At, 0, 0); PG8_STAGE(PG8_SA(1, 1), a1 + hstep, voffA);
;             PG8_WAIT_V(8); PG8_WAIT_L(0); PG8_BAR; PG8_MMA(0, 0, At, B0); PG8_MMA(0, 1, At, B1); PG8_BAR; PG8_SCHED;
;             PG8_LDA(At, 0, 1); PG8_STAGE(PG8_SB(0, 0), b2, voffB); PG8_STAGE(PG8_SB(0, 1), b2 + hstep, voffB); PG8_STAGE(PG8_SA(0, 0), a2, voffA);
;             PG8_WAIT_V(8); PG8_WAIT_L(0); PG8_BAR; PG8_MMA(1, 0, At, B0); PG8_MMA(1, 1, At, B1); PG8_BAR; PG8_SCHED;
.LBB0_816:
	s_add_u32 s0, s50, 0xfff00080
	s_addc_u32 s1, s51, -1
	s_add_i32 s61, 0, 0x10000
	s_cmp_eq_u32 s60, 60
	s_cselect_b32 s27, s47, s1
	s_cselect_b32 s26, s46, s0
	s_cselect_b32 s1, s49, s45
	s_cselect_b32 s0, s48, s43
	s_add_i32 s64, 0, 0x14000
	ds_read_b128 v[142:145], v198
	ds_read_b128 v[146:149], v198 offset:1024
	ds_read_b128 v[154:157], v198 offset:2048
	ds_read_b128 v[158:161], v198 offset:3072
	ds_read_b128 v[162:165], v198 offset:16384
	ds_read_b128 v[166:169], v198 offset:17408
	ds_read_b128 v[170:173], v198 offset:18432
	ds_read_b128 v[174:177], v198 offset:19456
	s_add_i32 m0, s9, 0xc000
	ds_read_b128 v[178:181], v153
	ds_read_b128 v[182:185], v153 offset:1024
	ds_read_b128 v[186:189], v153 offset:2048
	ds_read_b128 v[190:193], v153 offset:3072
	ds_read_b128 v[194:197], v153 offset:4096
	ds_read_b128 v[214:217], v153 offset:5120
	ds_read_b128 v[218:221], v153 offset:6144
	ds_read_b128 v[234:237], v153 offset:7168
	global_load_lds_dwordx4 v138, s[50:51]
	s_add_i32 m0, s9, 0xe000
	s_nop 0
	global_load_lds_dwordx4 v140, s[50:51]
	s_waitcnt vmcnt(8)
	s_waitcnt lgkmcnt(0)
	s_setprio 1
	s_barrier
	v_mfma_f32_16x16x32_bf16 v[128:131], v[142:145], v[178:181], v[128:131]
	v_mfma_f32_16x16x32_bf16 v[124:127], v[154:157], v[178:181], v[124:127]
	v_mfma_f32_16x16x32_bf16 v[108:111], v[154:157], v[186:189], v[108:111]
	v_mfma_f32_16x16x32_bf16 v[116:119], v[142:145], v[186:189], v[116:119]
	v_mfma_f32_16x16x32_bf16 v[100:103], v[142:145], v[194:197], v[100:103]
	v_mfma_f32_16x16x32_bf16 v[92:95], v[154:157], v[194:197], v[92:95]
	v_mfma_f32_16x16x32_bf16 v[76:79], v[154:157], v[218:221], v[76:79]
	v_mfma_f32_16x16x32_bf16 v[84:87], v[142:145], v[218:221], v[84:87]
	v_mfma_f32_16x16x32_bf16 v[128:131], v[146:149], v[182:185], v[128:131]
	v_mfma_f32_16x16x32_bf16 v[124:127], v[158:161], v[182:185], v[124:127]
	v_mfma_f32_16x16x32_bf16 v[108:111], v[158:161], v[190:193], v[108:111]
	v_mfma_f32_16x16x32_bf16 v[116:119], v[146:149], v[190:193], v[116:119]
	v_mfma_f32_16x16x32_bf16 v[100:103], v[146:149], v[214:217], v[100:103]
	v_mfma_f32_16x16x32_bf16 v[92:95], v[158:161], v[214:217], v[92:95]
	v_mfma_f32_16x16x32_bf16 v[76:79], v[158:161], v[234:237], v[76:79]
	v_mfma_f32_16x16x32_bf16 v[84:87], v[146:149], v[234:237], v[84:87]
	s_setprio 0
	s_setprio 1
	v_mfma_f32_16x16x32_bf16 v[120:123], v[162:165], v[178:181], v[120:123]
	v_mfma_f32_16x16x32_bf16 v[112:115], v[170:173], v[178:181], v[112:115]
	v_mfma_f32_16x16x32_bf16 v[96:99], v[170:173], v[186:189], v[96:99]
	v_mfma_f32_16x16x32_bf16 v[104:107], v[162:165], v[186:189], v[104:107]
	v_mfma_f32_16x16x32_bf16 v[88:91], v[162:165], v[194:197], v[88:91]
	v_mfma_f32_16x16x32_bf16 v[80:83], v[170:173], v[194:197], v[80:83]
	v_mfma_f32_16x16x32_bf16 v[68:71], v[170:173], v[218:221], v[68:71]
	v_mfma_f32_16x16x32_bf16 v[72:75], v[162:165], v[218:221], v[72:75]
	v_mfma_f32_16x16x32_bf16 v[120:123], v[166:169], v[182:185], v[120:123]
	v_mfma_f32_16x16x32_bf16 v[112:115], v[174:177], v[182:185], v[112:115]
	v_mfma_f32_16x16x32_bf16 v[96:99], v[174:177], v[190:193], v[96:99]
	v_mfma_f32_16x16x32_bf16 v[104:107], v[166:169], v[190:193], v[104:107]
	v_mfma_f32_16x16x32_bf16 v[88:91], v[166:169], v[214:217], v[88:91]
	v_mfma_f32_16x16x32_bf16 v[80:83], v[174:177], v[214:217], v[80:83]
	v_mfma_f32_16x16x32_bf16 v[68:71], v[174:177], v[234:237], v[68:71]
	v_mfma_f32_16x16x32_bf16 v[72:75], v[166:169], v[234:237], v[72:75]
	s_barrier
	s_setprio 0
	s_add_i32 s61, s61, s8
	s_mov_b32 m0, s61
	ds_read_b128 v[178:181], v153 offset:16384
	ds_read_b128 v[182:185], v153 offset:17408
	ds_read_b128 v[186:189], v153 offset:18432
	ds_read_b128 v[190:193], v153 offset:19456
	ds_read_b128 v[194:197], v153 offset:20480
	ds_read_b128 v[214:217], v153 offset:21504
	ds_read_b128 v[218:221], v153 offset:22528
	ds_read_b128 v[234:237], v153 offset:23552
	global_load_lds_dwordx4 v2, s[0:1]
	s_add_i32 m0, s61, 0x2000
	s_add_u32 s62, s0, 0x100000
	s_addc_u32 s63, s1, 0
	s_add_i32 s61, s64, s8
	global_load_lds_dwordx4 v132, s[0:1]
	s_mov_b32 m0, s61
	s_nop 0
	global_load_lds_dwordx4 v2, s[62:63]
	s_add_i32 m0, s61, 0x2000
	s_nop 0
	global_load_lds_dwordx4 v132, s[62:63]
	s_mov_b32 m0, s9
	s_nop 0
	global_load_lds_dwordx4 v136, s[26:27]
	s_mov_b32 m0, s10
	s_nop 0
	global_load_lds_dwordx4 v134, s[26:27]
	s_add_u32 s100, s26, 0x80
	s_addc_u32 s101, s27, 0
	s_waitcnt vmcnt(8)
	s_waitcnt lgkmcnt(0)
	s_setprio 1
	s_barrier
	v_mfma_f32_16x16x32_bf16 v[64:67], v[142:145], v[178:181], v[64:67]
	v_mfma_f32_16x16x32_bf16 v[60:63], v[154:157], v[178:181], v[60:63]
	v_mfma_f32_16x16x32_bf16 v[44:47], v[154:157], v[186:189], v[44:47]
	v_mfma_f32_16x16x32_bf16 v[52:55], v[142:145], v[186:189], v[52:55]
	v_mfma_f32_16x16x32_bf16 v[36:39], v[142:145], v[194:197], v[36:39]
	v_mfma_f32_16x16x32_bf16 v[28:31], v[154:157], v[194:197], v[28:31]
	v_mfma_f32_16x16x32_bf16 v[12:15], v[154:157], v[218:221], v[12:15]
	v_mfma_f32_16x16x32_bf16 v[16:19], v[142:145], v[218:221], v[16:19]
	v_mfma_f32_16x16x32_bf16 v[64:67], v[146:149], v[182:185], v[64:67]
	v_mfma_f32_16x16x32_bf16 v[60:63], v[158:161], v[182:185], v[60:63]
	v_mfma_f32_16x16x32_bf16 v[44:47], v[158:161], v[190:193], v[44:47]
	v_mfma_f32_16x16x32_bf16 v[52:55], v[146:149], v[190:193], v[52:55]
	v_mfma_f32_16x16x32_bf16 v[36:39], v[146:149], v[214:217], v[36:39]
	v_mfma_f32_16x16x32_bf16 v[28:31], v[158:161], v[214:217], v[28:31]
	v_mfma_f32_16x16x32_bf16 v[12:15], v[158:161], v[234:237], v[12:15]
	v_mfma_f32_16x16x32_bf16 v[16:19], v[146:149], v[234:237], v[16:19]
	s_setprio 0
	s_setprio 1
	v_mfma_f32_16x16x32_bf16 v[56:59], v[162:165], v[178:181], v[56:59]
	v_mfma_f32_16x16x32_bf16 v[48:51], v[170:173], v[178:181], v[48:51]
	v_mfma_f32_16x16x32_bf16 v[32:35], v[170:173], v[186:189], v[32:35]
	v_mfma_f32_16x16x32_bf16 v[40:43], v[162:165], v[186:189], v[40:43]
	v_mfma_f32_16x16x32_bf16 v[24:27], v[162:165], v[194:197], v[24:27]
	v_mfma_f32_16x16x32_bf16 v[20:23], v[170:173], v[194:197], v[20:23]
	v_mfma_f32_16x16x32_bf16 v[4:7], v[170:173], v[218:221], v[4:7]
	v_mfma_f32_16x16x32_bf16 v[8:11], v[162:165], v[218:221], v[8:11]
	v_mfma_f32_16x16x32_bf16 v[56:59], v[166:169], v[182:185], v[56:59]
	v_mfma_f32_16x16x32_bf16 v[48:51], v[174:177], v[182:185], v[48:51]
	v_mfma_f32_16x16x32_bf16 v[32:35], v[174:177], v[190:193], v[32:35]
	v_mfma_f32_16x16x32_bf16 v[40:43], v[166:169], v[190:193], v[40:43]
	v_mfma_f32_16x16x32_bf16 v[24:27], v[166:169], v[214:217], v[24:27]
	v_mfma_f32_16x16x32_bf16 v[20:23], v[174:177], v[214:217], v[20:23]
	v_mfma_f32_16x16x32_bf16 v[4:7], v[174:177], v[234:237], v[4:7]
	v_mfma_f32_16x16x32_bf16 v[8:11], v[166:169], v[234:237], v[8:11]
	s_barrier
; #define PG8_STAGE(bufoff, gbase, voff) do { _Pragma("unroll") for (int _i = 0; _i < 2; ++_i) \
;         __builtin_amdgcn_global_load_lds((const unsigned*)((const char*)(gbase) + (voff)[_i]), (PG8_LAS unsigned*)(lds + (bufoff) + ldsw + _i * 8192), 16, 0, 0); } while (0)
; #define PG8_LDA(dst, b, h) do { _Pragma("unroll") for (int m = 0; m < 4; ++m) _Pragma("unroll") for (int k = 0; k < 2; ++k) dst[m][k] = *(const PG8_LAS bf16x8*)(lds + PG8_SA(b, h) + aoff + m * 2048 + k * 1024); } while (0)
; #define PG8_LDB(dst, b, h) do { _Pragma("unroll") for (int n = 0; n < 2; ++n) _Pragma("unroll") for (int k = 0; k < 2; ++k) dst[n][k] = *(const PG8_LAS bf16x8*)(lds + PG8_SB(b, h) + boff + n * 2048 + k * 1024); } while (0)
; #define PG8_MMA(ai, bj, At, Bt) do { __builtin_amdgcn_s_setprio(1); _Pragma("unroll") for (int m = 0; m < 4; ++m) _Pragma("unroll") for (int n = 0; n < 2; ++n) _Pragma("unroll") for (int k = 0; k < 2; ++k) \
;         acc[ai][bj][m][n] = __builtin_amdgcn_mfma_f32_16x16x32_bf16(Bt[n][k], At[m][k], acc[ai][bj][m][n], 0, 0, 0); __builtin_amdgcn_s_setprio(0); } while (0)
; #define PG8_WAIT_V(n) asm volatile("s_waitcnt vmcnt(" #n ")" ::: "memory")
; #define PG8_WAIT_L(n) asm volatile("s_waitcnt lgkmcnt(" #n ")" ::: "memory")
; #define PG8_BAR __builtin_amdgcn_s_barrier()
; #define PG8_SCHED __builtin_amdgcn_sched_barrier(0)
; template <class Epi, class Sched, bool ALIGN_EPI = false, bool SP2 = false>
; __device__ __forceinline__ void gemm_phase(PG8_LAS unsigned char* lds, const Gemm g, const Sched& S, const Epi& E) {
;     ...
;             PG8_LDB(B0, 1, 0); PG8_LDB(B1, 1, 1); PG8_SCHED; PG8_LDA(At, 1, 0); PG8_STAGE(PG8_SA(0, 1), a2 + hstep, voffA);
;             PG8_WAIT_V(8); PG8_WAIT_L(0); PG8_BAR; PG8_MMA(0, 0, At, B0); PG8_MMA(0, 1, At, B1); PG8_BAR; PG8_SCHED;
;             PG8_LDA(At, 1, 1); PG8_STAGE(PG8_SB(1, 0), b3, voffB); PG8_STAGE(PG8_SB(1, 1), b3 + hstep, voffB); PG8_STAGE(PG8_SA(1, 0), a3, voffA);
;             PG8_WAIT_V(8); PG8_WAIT_L(0); PG8_BAR; PG8_MMA(1, 0, At, B0); PG8_MMA(1, 1, At, B1); PG8_BAR; PG8_SCHED;
	s_setprio 0
	s_add_i32 s61, 0, 0x18000
	s_add_i32 s62, 0, 0x1c000
	ds_read_b128 v[142:145], v198 offset:32768
	ds_read_b128 v[146:149], v198 offset:33792
	ds_read_b128 v[154:157], v198 offset:34816
	ds_read_b128 v[158:161], v198 offset:35840
	ds_read_b128 v[162:165], v198 offset:49152
	ds_read_b128 v[166:169], v198 offset:50176
	ds_read_b128 v[170:173], v198 offset:51200
	ds_read_b128 v[174:177], v198 offset:52224
	s_add_u32 s26, s26, 0x100000
	s_addc_u32 s27, s27, 0
	s_mov_b32 m0, s11
	ds_read_b128 v[178:181], v153 offset:32768
	ds_read_b128 v[182:185], v153 offset:33792
	ds_read_b128 v[186:189], v153 offset:34816
	ds_read_b128 v[190:193], v153 offset:35840
	ds_read_b128 v[194:197], v153 offset:36864
	ds_read_b128 v[214:217], v153 offset:37888
	ds_read_b128 v[218:221], v153 offset:38912
	ds_read_b128 v[234:237], v153 offset:39936
	global_load_lds_dwordx4 v136, s[26:27]
	s_mov_b32 m0, s52
	s_nop 0
	global_load_lds_dwordx4 v134, s[26:27]
	s_waitcnt vmcnt(8)
	s_waitcnt lgkmcnt(0)
	s_setprio 1
	s_barrier
	v_mfma_f32_16x16x32_bf16 v[128:131], v[142:145], v[178:181], v[128:131]
	v_mfma_f32_16x16x32_bf16 v[124:127], v[154:157], v[178:181], v[124:127]
	v_mfma_f32_16x16x32_bf16 v[108:111], v[154:157], v[186:189], v[108:111]
	v_mfma_f32_16x16x32_bf16 v[116:119], v[142:145], v[186:189], v[116:119]
	v_mfma_f32_16x16x32_bf16 v[100:103], v[142:145], v[194:197], v[100:103]
	v_mfma_f32_16x16x32_bf16 v[92:95], v[154:157], v[194:197], v[92:95]
	v_mfma_f32_16x16x32_bf16 v[76:79], v[154:157], v[218:221], v[76:79]
	v_mfma_f32_16x16x32_bf16 v[84:87], v[142:145], v[218:221], v[84:87]
	v_mfma_f32_16x16x32_bf16 v[128:131], v[146:149], v[182:185], v[128:131]
	v_mfma_f32_16x16x32_bf16 v[124:127], v[158:161], v[182:185], v[124:127]
	v_mfma_f32_16x16x32_bf16 v[108:111], v[158:161], v[190:193], v[108:111]
	v_mfma_f32_16x16x32_bf16 v[116:119], v[146:149], v[190:193], v[116:119]
	v_mfma_f32_16x16x32_bf16 v[100:103], v[146:149], v[214:217], v[100:103]
	v_mfma_f32_16x16x32_bf16 v[92:95], v[158:161], v[214:217], v[92:95]
	v_mfma_f32_16x16x32_bf16 v[76:79], v[158:161], v[234:237], v[76:79]
	v_mfma_f32_16x16x32_bf16 v[84:87], v[146:149], v[234:237], v[84:87]
	s_setprio 0
	s_setprio 1
	v_mfma_f32_16x16x32_bf16 v[120:123], v[162:165], v[178:181], v[120:123]
	v_mfma_f32_16x16x32_bf16 v[112:115], v[170:173], v[178:181], v[112:115]
	v_mfma_f32_16x16x32_bf16 v[96:99], v[170:173], v[186:189], v[96:99]
	v_mfma_f32_16x16x32_bf16 v[104:107], v[162:165], v[186:189], v[104:107]
	v_mfma_f32_16x16x32_bf16 v[88:91], v[162:165], v[194:197], v[88:91]
	v_mfma_f32_16x16x32_bf16 v[80:83], v[170:173], v[194:197], v[80:83]
	v_mfma_f32_16x16x32_bf16 v[68:71], v[170:173], v[218:221], v[68:71]
	v_mfma_f32_16x16x32_bf16 v[72:75], v[162:165], v[218:221], v[72:75]
	v_mfma_f32_16x16x32_bf16 v[120:123], v[166:169], v[182:185], v[120:123]
	v_mfma_f32_16x16x32_bf16 v[112:115], v[174:177], v[182:185], v[112:115]
	v_mfma_f32_16x16x32_bf16 v[96:99], v[174:177], v[190:193], v[96:99]
	v_mfma_f32_16x16x32_bf16 v[104:107], v[166:169], v[190:193], v[104:107]
	v_mfma_f32_16x16x32_bf16 v[88:91], v[166:169], v[214:217], v[88:91]
	v_mfma_f32_16x16x32_bf16 v[80:83], v[174:177], v[214:217], v[80:83]
	v_mfma_f32_16x16x32_bf16 v[68:71], v[174:177], v[234:237], v[68:71]
	v_mfma_f32_16x16x32_bf16 v[72:75], v[166:169], v[234:237], v[72:75]
	s_barrier
	s_setprio 0
	s_add_i32 s26, s61, s8
	s_mov_b32 m0, s26
	ds_read_b128 v[178:181], v153 offset:49152
	ds_read_b128 v[182:185], v153 offset:50176
	ds_read_b128 v[186:189], v153 offset:51200
	ds_read_b128 v[190:193], v153 offset:52224
	ds_read_b128 v[194:197], v153 offset:53248
	ds_read_b128 v[214:217], v153 offset:54272
	ds_read_b128 v[218:221], v153 offset:55296
	ds_read_b128 v[234:237], v153 offset:56320
	s_add_u32 s0, s0, 0x80
	s_addc_u32 s1, s1, 0
	global_load_lds_dwordx4 v2, s[0:1]
	s_add_i32 m0, s26, 0x2000
	s_add_i32 s26, s62, s8
	global_load_lds_dwordx4 v132, s[0:1]
	s_add_u32 s0, s0, 0x100000
	s_addc_u32 s1, s1, 0
	s_mov_b32 m0, s26
	s_nop 0
	global_load_lds_dwordx4 v2, s[0:1]
	s_add_i32 m0, s26, 0x2000
	s_nop 0
	global_load_lds_dwordx4 v132, s[0:1]
	s_mov_b32 m0, s54
	s_nop 0
	global_load_lds_dwordx4 v136, s[100:101]
	s_mov_b32 m0, s55
	s_nop 0
	global_load_lds_dwordx4 v134, s[100:101]
	s_waitcnt vmcnt(8)
	s_waitcnt lgkmcnt(0)
	s_setprio 1
	s_barrier
	v_mfma_f32_16x16x32_bf16 v[64:67], v[142:145], v[178:181], v[64:67]
	v_mfma_f32_16x16x32_bf16 v[60:63], v[154:157], v[178:181], v[60:63]
	v_mfma_f32_16x16x32_bf16 v[44:47], v[154:157], v[186:189], v[44:47]
	v_mfma_f32_16x16x32_bf16 v[52:55], v[142:145], v[186:189], v[52:55]
	v_mfma_f32_16x16x32_bf16 v[36:39], v[142:145], v[194:197], v[36:39]
	v_mfma_f32_16x16x32_bf16 v[28:31], v[154:157], v[194:197], v[28:31]
	v_mfma_f32_16x16x32_bf16 v[12:15], v[154:157], v[218:221], v[12:15]
	v_mfma_f32_16x16x32_bf16 v[16:19], v[142:145], v[218:221], v[16:19]
	v_mfma_f32_16x16x32_bf16 v[64:67], v[146:149], v[182:185], v[64:67]
	v_mfma_f32_16x16x32_bf16 v[60:63], v[158:161], v[182:185], v[60:63]
	v_mfma_f32_16x16x32_bf16 v[44:47], v[158:161], v[190:193], v[44:47]
	v_mfma_f32_16x16x32_bf16 v[52:55], v[146:149], v[190:193], v[52:55]
	v_mfma_f32_16x16x32_bf16 v[36:39], v[146:149], v[214:217], v[36:39]
	v_mfma_f32_16x16x32_bf16 v[28:31], v[158:161], v[214:217], v[28:31]
	v_mfma_f32_16x16x32_bf16 v[12:15], v[158:161], v[234:237], v[12:15]
	v_mfma_f32_16x16x32_bf16 v[16:19], v[146:149], v[234:237], v[16:19]
	s_setprio 0
	s_setprio 1
	v_mfma_f32_16x16x32_bf16 v[56:59], v[162:165], v[178:181], v[56:59]
	v_mfma_f32_16x16x32_bf16 v[48:51], v[170:173], v[178:181], v[48:51]
	v_mfma_f32_16x16x32_bf16 v[32:35], v[170:173], v[186:189], v[32:35]
	v_mfma_f32_16x16x32_bf16 v[40:43], v[162:165], v[186:189], v[40:43]
	v_mfma_f32_16x16x32_bf16 v[24:27], v[162:165], v[194:197], v[24:27]
	v_mfma_f32_16x16x32_bf16 v[20:23], v[170:173], v[194:197], v[20:23]
	v_mfma_f32_16x16x32_bf16 v[4:7], v[170:173], v[218:221], v[4:7]
	v_mfma_f32_16x16x32_bf16 v[8:11], v[162:165], v[218:221], v[8:11]
	v_mfma_f32_16x16x32_bf16 v[56:59], v[166:169], v[182:185], v[56:59]
	v_mfma_f32_16x16x32_bf16 v[48:51], v[174:177], v[182:185], v[48:51]
	v_mfma_f32_16x16x32_bf16 v[32:35], v[174:177], v[190:193], v[32:35]
	v_mfma_f32_16x16x32_bf16 v[40:43], v[166:169], v[190:193], v[40:43]
	v_mfma_f32_16x16x32_bf16 v[24:27], v[166:169], v[214:217], v[24:27]
	v_mfma_f32_16x16x32_bf16 v[20:23], v[174:177], v[214:217], v[20:23]
	v_mfma_f32_16x16x32_bf16 v[4:7], v[174:177], v[234:237], v[4:7]
	v_mfma_f32_16x16x32_bf16 v[8:11], v[166:169], v[234:237], v[8:11]
	s_barrier
	s_setprio 0
	s_add_i32 s60, s60, 2
	s_add_u32 s50, s50, 0x100
	s_addc_u32 s51, s51, 0
	s_add_u32 s43, s43, 0x100
	s_addc_u32 s45, s45, 0
	s_cmp_gt_u32 s60, 61
	s_cbranch_scc0 .LBB0_816
	s_and_b64 vcc, exec, s[40:41]
	s_cbranch_vccz .LBB0_819
	s_barrier

; #define PG8_STAGE(bufoff, gbase, voff) do { _Pragma("unroll") for (int _i = 0; _i < 2; ++_i) \
;         __builtin_amdgcn_global_load_lds((const unsigned*)((const char*)(gbase) + (voff)[_i]), (PG8_LAS unsigned*)(lds + (bufoff) + ldsw + _i * 8192), 16, 0, 0); } while (0)
; #define PG8_LDA(dst, b, h) do { _Pragma("unroll") for (int m = 0; m < 4; ++m) _Pragma("unroll") for (int k = 0; k < 2; ++k) dst[m][k] = *(const PG8_LAS bf16x8*)(lds + PG8_SA(b, h) + aoff + m * 2048 + k * 1024); } while (0)
; #define PG8_LDB(dst, b, h) do { _Pragma("unroll") for (int n = 0; n < 2; ++n) _Pragma("unroll") for (int k = 0; k < 2; ++k) dst[n][k] = *(const PG8_LAS bf16x8*)(lds + PG8_SB(b, h) + boff + n * 2048 + k * 1024); } while (0)
; #define PG8_MMA(ai, bj, At, Bt) do { __builtin_amdgcn_s_setprio(1); _Pragma("unroll") for (int m = 0; m < 4; ++m) _Pragma("unroll") for (int n = 0; n < 2; ++n) _Pragma("unroll") for (int k = 0; k < 2; ++k) \
;         acc[ai][bj][m][n] = __builtin_amdgcn_mfma_f32_16x16x32_bf16(Bt[n][k], At[m][k], acc[ai][bj][m][n], 0, 0, 0); __builtin_amdgcn_s_setprio(0); } while (0)
; #define PG8_WAIT_V(n) asm volatile("s_waitcnt vmcnt(" #n ")" ::: "memory")
; #define PG8_WAIT_L(n) asm volatile("s_waitcnt lgkmcnt(" #n ")" ::: "memory")
; template <class Epi, class Sched, bool ALIGN_EPI = false, bool SP2 = false>
; __device__ __forceinline__ void gemm_phase(PG8_LAS unsigned char* lds, const Gemm g, const Sched& S, const Epi& E) {
;     ...
;             const bool last = (t == nt - 2);
;             const char* a1 = cA + (size_t)(t + 1) * kstep;
;             const char* a2 = last ? nA : cA + (size_t)(t + 2) * kstep; const char* b2 = last ? nB : cB + (size_t)(t + 2) * kstep;
;             const char* a3 = a2 + kstep; const char* b3 = b2 + kstep;
;             if (last && has_next) S.a_ready(nxt);
;             if constexpr (SP2) {
;             PG8_LDB(B0, 0, 0); PG8_LDB(B1, 0, 1); PG8_SCHED; PG8_LDA(At, 0, 0); PG8_STAGE(PG8_SA(1, 1), a1 + hstep, voffA);
;             PG8_WAIT_V(8); PG8_WAIT_L(0); PG8_BAR; PG8_MMA(0, 0, At, B0); PG8_MMA(0, 1, At, B1); PG8_BAR; PG8_SCHED;
;             PG8_LDA(At, 0, 1); PG8_STAGE(PG8_SB(0, 0), b2, voffB); PG8_STAGE(PG8_SB(0, 1), b2 + hstep, voffB); PG8_STAGE(PG8_SA(0, 0), a2, voffA);
;             PG8_WAIT_V(8); PG8_WAIT_L(0); PG8_BAR; PG8_MMA(1, 0, At, B0); PG8_MMA(1, 1, At, B1); PG8_BAR; PG8_SCHED;
.LBB0_1032:
	s_add_u32 s0, s50, 0xfffc0080
	s_addc_u32 s1, s51, -1
	s_add_i32 s53, 0, 0x10000
	s_cmp_eq_u32 s52, 12
	s_cselect_b32 s27, s47, s1
	s_cselect_b32 s26, s46, s0
	s_cselect_b32 s1, s49, s45
	s_cselect_b32 s0, s48, s43
	s_add_i32 s64, 0, 0x14000
	ds_read_b128 v[146:149], v198
	ds_read_b128 v[150:153], v198 offset:1024
	ds_read_b128 v[154:157], v198 offset:2048
	ds_read_b128 v[158:161], v198 offset:3072
	ds_read_b128 v[162:165], v198 offset:16384
	ds_read_b128 v[166:169], v198 offset:17408
	ds_read_b128 v[170:173], v198 offset:18432
	ds_read_b128 v[174:177], v198 offset:19456
	s_add_i32 m0, s37, 0xc000
	ds_read_b128 v[178:181], v145
	ds_read_b128 v[182:185], v145 offset:1024
	ds_read_b128 v[186:189], v145 offset:2048
	ds_read_b128 v[190:193], v145 offset:3072
	ds_read_b128 v[194:197], v145 offset:4096
	ds_read_b128 v[214:217], v145 offset:5120
	ds_read_b128 v[218:221], v145 offset:6144
	ds_read_b128 v[234:237], v145 offset:7168
	global_load_lds_dwordx4 v138, s[50:51]
	s_add_i32 m0, s37, 0xe000
	s_nop 0
	global_load_lds_dwordx4 v140, s[50:51]
	s_waitcnt vmcnt(8)
	s_waitcnt lgkmcnt(0)
	s_setprio 1
	s_barrier
	v_mfma_f32_16x16x32_bf16 v[128:131], v[146:149], v[178:181], v[128:131]
	v_mfma_f32_16x16x32_bf16 v[124:127], v[154:157], v[178:181], v[124:127]
	v_mfma_f32_16x16x32_bf16 v[116:119], v[154:157], v[186:189], v[116:119]
	v_mfma_f32_16x16x32_bf16 v[120:123], v[146:149], v[186:189], v[120:123]
	v_mfma_f32_16x16x32_bf16 v[104:107], v[146:149], v[194:197], v[104:107]
	v_mfma_f32_16x16x32_bf16 v[100:103], v[154:157], v[194:197], v[100:103]
	v_mfma_f32_16x16x32_bf16 v[84:87], v[154:157], v[218:221], v[84:87]
	v_mfma_f32_16x16x32_bf16 v[88:91], v[146:149], v[218:221], v[88:91]
	v_mfma_f32_16x16x32_bf16 v[128:131], v[150:153], v[182:185], v[128:131]
	v_mfma_f32_16x16x32_bf16 v[124:127], v[158:161], v[182:185], v[124:127]
	v_mfma_f32_16x16x32_bf16 v[116:119], v[158:161], v[190:193], v[116:119]
	v_mfma_f32_16x16x32_bf16 v[120:123], v[150:153], v[190:193], v[120:123]
	v_mfma_f32_16x16x32_bf16 v[104:107], v[150:153], v[214:217], v[104:107]
	v_mfma_f32_16x16x32_bf16 v[100:103], v[158:161], v[214:217], v[100:103]
	v_mfma_f32_16x16x32_bf16 v[84:87], v[158:161], v[234:237], v[84:87]
	v_mfma_f32_16x16x32_bf16 v[88:91], v[150:153], v[234:237], v[88:91]
	s_setprio 0
	s_setprio 1
	v_mfma_f32_16x16x32_bf16 v[112:115], v[162:165], v[178:181], v[112:115]
	v_mfma_f32_16x16x32_bf16 v[108:111], v[170:173], v[178:181], v[108:111]
	v_mfma_f32_16x16x32_bf16 v[92:95], v[170:173], v[186:189], v[92:95]
	v_mfma_f32_16x16x32_bf16 v[96:99], v[162:165], v[186:189], v[96:99]
	v_mfma_f32_16x16x32_bf16 v[80:83], v[162:165], v[194:197], v[80:83]
	v_mfma_f32_16x16x32_bf16 v[76:79], v[170:173], v[194:197], v[76:79]
	v_mfma_f32_16x16x32_bf16 v[68:71], v[170:173], v[218:221], v[68:71]
	v_mfma_f32_16x16x32_bf16 v[72:75], v[162:165], v[218:221], v[72:75]
	v_mfma_f32_16x16x32_bf16 v[112:115], v[166:169], v[182:185], v[112:115]
	v_mfma_f32_16x16x32_bf16 v[108:111], v[174:177], v[182:185], v[108:111]
	v_mfma_f32_16x16x32_bf16 v[92:95], v[174:177], v[190:193], v[92:95]
	v_mfma_f32_16x16x32_bf16 v[96:99], v[166:169], v[190:193], v[96:99]
	v_mfma_f32_16x16x32_bf16 v[80:83], v[166:169], v[214:217], v[80:83]
	v_mfma_f32_16x16x32_bf16 v[76:79], v[174:177], v[214:217], v[76:79]
	v_mfma_f32_16x16x32_bf16 v[68:71], v[174:177], v[234:237], v[68:71]
	v_mfma_f32_16x16x32_bf16 v[72:75], v[166:169], v[234:237], v[72:75]
	s_barrier
	s_setprio 0
	s_add_i32 s53, s53, s10
	s_mov_b32 m0, s53
	ds_read_b128 v[178:181], v145 offset:16384
	ds_read_b128 v[182:185], v145 offset:17408
	ds_read_b128 v[186:189], v145 offset:18432
	ds_read_b128 v[190:193], v145 offset:19456
	ds_read_b128 v[194:197], v145 offset:20480
	ds_read_b128 v[214:217], v145 offset:21504
	ds_read_b128 v[218:221], v145 offset:22528
	ds_read_b128 v[234:237], v145 offset:23552
	global_load_lds_dwordx4 v2, s[0:1]
	s_add_i32 m0, s53, 0x2000
	s_add_u32 s62, s0, 0x40000
	s_addc_u32 s63, s1, 0
	s_add_i32 s53, s64, s10
	global_load_lds_dwordx4 v132, s[0:1]
	s_mov_b32 m0, s53
	s_nop 0
	global_load_lds_dwordx4 v2, s[62:63]
	s_add_i32 m0, s53, 0x2000
	s_nop 0
	global_load_lds_dwordx4 v132, s[62:63]
	s_mov_b32 m0, s37
	s_nop 0
	global_load_lds_dwordx4 v136, s[26:27]
	s_mov_b32 m0, s54
	s_nop 0
	global_load_lds_dwordx4 v134, s[26:27]
	s_add_u32 s100, s26, 0x80
	s_addc_u32 s101, s27, 0
	s_waitcnt vmcnt(8)
	s_waitcnt lgkmcnt(0)
	s_setprio 1
	s_barrier
	v_mfma_f32_16x16x32_bf16 v[64:67], v[146:149], v[178:181], v[64:67]
	v_mfma_f32_16x16x32_bf16 v[60:63], v[154:157], v[178:181], v[60:63]
	v_mfma_f32_16x16x32_bf16 v[52:55], v[154:157], v[186:189], v[52:55]
	v_mfma_f32_16x16x32_bf16 v[56:59], v[146:149], v[186:189], v[56:59]
	v_mfma_f32_16x16x32_bf16 v[40:43], v[146:149], v[194:197], v[40:43]
	v_mfma_f32_16x16x32_bf16 v[36:39], v[154:157], v[194:197], v[36:39]
	v_mfma_f32_16x16x32_bf16 v[20:23], v[154:157], v[218:221], v[20:23]
	v_mfma_f32_16x16x32_bf16 v[24:27], v[146:149], v[218:221], v[24:27]
	v_mfma_f32_16x16x32_bf16 v[64:67], v[150:153], v[182:185], v[64:67]
	v_mfma_f32_16x16x32_bf16 v[60:63], v[158:161], v[182:185], v[60:63]
	v_mfma_f32_16x16x32_bf16 v[52:55], v[158:161], v[190:193], v[52:55]
	v_mfma_f32_16x16x32_bf16 v[56:59], v[150:153], v[190:193], v[56:59]
	v_mfma_f32_16x16x32_bf16 v[40:43], v[150:153], v[214:217], v[40:43]
	v_mfma_f32_16x16x32_bf16 v[36:39], v[158:161], v[214:217], v[36:39]
	v_mfma_f32_16x16x32_bf16 v[20:23], v[158:161], v[234:237], v[20:23]
	v_mfma_f32_16x16x32_bf16 v[24:27], v[150:153], v[234:237], v[24:27]
	s_setprio 0
	s_setprio 1
	v_mfma_f32_16x16x32_bf16 v[48:51], v[162:165], v[178:181], v[48:51]
	v_mfma_f32_16x16x32_bf16 v[44:47], v[170:173], v[178:181], v[44:47]
	v_mfma_f32_16x16x32_bf16 v[28:31], v[170:173], v[186:189], v[28:31]
	v_mfma_f32_16x16x32_bf16 v[32:35], v[162:165], v[186:189], v[32:35]
	v_mfma_f32_16x16x32_bf16 v[16:19], v[162:165], v[194:197], v[16:19]
	v_mfma_f32_16x16x32_bf16 v[12:15], v[170:173], v[194:197], v[12:15]
	v_mfma_f32_16x16x32_bf16 v[4:7], v[170:173], v[218:221], v[4:7]
	v_mfma_f32_16x16x32_bf16 v[8:11], v[162:165], v[218:221], v[8:11]
	v_mfma_f32_16x16x32_bf16 v[48:51], v[166:169], v[182:185], v[48:51]
	v_mfma_f32_16x16x32_bf16 v[44:47], v[174:177], v[182:185], v[44:47]
	v_mfma_f32_16x16x32_bf16 v[28:31], v[174:177], v[190:193], v[28:31]
	v_mfma_f32_16x16x32_bf16 v[32:35], v[166:169], v[190:193], v[32:35]
	v_mfma_f32_16x16x32_bf16 v[16:19], v[166:169], v[214:217], v[16:19]
	v_mfma_f32_16x16x32_bf16 v[12:15], v[174:177], v[214:217], v[12:15]
	v_mfma_f32_16x16x32_bf16 v[4:7], v[174:177], v[234:237], v[4:7]
	v_mfma_f32_16x16x32_bf16 v[8:11], v[166:169], v[234:237], v[8:11]
	s_barrier
; #define PG8_STAGE(bufoff, gbase, voff) do { _Pragma("unroll") for (int _i = 0; _i < 2; ++_i) \
;         __builtin_amdgcn_global_load_lds((const unsigned*)((const char*)(gbase) + (voff)[_i]), (PG8_LAS unsigned*)(lds + (bufoff) + ldsw + _i * 8192), 16, 0, 0); } while (0)
; #define PG8_LDA(dst, b, h) do { _Pragma("unroll") for (int m = 0; m < 4; ++m) _Pragma("unroll") for (int k = 0; k < 2; ++k) dst[m][k] = *(const PG8_LAS bf16x8*)(lds + PG8_SA(b, h) + aoff + m * 2048 + k * 1024); } while (0)
; #define PG8_LDB(dst, b, h) do { _Pragma("unroll") for (int n = 0; n < 2; ++n) _Pragma("unroll") for (int k = 0; k < 2; ++k) dst[n][k] = *(const PG8_LAS bf16x8*)(lds + PG8_SB(b, h) + boff + n * 2048 + k * 1024); } while (0)
; #define PG8_MMA(ai, bj, At, Bt) do { __builtin_amdgcn_s_setprio(1); _Pragma("unroll") for (int m = 0; m < 4; ++m) _Pragma("unroll") for (int n = 0; n < 2; ++n) _Pragma("unroll") for (int k = 0; k < 2; ++k) \
;         acc[ai][bj][m][n] = __builtin_amdgcn_mfma_f32_16x16x32_bf16(Bt[n][k], At[m][k], acc[ai][bj][m][n], 0, 0, 0); __builtin_amdgcn_s_setprio(0); } while (0)
; #define PG8_WAIT_V(n) asm volatile("s_waitcnt vmcnt(" #n ")" ::: "memory")
; #define PG8_WAIT_L(n) asm volatile("s_waitcnt lgkmcnt(" #n ")" ::: "memory")
; #define PG8_BAR __builtin_amdgcn_s_barrier()
; #define PG8_SCHED __builtin_amdgcn_sched_barrier(0)
; template <class Epi, class Sched, bool ALIGN_EPI = false, bool SP2 = false>
; __device__ __forceinline__ void gemm_phase(PG8_LAS unsigned char* lds, const Gemm g, const Sched& S, const Epi& E) {
;     ...
;             PG8_LDB(B0, 1, 0); PG8_LDB(B1, 1, 1); PG8_SCHED; PG8_LDA(At, 1, 0); PG8_STAGE(PG8_SA(0, 1), a2 + hstep, voffA);
;             PG8_WAIT_V(8); PG8_WAIT_L(0); PG8_BAR; PG8_MMA(0, 0, At, B0); PG8_MMA(0, 1, At, B1); PG8_BAR; PG8_SCHED;
;             PG8_LDA(At, 1, 1); PG8_STAGE(PG8_SB(1, 0), b3, voffB); PG8_STAGE(PG8_SB(1, 1), b3 + hstep, voffB); PG8_STAGE(PG8_SA(1, 0), a3, voffA);
;             PG8_WAIT_V(8); PG8_WAIT_L(0); PG8_BAR; PG8_MMA(1, 0, At, B0); PG8_MMA(1, 1, At, B1); PG8_BAR; PG8_SCHED;
	s_setprio 0
	s_add_i32 s53, 0, 0x18000
	s_add_i32 s62, 0, 0x1c000
	ds_read_b128 v[146:149], v198 offset:32768
	ds_read_b128 v[150:153], v198 offset:33792
	ds_read_b128 v[154:157], v198 offset:34816
	ds_read_b128 v[158:161], v198 offset:35840
	ds_read_b128 v[162:165], v198 offset:49152
	ds_read_b128 v[166:169], v198 offset:50176
	ds_read_b128 v[170:173], v198 offset:51200
	ds_read_b128 v[174:177], v198 offset:52224
	s_add_u32 s26, s26, 0x40000
	s_addc_u32 s27, s27, 0
	s_mov_b32 m0, s55
	ds_read_b128 v[178:181], v145 offset:32768
	ds_read_b128 v[182:185], v145 offset:33792
	ds_read_b128 v[186:189], v145 offset:34816
	ds_read_b128 v[190:193], v145 offset:35840
	ds_read_b128 v[194:197], v145 offset:36864
	ds_read_b128 v[214:217], v145 offset:37888
	ds_read_b128 v[218:221], v145 offset:38912
	ds_read_b128 v[234:237], v145 offset:39936
	global_load_lds_dwordx4 v136, s[26:27]
	s_mov_b32 m0, s56
	s_nop 0
	global_load_lds_dwordx4 v134, s[26:27]
	s_waitcnt vmcnt(8)
	s_waitcnt lgkmcnt(0)
	s_setprio 1
	s_barrier
	v_mfma_f32_16x16x32_bf16 v[128:131], v[146:149], v[178:181], v[128:131]
	v_mfma_f32_16x16x32_bf16 v[124:127], v[154:157], v[178:181], v[124:127]
	v_mfma_f32_16x16x32_bf16 v[116:119], v[154:157], v[186:189], v[116:119]
	v_mfma_f32_16x16x32_bf16 v[120:123], v[146:149], v[186:189], v[120:123]
	v_mfma_f32_16x16x32_bf16 v[104:107], v[146:149], v[194:197], v[104:107]
	v_mfma_f32_16x16x32_bf16 v[100:103], v[154:157], v[194:197], v[100:103]
	v_mfma_f32_16x16x32_bf16 v[84:87], v[154:157], v[218:221], v[84:87]
	v_mfma_f32_16x16x32_bf16 v[88:91], v[146:149], v[218:221], v[88:91]
	v_mfma_f32_16x16x32_bf16 v[128:131], v[150:153], v[182:185], v[128:131]
	v_mfma_f32_16x16x32_bf16 v[124:127], v[158:161], v[182:185], v[124:127]
	v_mfma_f32_16x16x32_bf16 v[116:119], v[158:161], v[190:193], v[116:119]
	v_mfma_f32_16x16x32_bf16 v[120:123], v[150:153], v[190:193], v[120:123]
	v_mfma_f32_16x16x32_bf16 v[104:107], v[150:153], v[214:217], v[104:107]
	v_mfma_f32_16x16x32_bf16 v[100:103], v[158:161], v[214:217], v[100:103]
	v_mfma_f32_16x16x32_bf16 v[84:87], v[158:161], v[234:237], v[84:87]
	v_mfma_f32_16x16x32_bf16 v[88:91], v[150:153], v[234:237], v[88:91]
	s_setprio 0
	s_setprio 1
	v_mfma_f32_16x16x32_bf16 v[112:115], v[162:165], v[178:181], v[112:115]
	v_mfma_f32_16x16x32_bf16 v[108:111], v[170:173], v[178:181], v[108:111]
	v_mfma_f32_16x16x32_bf16 v[92:95], v[170:173], v[186:189], v[92:95]
	v_mfma_f32_16x16x32_bf16 v[96:99], v[162:165], v[186:189], v[96:99]
	v_mfma_f32_16x16x32_bf16 v[80:83], v[162:165], v[194:197], v[80:83]
	v_mfma_f32_16x16x32_bf16 v[76:79], v[170:173], v[194:197], v[76:79]
	v_mfma_f32_16x16x32_bf16 v[68:71], v[170:173], v[218:221], v[68:71]
	v_mfma_f32_16x16x32_bf16 v[72:75], v[162:165], v[218:221], v[72:75]
	v_mfma_f32_16x16x32_bf16 v[112:115], v[166:169], v[182:185], v[112:115]
	v_mfma_f32_16x16x32_bf16 v[108:111], v[174:177], v[182:185], v[108:111]
	v_mfma_f32_16x16x32_bf16 v[92:95], v[174:177], v[190:193], v[92:95]
	v_mfma_f32_16x16x32_bf16 v[96:99], v[166:169], v[190:193], v[96:99]
	v_mfma_f32_16x16x32_bf16 v[80:83], v[166:169], v[214:217], v[80:83]
	v_mfma_f32_16x16x32_bf16 v[76:79], v[174:177], v[214:217], v[76:79]
	v_mfma_f32_16x16x32_bf16 v[68:71], v[174:177], v[234:237], v[68:71]
	v_mfma_f32_16x16x32_bf16 v[72:75], v[166:169], v[234:237], v[72:75]
	s_barrier
	s_setprio 0
	s_add_i32 s26, s53, s10
	s_mov_b32 m0, s26
	ds_read_b128 v[178:181], v145 offset:49152
	ds_read_b128 v[182:185], v145 offset:50176
	ds_read_b128 v[186:189], v145 offset:51200
	ds_read_b128 v[190:193], v145 offset:52224
	ds_read_b128 v[194:197], v145 offset:53248
	ds_read_b128 v[214:217], v145 offset:54272
	ds_read_b128 v[218:221], v145 offset:55296
	ds_read_b128 v[234:237], v145 offset:56320
	s_add_u32 s0, s0, 0x80
	s_addc_u32 s1, s1, 0
	global_load_lds_dwordx4 v2, s[0:1]
	s_add_i32 m0, s26, 0x2000
	s_add_i32 s26, s62, s10
	global_load_lds_dwordx4 v132, s[0:1]
	s_add_u32 s0, s0, 0x40000
	s_addc_u32 s1, s1, 0
	s_mov_b32 m0, s26
	s_nop 0
	global_load_lds_dwordx4 v2, s[0:1]
	s_add_i32 m0, s26, 0x2000
	s_nop 0
	global_load_lds_dwordx4 v132, s[0:1]
	s_mov_b32 m0, s57
	s_nop 0
	global_load_lds_dwordx4 v136, s[100:101]
	s_mov_b32 m0, s58
	s_nop 0
	global_load_lds_dwordx4 v134, s[100:101]
	s_waitcnt vmcnt(8)
	s_waitcnt lgkmcnt(0)
	s_setprio 1
	s_barrier
	v_mfma_f32_16x16x32_bf16 v[64:67], v[146:149], v[178:181], v[64:67]
	v_mfma_f32_16x16x32_bf16 v[60:63], v[154:157], v[178:181], v[60:63]
	v_mfma_f32_16x16x32_bf16 v[52:55], v[154:157], v[186:189], v[52:55]
	v_mfma_f32_16x16x32_bf16 v[56:59], v[146:149], v[186:189], v[56:59]
	v_mfma_f32_16x16x32_bf16 v[40:43], v[146:149], v[194:197], v[40:43]
	v_mfma_f32_16x16x32_bf16 v[36:39], v[154:157], v[194:197], v[36:39]
	v_mfma_f32_16x16x32_bf16 v[20:23], v[154:157], v[218:221], v[20:23]
	v_mfma_f32_16x16x32_bf16 v[24:27], v[146:149], v[218:221], v[24:27]
	v_mfma_f32_16x16x32_bf16 v[64:67], v[150:153], v[182:185], v[64:67]
	v_mfma_f32_16x16x32_bf16 v[60:63], v[158:161], v[182:185], v[60:63]
	v_mfma_f32_16x16x32_bf16 v[52:55], v[158:161], v[190:193], v[52:55]
	v_mfma_f32_16x16x32_bf16 v[56:59], v[150:153], v[190:193], v[56:59]
	v_mfma_f32_16x16x32_bf16 v[40:43], v[150:153], v[214:217], v[40:43]
	v_mfma_f32_16x16x32_bf16 v[36:39], v[158:161], v[214:217], v[36:39]
	v_mfma_f32_16x16x32_bf16 v[20:23], v[158:161], v[234:237], v[20:23]
	v_mfma_f32_16x16x32_bf16 v[24:27], v[150:153], v[234:237], v[24:27]
	s_setprio 0
	s_setprio 1
	v_mfma_f32_16x16x32_bf16 v[48:51], v[162:165], v[178:181], v[48:51]
	v_mfma_f32_16x16x32_bf16 v[44:47], v[170:173], v[178:181], v[44:47]
	v_mfma_f32_16x16x32_bf16 v[28:31], v[170:173], v[186:189], v[28:31]
	v_mfma_f32_16x16x32_bf16 v[32:35], v[162:165], v[186:189], v[32:35]
	v_mfma_f32_16x16x32_bf16 v[16:19], v[162:165], v[194:197], v[16:19]
	v_mfma_f32_16x16x32_bf16 v[12:15], v[170:173], v[194:197], v[12:15]
	v_mfma_f32_16x16x32_bf16 v[4:7], v[170:173], v[218:221], v[4:7]
	v_mfma_f32_16x16x32_bf16 v[8:11], v[162:165], v[218:221], v[8:11]
	v_mfma_f32_16x16x32_bf16 v[48:51], v[166:169], v[182:185], v[48:51]
	v_mfma_f32_16x16x32_bf16 v[44:47], v[174:177], v[182:185], v[44:47]
	v_mfma_f32_16x16x32_bf16 v[28:31], v[174:177], v[190:193], v[28:31]
	v_mfma_f32_16x16x32_bf16 v[32:35], v[166:169], v[190:193], v[32:35]
	v_mfma_f32_16x16x32_bf16 v[16:19], v[166:169], v[214:217], v[16:19]
	v_mfma_f32_16x16x32_bf16 v[12:15], v[174:177], v[214:217], v[12:15]
	v_mfma_f32_16x16x32_bf16 v[4:7], v[174:177], v[234:237], v[4:7]
	v_mfma_f32_16x16x32_bf16 v[8:11], v[166:169], v[234:237], v[8:11]
	s_barrier
	s_setprio 0
	s_add_i32 s52, s52, 2
	s_add_u32 s50, s50, 0x100
	s_addc_u32 s51, s51, 0
	s_add_u32 s43, s43, 0x100
	s_addc_u32 s45, s45, 0
	s_cmp_gt_u32 s52, 13
	s_cbranch_scc0 .LBB0_1032
	s_and_b64 vcc, exec, s[40:41]
	s_cbranch_vccz .LBB0_1035
	s_barrier

; #define PG8_STAGE(bufoff, gbase, voff) do { _Pragma("unroll") for (int _i = 0; _i < 2; ++_i) \
;         __builtin_amdgcn_global_load_lds((const unsigned*)((const char*)(gbase) + (voff)[_i]), (PG8_LAS unsigned*)(lds + (bufoff) + ldsw + _i * 8192), 16, 0, 0); } while (0)
; #define PG8_LDA(dst, b, h) do { _Pragma("unroll") for (int m = 0; m < 4; ++m) _Pragma("unroll") for (int k = 0; k < 2; ++k) dst[m][k] = *(const PG8_LAS bf16x8*)(lds + PG8_SA(b, h) + aoff + m * 2048 + k * 1024); } while (0)
; #define PG8_LDB(dst, b, h) do { _Pragma("unroll") for (int n = 0; n < 2; ++n) _Pragma("unroll") for (int k = 0; k < 2; ++k) dst[n][k] = *(const PG8_LAS bf16x8*)(lds + PG8_SB(b, h) + boff + n * 2048 + k * 1024); } while (0)
; #define PG8_MMA(ai, bj, At, Bt) do { __builtin_amdgcn_s_setprio(1); _Pragma("unroll") for (int m = 0; m < 4; ++m) _Pragma("unroll") for (int n = 0; n < 2; ++n) _Pragma("unroll") for (int k = 0; k < 2; ++k) \
;         acc[ai][bj][m][n] = __builtin_amdgcn_mfma_f32_16x16x32_bf16(Bt[n][k], At[m][k], acc[ai][bj][m][n], 0, 0, 0); __builtin_amdgcn_s_setprio(0); } while (0)
; #define PG8_WAIT_V(n) asm volatile("s_waitcnt vmcnt(" #n ")" ::: "memory")
; #define PG8_WAIT_L(n) asm volatile("s_waitcnt lgkmcnt(" #n ")" ::: "memory")
; template <class Epi, class Sched, bool ALIGN_EPI = false, bool SP2 = false>
; __device__ __forceinline__ void gemm_phase(PG8_LAS unsigned char* lds, const Gemm g, const Sched& S, const Epi& E) {
;     ...
;             const bool last = (t == nt - 2);
;             const char* a1 = cA + (size_t)(t + 1) * kstep;
;             const char* a2 = last ? nA : cA + (size_t)(t + 2) * kstep; const char* b2 = last ? nB : cB + (size_t)(t + 2) * kstep;
;             const char* a3 = a2 + kstep; const char* b3 = b2 + kstep;
;             if (last && has_next) S.a_ready(nxt);
;             if constexpr (SP2) {
;             PG8_LDB(B0, 0, 0); PG8_LDB(B1, 0, 1); PG8_SCHED; PG8_LDA(At, 0, 0); PG8_STAGE(PG8_SA(1, 1), a1 + hstep, voffA);
;             PG8_WAIT_V(8); PG8_WAIT_L(0); PG8_BAR; PG8_MMA(0, 0, At, B0); PG8_MMA(0, 1, At, B1); PG8_BAR; PG8_SCHED;
;             PG8_LDA(At, 0, 1); PG8_STAGE(PG8_SB(0, 0), b2, voffB); PG8_STAGE(PG8_SB(0, 1), b2 + hstep, voffB); PG8_STAGE(PG8_SA(0, 0), a2, voffA);
;             PG8_WAIT_V(8); PG8_WAIT_L(0); PG8_BAR; PG8_MMA(1, 0, At, B0); PG8_MMA(1, 1, At, B1); PG8_BAR; PG8_SCHED;
.LBB0_1051:
	s_add_u32 s0, s52, 0xfffe0080
	s_addc_u32 s1, s53, -1
	s_add_i32 s63, 0, 0x10000
	s_cmp_eq_u32 s62, 4
	s_cselect_b32 s27, s45, s1
	s_cselect_b32 s26, s58, s0
	s_cselect_b32 s1, s43, s61
	s_cselect_b32 s0, s59, s60
	s_add_i32 s66, 0, 0x14000
	ds_read_b128 v[84:87], v154
	ds_read_b128 v[88:91], v154 offset:1024
	ds_read_b128 v[162:165], v154 offset:2048
	ds_read_b128 v[166:169], v154 offset:3072
	ds_read_b128 v[170:173], v154 offset:16384
	ds_read_b128 v[174:177], v154 offset:17408
	ds_read_b128 v[178:181], v154 offset:18432
	ds_read_b128 v[182:185], v154 offset:19456
	s_add_i32 m0, s10, 0xc000
	ds_read_b128 v[186:189], v160
	ds_read_b128 v[190:193], v160 offset:1024
	ds_read_b128 v[194:197], v160 offset:2048
	ds_read_b128 v[214:217], v160 offset:3072
	ds_read_b128 v[218:221], v160 offset:4096
	ds_read_b128 v[234:237], v160 offset:5120
	ds_read_b128 v[238:241], v160 offset:6144
	ds_read_b128 v[242:245], v160 offset:7168
	global_load_lds_dwordx4 v150, s[52:53]
	s_add_i32 m0, s10, 0xe000
	s_nop 0
	global_load_lds_dwordx4 v152, s[52:53]
	s_waitcnt vmcnt(8)
	s_waitcnt lgkmcnt(0)
	s_setprio 1
	s_barrier
	v_mfma_f32_16x16x32_bf16 v[136:139], v[84:87], v[186:189], v[136:139]
	v_mfma_f32_16x16x32_bf16 v[132:135], v[162:165], v[186:189], v[132:135]
	v_mfma_f32_16x16x32_bf16 v[120:123], v[162:165], v[194:197], v[120:123]
	v_mfma_f32_16x16x32_bf16 v[128:131], v[84:87], v[194:197], v[128:131]
	v_mfma_f32_16x16x32_bf16 v[104:107], v[84:87], v[218:221], v[104:107]
	v_mfma_f32_16x16x32_bf16 v[100:103], v[162:165], v[218:221], v[100:103]
	v_mfma_f32_16x16x32_bf16 v[76:79], v[162:165], v[238:241], v[76:79]
	v_mfma_f32_16x16x32_bf16 v[80:83], v[84:87], v[238:241], v[80:83]
	v_mfma_f32_16x16x32_bf16 v[136:139], v[88:91], v[190:193], v[136:139]
	v_mfma_f32_16x16x32_bf16 v[132:135], v[166:169], v[190:193], v[132:135]
	v_mfma_f32_16x16x32_bf16 v[120:123], v[166:169], v[214:217], v[120:123]
	v_mfma_f32_16x16x32_bf16 v[128:131], v[88:91], v[214:217], v[128:131]
	v_mfma_f32_16x16x32_bf16 v[104:107], v[88:91], v[234:237], v[104:107]
	v_mfma_f32_16x16x32_bf16 v[100:103], v[166:169], v[234:237], v[100:103]
	v_mfma_f32_16x16x32_bf16 v[76:79], v[166:169], v[242:245], v[76:79]
	v_mfma_f32_16x16x32_bf16 v[80:83], v[88:91], v[242:245], v[80:83]
	s_setprio 0
	s_setprio 1
	v_mfma_f32_16x16x32_bf16 v[124:127], v[170:173], v[186:189], v[124:127]
	v_mfma_f32_16x16x32_bf16 v[116:119], v[178:181], v[186:189], v[116:119]
	v_mfma_f32_16x16x32_bf16 v[108:111], v[178:181], v[194:197], v[108:111]
	v_mfma_f32_16x16x32_bf16 v[112:115], v[170:173], v[194:197], v[112:115]
	v_mfma_f32_16x16x32_bf16 v[96:99], v[170:173], v[218:221], v[96:99]
	v_mfma_f32_16x16x32_bf16 v[92:95], v[178:181], v[218:221], v[92:95]
	v_mfma_f32_16x16x32_bf16 v[68:71], v[178:181], v[238:241], v[68:71]
	v_mfma_f32_16x16x32_bf16 v[72:75], v[170:173], v[238:241], v[72:75]
	v_mfma_f32_16x16x32_bf16 v[124:127], v[174:177], v[190:193], v[124:127]
	v_mfma_f32_16x16x32_bf16 v[116:119], v[182:185], v[190:193], v[116:119]
	v_mfma_f32_16x16x32_bf16 v[108:111], v[182:185], v[214:217], v[108:111]
	v_mfma_f32_16x16x32_bf16 v[112:115], v[174:177], v[214:217], v[112:115]
	v_mfma_f32_16x16x32_bf16 v[96:99], v[174:177], v[234:237], v[96:99]
	v_mfma_f32_16x16x32_bf16 v[92:95], v[182:185], v[234:237], v[92:95]
	v_mfma_f32_16x16x32_bf16 v[68:71], v[182:185], v[242:245], v[68:71]
	v_mfma_f32_16x16x32_bf16 v[72:75], v[174:177], v[242:245], v[72:75]
	s_barrier
	s_setprio 0
	s_add_i32 s63, s63, s9
	s_mov_b32 m0, s63
	ds_read_b128 v[186:189], v160 offset:16384
	ds_read_b128 v[190:193], v160 offset:17408
	ds_read_b128 v[194:197], v160 offset:18432
	ds_read_b128 v[214:217], v160 offset:19456
	ds_read_b128 v[218:221], v160 offset:20480
	ds_read_b128 v[234:237], v160 offset:21504
	ds_read_b128 v[238:241], v160 offset:22528
	ds_read_b128 v[242:245], v160 offset:23552
	global_load_lds_dwordx4 v2, s[0:1]
	s_add_i32 m0, s63, 0x2000
	s_add_u32 s64, s0, 0x20000
	s_addc_u32 s65, s1, 0
	s_add_i32 s63, s66, s9
	global_load_lds_dwordx4 v144, s[0:1]
	s_mov_b32 m0, s63
	s_nop 0
	global_load_lds_dwordx4 v2, s[64:65]
	s_add_i32 m0, s63, 0x2000
	s_nop 0
	global_load_lds_dwordx4 v144, s[64:65]
	s_mov_b32 m0, s10
	s_nop 0
	global_load_lds_dwordx4 v140, s[26:27]
	s_mov_b32 m0, s11
	s_nop 0
	global_load_lds_dwordx4 v142, s[26:27]
	s_add_u32 s100, s26, 0x80
	s_addc_u32 s101, s27, 0
	s_waitcnt vmcnt(8)
	s_waitcnt lgkmcnt(0)
	s_setprio 1
	s_barrier
	v_mfma_f32_16x16x32_bf16 v[64:67], v[84:87], v[186:189], v[64:67]
	v_mfma_f32_16x16x32_bf16 v[60:63], v[162:165], v[186:189], v[60:63]
	v_mfma_f32_16x16x32_bf16 v[44:47], v[162:165], v[194:197], v[44:47]
	v_mfma_f32_16x16x32_bf16 v[48:51], v[84:87], v[194:197], v[48:51]
	v_mfma_f32_16x16x32_bf16 v[32:35], v[84:87], v[218:221], v[32:35]
	v_mfma_f32_16x16x32_bf16 v[28:31], v[162:165], v[218:221], v[28:31]
	v_mfma_f32_16x16x32_bf16 v[12:15], v[162:165], v[238:241], v[12:15]
	v_mfma_f32_16x16x32_bf16 v[16:19], v[84:87], v[238:241], v[16:19]
	v_mfma_f32_16x16x32_bf16 v[64:67], v[88:91], v[190:193], v[64:67]
	v_mfma_f32_16x16x32_bf16 v[60:63], v[166:169], v[190:193], v[60:63]
	v_mfma_f32_16x16x32_bf16 v[44:47], v[166:169], v[214:217], v[44:47]
	v_mfma_f32_16x16x32_bf16 v[48:51], v[88:91], v[214:217], v[48:51]
	v_mfma_f32_16x16x32_bf16 v[32:35], v[88:91], v[234:237], v[32:35]
	v_mfma_f32_16x16x32_bf16 v[28:31], v[166:169], v[234:237], v[28:31]
	v_mfma_f32_16x16x32_bf16 v[12:15], v[166:169], v[242:245], v[12:15]
	v_mfma_f32_16x16x32_bf16 v[16:19], v[88:91], v[242:245], v[16:19]
	s_setprio 0
	s_setprio 1
	v_mfma_f32_16x16x32_bf16 v[56:59], v[170:173], v[186:189], v[56:59]
	v_mfma_f32_16x16x32_bf16 v[52:55], v[178:181], v[186:189], v[52:55]
	v_mfma_f32_16x16x32_bf16 v[36:39], v[178:181], v[194:197], v[36:39]
	v_mfma_f32_16x16x32_bf16 v[40:43], v[170:173], v[194:197], v[40:43]
	v_mfma_f32_16x16x32_bf16 v[24:27], v[170:173], v[218:221], v[24:27]
	v_mfma_f32_16x16x32_bf16 v[20:23], v[178:181], v[218:221], v[20:23]
	v_mfma_f32_16x16x32_bf16 v[4:7], v[178:181], v[238:241], v[4:7]
	v_mfma_f32_16x16x32_bf16 v[8:11], v[170:173], v[238:241], v[8:11]
	v_mfma_f32_16x16x32_bf16 v[56:59], v[174:177], v[190:193], v[56:59]
	v_mfma_f32_16x16x32_bf16 v[52:55], v[182:185], v[190:193], v[52:55]
	v_mfma_f32_16x16x32_bf16 v[36:39], v[182:185], v[214:217], v[36:39]
	v_mfma_f32_16x16x32_bf16 v[40:43], v[174:177], v[214:217], v[40:43]
	v_mfma_f32_16x16x32_bf16 v[24:27], v[174:177], v[234:237], v[24:27]
	v_mfma_f32_16x16x32_bf16 v[20:23], v[182:185], v[234:237], v[20:23]
	v_mfma_f32_16x16x32_bf16 v[4:7], v[182:185], v[242:245], v[4:7]
	v_mfma_f32_16x16x32_bf16 v[8:11], v[174:177], v[242:245], v[8:11]
	s_barrier
; #define PG8_STAGE(bufoff, gbase, voff) do { _Pragma("unroll") for (int _i = 0; _i < 2; ++_i) \
;         __builtin_amdgcn_global_load_lds((const unsigned*)((const char*)(gbase) + (voff)[_i]), (PG8_LAS unsigned*)(lds + (bufoff) + ldsw + _i * 8192), 16, 0, 0); } while (0)
; #define PG8_LDA(dst, b, h) do { _Pragma("unroll") for (int m = 0; m < 4; ++m) _Pragma("unroll") for (int k = 0; k < 2; ++k) dst[m][k] = *(const PG8_LAS bf16x8*)(lds + PG8_SA(b, h) + aoff + m * 2048 + k * 1024); } while (0)
; #define PG8_LDB(dst, b, h) do { _Pragma("unroll") for (int n = 0; n < 2; ++n) _Pragma("unroll") for (int k = 0; k < 2; ++k) dst[n][k] = *(const PG8_LAS bf16x8*)(lds + PG8_SB(b, h) + boff + n * 2048 + k * 1024); } while (0)
; #define PG8_MMA(ai, bj, At, Bt) do { __builtin_amdgcn_s_setprio(1); _Pragma("unroll") for (int m = 0; m < 4; ++m) _Pragma("unroll") for (int n = 0; n < 2; ++n) _Pragma("unroll") for (int k = 0; k < 2; ++k) \
;         acc[ai][bj][m][n] = __builtin_amdgcn_mfma_f32_16x16x32_bf16(Bt[n][k], At[m][k], acc[ai][bj][m][n], 0, 0, 0); __builtin_amdgcn_s_setprio(0); } while (0)
; #define PG8_WAIT_V(n) asm volatile("s_waitcnt vmcnt(" #n ")" ::: "memory")
; #define PG8_WAIT_L(n) asm volatile("s_waitcnt lgkmcnt(" #n ")" ::: "memory")
; #define PG8_BAR __builtin_amdgcn_s_barrier()
; #define PG8_SCHED __builtin_amdgcn_sched_barrier(0)
; template <class Epi, class Sched, bool ALIGN_EPI = false, bool SP2 = false>
; __device__ __forceinline__ void gemm_phase(PG8_LAS unsigned char* lds, const Gemm g, const Sched& S, const Epi& E) {
;     ...
;             PG8_LDB(B0, 1, 0); PG8_LDB(B1, 1, 1); PG8_SCHED; PG8_LDA(At, 1, 0); PG8_STAGE(PG8_SA(0, 1), a2 + hstep, voffA);
;             PG8_WAIT_V(8); PG8_WAIT_L(0); PG8_BAR; PG8_MMA(0, 0, At, B0); PG8_MMA(0, 1, At, B1); PG8_BAR; PG8_SCHED;
;             PG8_LDA(At, 1, 1); PG8_STAGE(PG8_SB(1, 0), b3, voffB); PG8_STAGE(PG8_SB(1, 1), b3 + hstep, voffB); PG8_STAGE(PG8_SA(1, 0), a3, voffA);
;             PG8_WAIT_V(8); PG8_WAIT_L(0); PG8_BAR; PG8_MMA(1, 0, At, B0); PG8_MMA(1, 1, At, B1); PG8_BAR; PG8_SCHED;
	s_setprio 0
	s_add_i32 s63, 0, 0x18000
	s_add_i32 s64, 0, 0x1c000
	ds_read_b128 v[84:87], v154 offset:32768
	ds_read_b128 v[88:91], v154 offset:33792
	ds_read_b128 v[162:165], v154 offset:34816
	ds_read_b128 v[166:169], v154 offset:35840
	ds_read_b128 v[170:173], v154 offset:49152
	ds_read_b128 v[174:177], v154 offset:50176
	ds_read_b128 v[178:181], v154 offset:51200
	ds_read_b128 v[182:185], v154 offset:52224
	s_add_u32 s26, s26, 0x20000
	s_addc_u32 s27, s27, 0
	s_mov_b32 m0, s25
	ds_read_b128 v[186:189], v160 offset:32768
	ds_read_b128 v[190:193], v160 offset:33792
	ds_read_b128 v[194:197], v160 offset:34816
	ds_read_b128 v[214:217], v160 offset:35840
	ds_read_b128 v[218:221], v160 offset:36864
	ds_read_b128 v[234:237], v160 offset:37888
	ds_read_b128 v[238:241], v160 offset:38912
	ds_read_b128 v[242:245], v160 offset:39936
	global_load_lds_dwordx4 v140, s[26:27]
	s_mov_b32 m0, s51
	s_nop 0
	global_load_lds_dwordx4 v142, s[26:27]
	s_waitcnt vmcnt(8)
	s_waitcnt lgkmcnt(0)
	s_setprio 1
	s_barrier
	v_mfma_f32_16x16x32_bf16 v[136:139], v[84:87], v[186:189], v[136:139]
	v_mfma_f32_16x16x32_bf16 v[132:135], v[162:165], v[186:189], v[132:135]
	v_mfma_f32_16x16x32_bf16 v[120:123], v[162:165], v[194:197], v[120:123]
	v_mfma_f32_16x16x32_bf16 v[128:131], v[84:87], v[194:197], v[128:131]
	v_mfma_f32_16x16x32_bf16 v[104:107], v[84:87], v[218:221], v[104:107]
	v_mfma_f32_16x16x32_bf16 v[100:103], v[162:165], v[218:221], v[100:103]
	v_mfma_f32_16x16x32_bf16 v[76:79], v[162:165], v[238:241], v[76:79]
	v_mfma_f32_16x16x32_bf16 v[80:83], v[84:87], v[238:241], v[80:83]
	v_mfma_f32_16x16x32_bf16 v[136:139], v[88:91], v[190:193], v[136:139]
	v_mfma_f32_16x16x32_bf16 v[132:135], v[166:169], v[190:193], v[132:135]
	v_mfma_f32_16x16x32_bf16 v[120:123], v[166:169], v[214:217], v[120:123]
	v_mfma_f32_16x16x32_bf16 v[128:131], v[88:91], v[214:217], v[128:131]
	v_mfma_f32_16x16x32_bf16 v[104:107], v[88:91], v[234:237], v[104:107]
	v_mfma_f32_16x16x32_bf16 v[100:103], v[166:169], v[234:237], v[100:103]
	v_mfma_f32_16x16x32_bf16 v[76:79], v[166:169], v[242:245], v[76:79]
	v_mfma_f32_16x16x32_bf16 v[80:83], v[88:91], v[242:245], v[80:83]
	s_setprio 0
	s_setprio 1
	v_mfma_f32_16x16x32_bf16 v[124:127], v[170:173], v[186:189], v[124:127]
	v_mfma_f32_16x16x32_bf16 v[116:119], v[178:181], v[186:189], v[116:119]
	v_mfma_f32_16x16x32_bf16 v[108:111], v[178:181], v[194:197], v[108:111]
	v_mfma_f32_16x16x32_bf16 v[112:115], v[170:173], v[194:197], v[112:115]
	v_mfma_f32_16x16x32_bf16 v[96:99], v[170:173], v[218:221], v[96:99]
	v_mfma_f32_16x16x32_bf16 v[92:95], v[178:181], v[218:221], v[92:95]
	v_mfma_f32_16x16x32_bf16 v[68:71], v[178:181], v[238:241], v[68:71]
	v_mfma_f32_16x16x32_bf16 v[72:75], v[170:173], v[238:241], v[72:75]
	v_mfma_f32_16x16x32_bf16 v[124:127], v[174:177], v[190:193], v[124:127]
	v_mfma_f32_16x16x32_bf16 v[116:119], v[182:185], v[190:193], v[116:119]
	v_mfma_f32_16x16x32_bf16 v[108:111], v[182:185], v[214:217], v[108:111]
	v_mfma_f32_16x16x32_bf16 v[112:115], v[174:177], v[214:217], v[112:115]
	v_mfma_f32_16x16x32_bf16 v[96:99], v[174:177], v[234:237], v[96:99]
	v_mfma_f32_16x16x32_bf16 v[92:95], v[182:185], v[234:237], v[92:95]
	v_mfma_f32_16x16x32_bf16 v[68:71], v[182:185], v[242:245], v[68:71]
	v_mfma_f32_16x16x32_bf16 v[72:75], v[174:177], v[242:245], v[72:75]
	s_barrier
	s_setprio 0
	s_add_i32 s26, s63, s9
	s_mov_b32 m0, s26
	ds_read_b128 v[186:189], v160 offset:49152
	ds_read_b128 v[190:193], v160 offset:50176
	ds_read_b128 v[194:197], v160 offset:51200
	ds_read_b128 v[214:217], v160 offset:52224
	ds_read_b128 v[218:221], v160 offset:53248
	ds_read_b128 v[234:237], v160 offset:54272
	ds_read_b128 v[238:241], v160 offset:55296
	ds_read_b128 v[242:245], v160 offset:56320
	s_add_u32 s0, s0, 0x80
	s_addc_u32 s1, s1, 0
	global_load_lds_dwordx4 v2, s[0:1]
	s_add_i32 m0, s26, 0x2000
	s_add_i32 s26, s64, s9
	global_load_lds_dwordx4 v144, s[0:1]
	s_add_u32 s0, s0, 0x20000
	s_addc_u32 s1, s1, 0
	s_mov_b32 m0, s26
	s_nop 0
	global_load_lds_dwordx4 v2, s[0:1]
	s_add_i32 m0, s26, 0x2000
	s_nop 0
	global_load_lds_dwordx4 v144, s[0:1]
	s_mov_b32 m0, s54
	s_nop 0
	global_load_lds_dwordx4 v140, s[100:101]
	s_mov_b32 m0, s55
	s_nop 0
	global_load_lds_dwordx4 v142, s[100:101]
	s_waitcnt vmcnt(8)
	s_waitcnt lgkmcnt(0)
	s_setprio 1
	s_barrier
	v_mfma_f32_16x16x32_bf16 v[64:67], v[84:87], v[186:189], v[64:67]
	v_mfma_f32_16x16x32_bf16 v[60:63], v[162:165], v[186:189], v[60:63]
	v_mfma_f32_16x16x32_bf16 v[44:47], v[162:165], v[194:197], v[44:47]
	v_mfma_f32_16x16x32_bf16 v[48:51], v[84:87], v[194:197], v[48:51]
	v_mfma_f32_16x16x32_bf16 v[32:35], v[84:87], v[218:221], v[32:35]
	v_mfma_f32_16x16x32_bf16 v[28:31], v[162:165], v[218:221], v[28:31]
	v_mfma_f32_16x16x32_bf16 v[12:15], v[162:165], v[238:241], v[12:15]
	v_mfma_f32_16x16x32_bf16 v[16:19], v[84:87], v[238:241], v[16:19]
	v_mfma_f32_16x16x32_bf16 v[64:67], v[88:91], v[190:193], v[64:67]
	v_mfma_f32_16x16x32_bf16 v[60:63], v[166:169], v[190:193], v[60:63]
	v_mfma_f32_16x16x32_bf16 v[44:47], v[166:169], v[214:217], v[44:47]
	v_mfma_f32_16x16x32_bf16 v[48:51], v[88:91], v[214:217], v[48:51]
	v_mfma_f32_16x16x32_bf16 v[32:35], v[88:91], v[234:237], v[32:35]
	v_mfma_f32_16x16x32_bf16 v[28:31], v[166:169], v[234:237], v[28:31]
	v_mfma_f32_16x16x32_bf16 v[12:15], v[166:169], v[242:245], v[12:15]
	v_mfma_f32_16x16x32_bf16 v[16:19], v[88:91], v[242:245], v[16:19]
	s_setprio 0
	s_setprio 1
	v_mfma_f32_16x16x32_bf16 v[56:59], v[170:173], v[186:189], v[56:59]
	v_mfma_f32_16x16x32_bf16 v[52:55], v[178:181], v[186:189], v[52:55]
	v_mfma_f32_16x16x32_bf16 v[36:39], v[178:181], v[194:197], v[36:39]
	v_mfma_f32_16x16x32_bf16 v[40:43], v[170:173], v[194:197], v[40:43]
	v_mfma_f32_16x16x32_bf16 v[24:27], v[170:173], v[218:221], v[24:27]
	v_mfma_f32_16x16x32_bf16 v[20:23], v[178:181], v[218:221], v[20:23]
	v_mfma_f32_16x16x32_bf16 v[4:7], v[178:181], v[238:241], v[4:7]
	v_mfma_f32_16x16x32_bf16 v[8:11], v[170:173], v[238:241], v[8:11]
	v_mfma_f32_16x16x32_bf16 v[56:59], v[174:177], v[190:193], v[56:59]
	v_mfma_f32_16x16x32_bf16 v[52:55], v[182:185], v[190:193], v[52:55]
	v_mfma_f32_16x16x32_bf16 v[36:39], v[182:185], v[214:217], v[36:39]
	v_mfma_f32_16x16x32_bf16 v[40:43], v[174:177], v[214:217], v[40:43]
	v_mfma_f32_16x16x32_bf16 v[24:27], v[174:177], v[234:237], v[24:27]
	v_mfma_f32_16x16x32_bf16 v[20:23], v[182:185], v[234:237], v[20:23]
	v_mfma_f32_16x16x32_bf16 v[4:7], v[182:185], v[242:245], v[4:7]
	v_mfma_f32_16x16x32_bf16 v[8:11], v[174:177], v[242:245], v[8:11]
	s_barrier
	s_setprio 0
	s_add_i32 s62, s62, 2
	s_add_u32 s52, s52, 0x100
	s_addc_u32 s53, s53, 0
	s_add_u32 s60, s60, 0x100
	s_addc_u32 s61, s61, 0
	s_cmp_gt_u32 s62, 5
	s_cbranch_scc0 .LBB0_1051
	s_and_b64 vcc, exec, s[36:37]
	s_cbranch_vccz .LBB0_1054
	s_barrier

; #define PG8_STAGE(bufoff, gbase, voff) do { _Pragma("unroll") for (int _i = 0; _i < 2; ++_i) \
;         __builtin_amdgcn_global_load_lds((const unsigned*)((const char*)(gbase) + (voff)[_i]), (PG8_LAS unsigned*)(lds + (bufoff) + ldsw + _i * 8192), 16, 0, 0); } while (0)
; #define PG8_LDA(dst, b, h) do { _Pragma("unroll") for (int m = 0; m < 4; ++m) _Pragma("unroll") for (int k = 0; k < 2; ++k) dst[m][k] = *(const PG8_LAS bf16x8*)(lds + PG8_SA(b, h) + aoff + m * 2048 + k * 1024); } while (0)
; #define PG8_LDB(dst, b, h) do { _Pragma("unroll") for (int n = 0; n < 2; ++n) _Pragma("unroll") for (int k = 0; k < 2; ++k) dst[n][k] = *(const PG8_LAS bf16x8*)(lds + PG8_SB(b, h) + boff + n * 2048 + k * 1024); } while (0)
; #define PG8_MMA(ai, bj, At, Bt) do { __builtin_amdgcn_s_setprio(1); _Pragma("unroll") for (int m = 0; m < 4; ++m) _Pragma("unroll") for (int n = 0; n < 2; ++n) _Pragma("unroll") for (int k = 0; k < 2; ++k) \
;         acc[ai][bj][m][n] = __builtin_amdgcn_mfma_f32_16x16x32_bf16(Bt[n][k], At[m][k], acc[ai][bj][m][n], 0, 0, 0); __builtin_amdgcn_s_setprio(0); } while (0)
; #define PG8_WAIT_V(n) asm volatile("s_waitcnt vmcnt(" #n ")" ::: "memory")
; #define PG8_WAIT_L(n) asm volatile("s_waitcnt lgkmcnt(" #n ")" ::: "memory")
; template <class Epi, class Sched, bool ALIGN_EPI = false, bool SP2 = false>
; __device__ __forceinline__ void gemm_phase(PG8_LAS unsigned char* lds, const Gemm g, const Sched& S, const Epi& E) {
;     ...
;             const bool last = (t == nt - 2);
;             const char* a1 = cA + (size_t)(t + 1) * kstep;
;             const char* a2 = last ? nA : cA + (size_t)(t + 2) * kstep; const char* b2 = last ? nB : cB + (size_t)(t + 2) * kstep;
;             const char* a3 = a2 + kstep; const char* b3 = b2 + kstep;
;             if (last && has_next) S.a_ready(nxt);
;             if constexpr (SP2) {
;             PG8_LDB(B0, 0, 0); PG8_LDB(B1, 0, 1); PG8_SCHED; PG8_LDA(At, 0, 0); PG8_STAGE(PG8_SA(1, 1), a1 + hstep, voffA);
;             PG8_WAIT_V(8); PG8_WAIT_L(0); PG8_BAR; PG8_MMA(0, 0, At, B0); PG8_MMA(0, 1, At, B1); PG8_BAR; PG8_SCHED;
;             PG8_LDA(At, 0, 1); PG8_STAGE(PG8_SB(0, 0), b2, voffB); PG8_STAGE(PG8_SB(0, 1), b2 + hstep, voffB); PG8_STAGE(PG8_SA(0, 0), a2, voffA);
;             PG8_WAIT_V(8); PG8_WAIT_L(0); PG8_BAR; PG8_MMA(1, 0, At, B0); PG8_MMA(1, 1, At, B1); PG8_BAR; PG8_SCHED;
.LBB0_1624:
	s_add_u32 s0, s56, 0xfff00080
	s_addc_u32 s1, s57, -1
	s_add_i32 s63, 0, 0x10000
	s_cmp_eq_u32 s62, 60
	s_cselect_b32 s27, s51, s1
	s_cselect_b32 s26, s50, s0
	s_cselect_b32 s1, s53, s49
	s_cselect_b32 s0, s52, s47
	s_add_i32 s66, 0, 0x14000
	ds_read_b128 v[142:145], v210
	ds_read_b128 v[150:153], v210 offset:1024
	ds_read_b128 v[154:157], v210 offset:2048
	ds_read_b128 v[158:161], v210 offset:3072
	ds_read_b128 v[162:165], v210 offset:16384
	ds_read_b128 v[166:169], v210 offset:17408
	ds_read_b128 v[170:173], v210 offset:18432
	ds_read_b128 v[174:177], v210 offset:19456
	s_add_i32 m0, s10, 0xc000
	ds_read_b128 v[178:181], v149
	ds_read_b128 v[182:185], v149 offset:1024
	ds_read_b128 v[186:189], v149 offset:2048
	ds_read_b128 v[190:193], v149 offset:3072
	ds_read_b128 v[194:197], v149 offset:4096
	ds_read_b128 v[198:201], v149 offset:5120
	ds_read_b128 v[202:205], v149 offset:6144
	ds_read_b128 v[206:209], v149 offset:7168
	global_load_lds_dwordx4 v138, s[56:57]
	s_add_i32 m0, s10, 0xe000
	s_nop 0
	global_load_lds_dwordx4 v140, s[56:57]
	s_waitcnt vmcnt(8)
	s_waitcnt lgkmcnt(0)
	s_setprio 1
	s_barrier
	v_mfma_f32_16x16x32_bf16 v[128:131], v[142:145], v[178:181], v[128:131]
	v_mfma_f32_16x16x32_bf16 v[124:127], v[154:157], v[178:181], v[124:127]
	v_mfma_f32_16x16x32_bf16 v[108:111], v[154:157], v[186:189], v[108:111]
	v_mfma_f32_16x16x32_bf16 v[112:115], v[142:145], v[186:189], v[112:115]
	v_mfma_f32_16x16x32_bf16 v[96:99], v[142:145], v[194:197], v[96:99]
	v_mfma_f32_16x16x32_bf16 v[92:95], v[154:157], v[194:197], v[92:95]
	v_mfma_f32_16x16x32_bf16 v[76:79], v[154:157], v[202:205], v[76:79]
	v_mfma_f32_16x16x32_bf16 v[80:83], v[142:145], v[202:205], v[80:83]
	v_mfma_f32_16x16x32_bf16 v[128:131], v[150:153], v[182:185], v[128:131]
	v_mfma_f32_16x16x32_bf16 v[124:127], v[158:161], v[182:185], v[124:127]
	v_mfma_f32_16x16x32_bf16 v[108:111], v[158:161], v[190:193], v[108:111]
	v_mfma_f32_16x16x32_bf16 v[112:115], v[150:153], v[190:193], v[112:115]
	v_mfma_f32_16x16x32_bf16 v[96:99], v[150:153], v[198:201], v[96:99]
	v_mfma_f32_16x16x32_bf16 v[92:95], v[158:161], v[198:201], v[92:95]
	v_mfma_f32_16x16x32_bf16 v[76:79], v[158:161], v[206:209], v[76:79]
	v_mfma_f32_16x16x32_bf16 v[80:83], v[150:153], v[206:209], v[80:83]
	s_setprio 0
	s_setprio 1
	v_mfma_f32_16x16x32_bf16 v[120:123], v[162:165], v[178:181], v[120:123]
	v_mfma_f32_16x16x32_bf16 v[116:119], v[170:173], v[178:181], v[116:119]
	v_mfma_f32_16x16x32_bf16 v[100:103], v[170:173], v[186:189], v[100:103]
	v_mfma_f32_16x16x32_bf16 v[104:107], v[162:165], v[186:189], v[104:107]
	v_mfma_f32_16x16x32_bf16 v[88:91], v[162:165], v[194:197], v[88:91]
	v_mfma_f32_16x16x32_bf16 v[84:87], v[170:173], v[194:197], v[84:87]
	v_mfma_f32_16x16x32_bf16 v[68:71], v[170:173], v[202:205], v[68:71]
	v_mfma_f32_16x16x32_bf16 v[72:75], v[162:165], v[202:205], v[72:75]
	v_mfma_f32_16x16x32_bf16 v[120:123], v[166:169], v[182:185], v[120:123]
	v_mfma_f32_16x16x32_bf16 v[116:119], v[174:177], v[182:185], v[116:119]
	v_mfma_f32_16x16x32_bf16 v[100:103], v[174:177], v[190:193], v[100:103]
	v_mfma_f32_16x16x32_bf16 v[104:107], v[166:169], v[190:193], v[104:107]
	v_mfma_f32_16x16x32_bf16 v[88:91], v[166:169], v[198:201], v[88:91]
	v_mfma_f32_16x16x32_bf16 v[84:87], v[174:177], v[198:201], v[84:87]
	v_mfma_f32_16x16x32_bf16 v[68:71], v[174:177], v[206:209], v[68:71]
	v_mfma_f32_16x16x32_bf16 v[72:75], v[166:169], v[206:209], v[72:75]
	s_barrier
	s_setprio 0
	s_add_i32 s63, s63, s9
	s_mov_b32 m0, s63
	ds_read_b128 v[178:181], v149 offset:16384
	ds_read_b128 v[182:185], v149 offset:17408
	ds_read_b128 v[186:189], v149 offset:18432
	ds_read_b128 v[190:193], v149 offset:19456
	ds_read_b128 v[194:197], v149 offset:20480
	ds_read_b128 v[198:201], v149 offset:21504
	ds_read_b128 v[202:205], v149 offset:22528
	ds_read_b128 v[206:209], v149 offset:23552
	global_load_lds_dwordx4 v2, s[0:1]
	s_add_i32 m0, s63, 0x2000
	s_add_u32 s64, s0, 0x100000
	s_addc_u32 s65, s1, 0
	s_add_i32 s63, s66, s9
	global_load_lds_dwordx4 v136, s[0:1]
	s_mov_b32 m0, s63
	s_nop 0
	global_load_lds_dwordx4 v2, s[64:65]
	s_add_i32 m0, s63, 0x2000
	s_nop 0
	global_load_lds_dwordx4 v136, s[64:65]
	s_mov_b32 m0, s10
	s_nop 0
	global_load_lds_dwordx4 v132, s[26:27]
	s_mov_b32 m0, s11
	s_nop 0
	global_load_lds_dwordx4 v134, s[26:27]
	s_add_u32 s100, s26, 0x80
	s_addc_u32 s101, s27, 0
	s_waitcnt vmcnt(8)
	s_waitcnt lgkmcnt(0)
	s_setprio 1
	s_barrier
	v_mfma_f32_16x16x32_bf16 v[64:67], v[142:145], v[178:181], v[64:67]
	v_mfma_f32_16x16x32_bf16 v[60:63], v[154:157], v[178:181], v[60:63]
	v_mfma_f32_16x16x32_bf16 v[44:47], v[154:157], v[186:189], v[44:47]
	v_mfma_f32_16x16x32_bf16 v[48:51], v[142:145], v[186:189], v[48:51]
	v_mfma_f32_16x16x32_bf16 v[32:35], v[142:145], v[194:197], v[32:35]
	v_mfma_f32_16x16x32_bf16 v[28:31], v[154:157], v[194:197], v[28:31]
	v_mfma_f32_16x16x32_bf16 v[12:15], v[154:157], v[202:205], v[12:15]
	v_mfma_f32_16x16x32_bf16 v[16:19], v[142:145], v[202:205], v[16:19]
	v_mfma_f32_16x16x32_bf16 v[64:67], v[150:153], v[182:185], v[64:67]
	v_mfma_f32_16x16x32_bf16 v[60:63], v[158:161], v[182:185], v[60:63]
	v_mfma_f32_16x16x32_bf16 v[44:47], v[158:161], v[190:193], v[44:47]
	v_mfma_f32_16x16x32_bf16 v[48:51], v[150:153], v[190:193], v[48:51]
	v_mfma_f32_16x16x32_bf16 v[32:35], v[150:153], v[198:201], v[32:35]
	v_mfma_f32_16x16x32_bf16 v[28:31], v[158:161], v[198:201], v[28:31]
	v_mfma_f32_16x16x32_bf16 v[12:15], v[158:161], v[206:209], v[12:15]
	v_mfma_f32_16x16x32_bf16 v[16:19], v[150:153], v[206:209], v[16:19]
	s_setprio 0
	s_setprio 1
	v_mfma_f32_16x16x32_bf16 v[56:59], v[162:165], v[178:181], v[56:59]
	v_mfma_f32_16x16x32_bf16 v[52:55], v[170:173], v[178:181], v[52:55]
	v_mfma_f32_16x16x32_bf16 v[36:39], v[170:173], v[186:189], v[36:39]
	v_mfma_f32_16x16x32_bf16 v[40:43], v[162:165], v[186:189], v[40:43]
	v_mfma_f32_16x16x32_bf16 v[24:27], v[162:165], v[194:197], v[24:27]
	v_mfma_f32_16x16x32_bf16 v[20:23], v[170:173], v[194:197], v[20:23]
	v_mfma_f32_16x16x32_bf16 v[4:7], v[170:173], v[202:205], v[4:7]
	v_mfma_f32_16x16x32_bf16 v[8:11], v[162:165], v[202:205], v[8:11]
	v_mfma_f32_16x16x32_bf16 v[56:59], v[166:169], v[182:185], v[56:59]
	v_mfma_f32_16x16x32_bf16 v[52:55], v[174:177], v[182:185], v[52:55]
	v_mfma_f32_16x16x32_bf16 v[36:39], v[174:177], v[190:193], v[36:39]
	v_mfma_f32_16x16x32_bf16 v[40:43], v[166:169], v[190:193], v[40:43]
	v_mfma_f32_16x16x32_bf16 v[24:27], v[166:169], v[198:201], v[24:27]
	v_mfma_f32_16x16x32_bf16 v[20:23], v[174:177], v[198:201], v[20:23]
	v_mfma_f32_16x16x32_bf16 v[4:7], v[174:177], v[206:209], v[4:7]
	v_mfma_f32_16x16x32_bf16 v[8:11], v[166:169], v[206:209], v[8:11]
	s_barrier
; #define PG8_STAGE(bufoff, gbase, voff) do { _Pragma("unroll") for (int _i = 0; _i < 2; ++_i) \
;         __builtin_amdgcn_global_load_lds((const unsigned*)((const char*)(gbase) + (voff)[_i]), (PG8_LAS unsigned*)(lds + (bufoff) + ldsw + _i * 8192), 16, 0, 0); } while (0)
; #define PG8_LDA(dst, b, h) do { _Pragma("unroll") for (int m = 0; m < 4; ++m) _Pragma("unroll") for (int k = 0; k < 2; ++k) dst[m][k] = *(const PG8_LAS bf16x8*)(lds + PG8_SA(b, h) + aoff + m * 2048 + k * 1024); } while (0)
; #define PG8_LDB(dst, b, h) do { _Pragma("unroll") for (int n = 0; n < 2; ++n) _Pragma("unroll") for (int k = 0; k < 2; ++k) dst[n][k] = *(const PG8_LAS bf16x8*)(lds + PG8_SB(b, h) + boff + n * 2048 + k * 1024); } while (0)
; #define PG8_MMA(ai, bj, At, Bt) do { __builtin_amdgcn_s_setprio(1); _Pragma("unroll") for (int m = 0; m < 4; ++m) _Pragma("unroll") for (int n = 0; n < 2; ++n) _Pragma("unroll") for (int k = 0; k < 2; ++k) \
;         acc[ai][bj][m][n] = __builtin_amdgcn_mfma_f32_16x16x32_bf16(Bt[n][k], At[m][k], acc[ai][bj][m][n], 0, 0, 0); __builtin_amdgcn_s_setprio(0); } while (0)
; #define PG8_WAIT_V(n) asm volatile("s_waitcnt vmcnt(" #n ")" ::: "memory")
; #define PG8_WAIT_L(n) asm volatile("s_waitcnt lgkmcnt(" #n ")" ::: "memory")
; #define PG8_BAR __builtin_amdgcn_s_barrier()
; #define PG8_SCHED __builtin_amdgcn_sched_barrier(0)
; template <class Epi, class Sched, bool ALIGN_EPI = false, bool SP2 = false>
; __device__ __forceinline__ void gemm_phase(PG8_LAS unsigned char* lds, const Gemm g, const Sched& S, const Epi& E) {
;     ...
;             PG8_LDB(B0, 1, 0); PG8_LDB(B1, 1, 1); PG8_SCHED; PG8_LDA(At, 1, 0); PG8_STAGE(PG8_SA(0, 1), a2 + hstep, voffA);
;             PG8_WAIT_V(8); PG8_WAIT_L(0); PG8_BAR; PG8_MMA(0, 0, At, B0); PG8_MMA(0, 1, At, B1); PG8_BAR; PG8_SCHED;
;             PG8_LDA(At, 1, 1); PG8_STAGE(PG8_SB(1, 0), b3, voffB); PG8_STAGE(PG8_SB(1, 1), b3 + hstep, voffB); PG8_STAGE(PG8_SA(1, 0), a3, voffA);
;             PG8_WAIT_V(8); PG8_WAIT_L(0); PG8_BAR; PG8_MMA(1, 0, At, B0); PG8_MMA(1, 1, At, B1); PG8_BAR; PG8_SCHED;
	s_setprio 0
	s_add_i32 s63, 0, 0x18000
	s_add_i32 s64, 0, 0x1c000
	ds_read_b128 v[142:145], v210 offset:32768
	ds_read_b128 v[150:153], v210 offset:33792
	ds_read_b128 v[154:157], v210 offset:34816
	ds_read_b128 v[158:161], v210 offset:35840
	ds_read_b128 v[162:165], v210 offset:49152
	ds_read_b128 v[166:169], v210 offset:50176
	ds_read_b128 v[170:173], v210 offset:51200
	ds_read_b128 v[174:177], v210 offset:52224
	s_add_u32 s26, s26, 0x100000
	s_addc_u32 s27, s27, 0
	s_mov_b32 m0, s25
	ds_read_b128 v[178:181], v149 offset:32768
	ds_read_b128 v[182:185], v149 offset:33792
	ds_read_b128 v[186:189], v149 offset:34816
	ds_read_b128 v[190:193], v149 offset:35840
	ds_read_b128 v[194:197], v149 offset:36864
	ds_read_b128 v[198:201], v149 offset:37888
	ds_read_b128 v[202:205], v149 offset:38912
	ds_read_b128 v[206:209], v149 offset:39936
	global_load_lds_dwordx4 v132, s[26:27]
	s_mov_b32 m0, s55
	s_nop 0
	global_load_lds_dwordx4 v134, s[26:27]
	s_waitcnt vmcnt(8)
	s_waitcnt lgkmcnt(0)
	s_setprio 1
	s_barrier
	v_mfma_f32_16x16x32_bf16 v[128:131], v[142:145], v[178:181], v[128:131]
	v_mfma_f32_16x16x32_bf16 v[124:127], v[154:157], v[178:181], v[124:127]
	v_mfma_f32_16x16x32_bf16 v[108:111], v[154:157], v[186:189], v[108:111]
	v_mfma_f32_16x16x32_bf16 v[112:115], v[142:145], v[186:189], v[112:115]
	v_mfma_f32_16x16x32_bf16 v[96:99], v[142:145], v[194:197], v[96:99]
	v_mfma_f32_16x16x32_bf16 v[92:95], v[154:157], v[194:197], v[92:95]
	v_mfma_f32_16x16x32_bf16 v[76:79], v[154:157], v[202:205], v[76:79]
	v_mfma_f32_16x16x32_bf16 v[80:83], v[142:145], v[202:205], v[80:83]
	v_mfma_f32_16x16x32_bf16 v[128:131], v[150:153], v[182:185], v[128:131]
	v_mfma_f32_16x16x32_bf16 v[124:127], v[158:161], v[182:185], v[124:127]
	v_mfma_f32_16x16x32_bf16 v[108:111], v[158:161], v[190:193], v[108:111]
	v_mfma_f32_16x16x32_bf16 v[112:115], v[150:153], v[190:193], v[112:115]
	v_mfma_f32_16x16x32_bf16 v[96:99], v[150:153], v[198:201], v[96:99]
	v_mfma_f32_16x16x32_bf16 v[92:95], v[158:161], v[198:201], v[92:95]
	v_mfma_f32_16x16x32_bf16 v[76:79], v[158:161], v[206:209], v[76:79]
	v_mfma_f32_16x16x32_bf16 v[80:83], v[150:153], v[206:209], v[80:83]
	s_setprio 0
	s_setprio 1
	v_mfma_f32_16x16x32_bf16 v[120:123], v[162:165], v[178:181], v[120:123]
	v_mfma_f32_16x16x32_bf16 v[116:119], v[170:173], v[178:181], v[116:119]
	v_mfma_f32_16x16x32_bf16 v[100:103], v[170:173], v[186:189], v[100:103]
	v_mfma_f32_16x16x32_bf16 v[104:107], v[162:165], v[186:189], v[104:107]
	v_mfma_f32_16x16x32_bf16 v[88:91], v[162:165], v[194:197], v[88:91]
	v_mfma_f32_16x16x32_bf16 v[84:87], v[170:173], v[194:197], v[84:87]
	v_mfma_f32_16x16x32_bf16 v[68:71], v[170:173], v[202:205], v[68:71]
	v_mfma_f32_16x16x32_bf16 v[72:75], v[162:165], v[202:205], v[72:75]
	v_mfma_f32_16x16x32_bf16 v[120:123], v[166:169], v[182:185], v[120:123]
	v_mfma_f32_16x16x32_bf16 v[116:119], v[174:177], v[182:185], v[116:119]
	v_mfma_f32_16x16x32_bf16 v[100:103], v[174:177], v[190:193], v[100:103]
	v_mfma_f32_16x16x32_bf16 v[104:107], v[166:169], v[190:193], v[104:107]
	v_mfma_f32_16x16x32_bf16 v[88:91], v[166:169], v[198:201], v[88:91]
	v_mfma_f32_16x16x32_bf16 v[84:87], v[174:177], v[198:201], v[84:87]
	v_mfma_f32_16x16x32_bf16 v[68:71], v[174:177], v[206:209], v[68:71]
	v_mfma_f32_16x16x32_bf16 v[72:75], v[166:169], v[206:209], v[72:75]
	s_barrier
	s_setprio 0
	s_add_i32 s26, s63, s9
	s_mov_b32 m0, s26
	ds_read_b128 v[178:181], v149 offset:49152
	ds_read_b128 v[182:185], v149 offset:50176
	ds_read_b128 v[186:189], v149 offset:51200
	ds_read_b128 v[190:193], v149 offset:52224
	ds_read_b128 v[194:197], v149 offset:53248
	ds_read_b128 v[198:201], v149 offset:54272
	ds_read_b128 v[202:205], v149 offset:55296
	ds_read_b128 v[206:209], v149 offset:56320
	s_add_u32 s0, s0, 0x80
	s_addc_u32 s1, s1, 0
	global_load_lds_dwordx4 v2, s[0:1]
	s_add_i32 m0, s26, 0x2000
	s_add_i32 s26, s64, s9
	global_load_lds_dwordx4 v136, s[0:1]
	s_add_u32 s0, s0, 0x100000
	s_addc_u32 s1, s1, 0
	s_mov_b32 m0, s26
	s_nop 0
	global_load_lds_dwordx4 v2, s[0:1]
	s_add_i32 m0, s26, 0x2000
	s_nop 0
	global_load_lds_dwordx4 v136, s[0:1]
	s_mov_b32 m0, s58
	s_nop 0
	global_load_lds_dwordx4 v132, s[100:101]
	s_mov_b32 m0, s59
	s_nop 0
	global_load_lds_dwordx4 v134, s[100:101]
	s_waitcnt vmcnt(8)
	s_waitcnt lgkmcnt(0)
	s_setprio 1
	s_barrier
	v_mfma_f32_16x16x32_bf16 v[64:67], v[142:145], v[178:181], v[64:67]
	v_mfma_f32_16x16x32_bf16 v[60:63], v[154:157], v[178:181], v[60:63]
	v_mfma_f32_16x16x32_bf16 v[44:47], v[154:157], v[186:189], v[44:47]
	v_mfma_f32_16x16x32_bf16 v[48:51], v[142:145], v[186:189], v[48:51]
	v_mfma_f32_16x16x32_bf16 v[32:35], v[142:145], v[194:197], v[32:35]
	v_mfma_f32_16x16x32_bf16 v[28:31], v[154:157], v[194:197], v[28:31]
	v_mfma_f32_16x16x32_bf16 v[12:15], v[154:157], v[202:205], v[12:15]
	v_mfma_f32_16x16x32_bf16 v[16:19], v[142:145], v[202:205], v[16:19]
	v_mfma_f32_16x16x32_bf16 v[64:67], v[150:153], v[182:185], v[64:67]
	v_mfma_f32_16x16x32_bf16 v[60:63], v[158:161], v[182:185], v[60:63]
	v_mfma_f32_16x16x32_bf16 v[44:47], v[158:161], v[190:193], v[44:47]
	v_mfma_f32_16x16x32_bf16 v[48:51], v[150:153], v[190:193], v[48:51]
	v_mfma_f32_16x16x32_bf16 v[32:35], v[150:153], v[198:201], v[32:35]
	v_mfma_f32_16x16x32_bf16 v[28:31], v[158:161], v[198:201], v[28:31]
	v_mfma_f32_16x16x32_bf16 v[12:15], v[158:161], v[206:209], v[12:15]
	v_mfma_f32_16x16x32_bf16 v[16:19], v[150:153], v[206:209], v[16:19]
	s_setprio 0
	s_setprio 1
	v_mfma_f32_16x16x32_bf16 v[56:59], v[162:165], v[178:181], v[56:59]
	v_mfma_f32_16x16x32_bf16 v[52:55], v[170:173], v[178:181], v[52:55]
	v_mfma_f32_16x16x32_bf16 v[36:39], v[170:173], v[186:189], v[36:39]
	v_mfma_f32_16x16x32_bf16 v[40:43], v[162:165], v[186:189], v[40:43]
	v_mfma_f32_16x16x32_bf16 v[24:27], v[162:165], v[194:197], v[24:27]
	v_mfma_f32_16x16x32_bf16 v[20:23], v[170:173], v[194:197], v[20:23]
	v_mfma_f32_16x16x32_bf16 v[4:7], v[170:173], v[202:205], v[4:7]
	v_mfma_f32_16x16x32_bf16 v[8:11], v[162:165], v[202:205], v[8:11]
	v_mfma_f32_16x16x32_bf16 v[56:59], v[166:169], v[182:185], v[56:59]
	v_mfma_f32_16x16x32_bf16 v[52:55], v[174:177], v[182:185], v[52:55]
	v_mfma_f32_16x16x32_bf16 v[36:39], v[174:177], v[190:193], v[36:39]
	v_mfma_f32_16x16x32_bf16 v[40:43], v[166:169], v[190:193], v[40:43]
	v_mfma_f32_16x16x32_bf16 v[24:27], v[166:169], v[198:201], v[24:27]
	v_mfma_f32_16x16x32_bf16 v[20:23], v[174:177], v[198:201], v[20:23]
	v_mfma_f32_16x16x32_bf16 v[4:7], v[174:177], v[206:209], v[4:7]
	v_mfma_f32_16x16x32_bf16 v[8:11], v[166:169], v[206:209], v[8:11]
	s_barrier
	s_setprio 0
	s_add_i32 s62, s62, 2
	s_add_u32 s56, s56, 0x100
	s_addc_u32 s57, s57, 0
	s_add_u32 s47, s47, 0x100
	s_addc_u32 s49, s49, 0
	s_cmp_gt_u32 s62, 61
	s_cbranch_scc0 .LBB0_1624
	s_and_b64 vcc, exec, s[44:45]
	s_cbranch_vccz .LBB0_1627
	s_barrier

; #define PG8_STAGE(bufoff, gbase, voff) do { _Pragma("unroll") for (int _i = 0; _i < 2; ++_i) \
;         __builtin_amdgcn_global_load_lds((const unsigned*)((const char*)(gbase) + (voff)[_i]), (PG8_LAS unsigned*)(lds + (bufoff) + ldsw + _i * 8192), 16, 0, 0); } while (0)
; #define PG8_LDA(dst, b, h) do { _Pragma("unroll") for (int m = 0; m < 4; ++m) _Pragma("unroll") for (int k = 0; k < 2; ++k) dst[m][k] = *(const PG8_LAS bf16x8*)(lds + PG8_SA(b, h) + aoff + m * 2048 + k * 1024); } while (0)
; #define PG8_LDB(dst, b, h) do { _Pragma("unroll") for (int n = 0; n < 2; ++n) _Pragma("unroll") for (int k = 0; k < 2; ++k) dst[n][k] = *(const PG8_LAS bf16x8*)(lds + PG8_SB(b, h) + boff + n * 2048 + k * 1024); } while (0)
; #define PG8_MMA(ai, bj, At, Bt) do { __builtin_amdgcn_s_setprio(1); _Pragma("unroll") for (int m = 0; m < 4; ++m) _Pragma("unroll") for (int n = 0; n < 2; ++n) _Pragma("unroll") for (int k = 0; k < 2; ++k) \
;         acc[ai][bj][m][n] = __builtin_amdgcn_mfma_f32_16x16x32_bf16(Bt[n][k], At[m][k], acc[ai][bj][m][n], 0, 0, 0); __builtin_amdgcn_s_setprio(0); } while (0)
; #define PG8_WAIT_V(n) asm volatile("s_waitcnt vmcnt(" #n ")" ::: "memory")
; #define PG8_WAIT_L(n) asm volatile("s_waitcnt lgkmcnt(" #n ")" ::: "memory")
; template <class Epi, class Sched, bool ALIGN_EPI = false, bool SP2 = false>
; __device__ __forceinline__ void gemm_phase(PG8_LAS unsigned char* lds, const Gemm g, const Sched& S, const Epi& E) {
;     ...
;             const bool last = (t == nt - 2);
;             const char* a1 = cA + (size_t)(t + 1) * kstep;
;             const char* a2 = last ? nA : cA + (size_t)(t + 2) * kstep; const char* b2 = last ? nB : cB + (size_t)(t + 2) * kstep;
;             const char* a3 = a2 + kstep; const char* b3 = b2 + kstep;
;             if (last && has_next) S.a_ready(nxt);
;             if constexpr (SP2) {
;             PG8_LDB(B0, 0, 0); PG8_LDB(B1, 0, 1); PG8_SCHED; PG8_LDA(At, 0, 0); PG8_STAGE(PG8_SA(1, 1), a1 + hstep, voffA);
;             PG8_WAIT_V(8); PG8_WAIT_L(0); PG8_BAR; PG8_MMA(0, 0, At, B0); PG8_MMA(0, 1, At, B1); PG8_BAR; PG8_SCHED;
;             PG8_LDA(At, 0, 1); PG8_STAGE(PG8_SB(0, 0), b2, voffB); PG8_STAGE(PG8_SB(0, 1), b2 + hstep, voffB); PG8_STAGE(PG8_SA(0, 0), a2, voffA);
;             PG8_WAIT_V(8); PG8_WAIT_L(0); PG8_BAR; PG8_MMA(1, 0, At, B0); PG8_MMA(1, 1, At, B1); PG8_BAR; PG8_SCHED;
.LBB0_2089:
	s_add_u32 s0, s50, 0xfff00080
	s_addc_u32 s1, s51, -1
	s_add_i32 s61, 0, 0x10000
	s_cmp_eq_u32 s60, 60
	s_cselect_b32 s27, s47, s1
	s_cselect_b32 s26, s46, s0
	s_cselect_b32 s1, s49, s45
	s_cselect_b32 s0, s48, s43
	s_add_i32 s64, 0, 0x14000
	ds_read_b128 v[142:145], v210
	ds_read_b128 v[146:149], v210 offset:1024
	ds_read_b128 v[154:157], v210 offset:2048
	ds_read_b128 v[158:161], v210 offset:3072
	ds_read_b128 v[162:165], v210 offset:16384
	ds_read_b128 v[166:169], v210 offset:17408
	ds_read_b128 v[170:173], v210 offset:18432
	ds_read_b128 v[174:177], v210 offset:19456
	s_add_i32 m0, s10, 0xc000
	ds_read_b128 v[178:181], v153
	ds_read_b128 v[182:185], v153 offset:1024
	ds_read_b128 v[186:189], v153 offset:2048
	ds_read_b128 v[190:193], v153 offset:3072
	ds_read_b128 v[194:197], v153 offset:4096
	ds_read_b128 v[198:201], v153 offset:5120
	ds_read_b128 v[202:205], v153 offset:6144
	ds_read_b128 v[206:209], v153 offset:7168
	global_load_lds_dwordx4 v138, s[50:51]
	s_add_i32 m0, s10, 0xe000
	s_nop 0
	global_load_lds_dwordx4 v140, s[50:51]
	s_waitcnt vmcnt(8)
	s_waitcnt lgkmcnt(0)
	s_setprio 1
	s_barrier
	v_mfma_f32_16x16x32_bf16 v[128:131], v[142:145], v[178:181], v[128:131]
	v_mfma_f32_16x16x32_bf16 v[124:127], v[154:157], v[178:181], v[124:127]
	v_mfma_f32_16x16x32_bf16 v[108:111], v[154:157], v[186:189], v[108:111]
	v_mfma_f32_16x16x32_bf16 v[112:115], v[142:145], v[186:189], v[112:115]
	v_mfma_f32_16x16x32_bf16 v[96:99], v[142:145], v[194:197], v[96:99]
	v_mfma_f32_16x16x32_bf16 v[92:95], v[154:157], v[194:197], v[92:95]
	v_mfma_f32_16x16x32_bf16 v[76:79], v[154:157], v[202:205], v[76:79]
	v_mfma_f32_16x16x32_bf16 v[80:83], v[142:145], v[202:205], v[80:83]
	v_mfma_f32_16x16x32_bf16 v[128:131], v[146:149], v[182:185], v[128:131]
	v_mfma_f32_16x16x32_bf16 v[124:127], v[158:161], v[182:185], v[124:127]
	v_mfma_f32_16x16x32_bf16 v[108:111], v[158:161], v[190:193], v[108:111]
	v_mfma_f32_16x16x32_bf16 v[112:115], v[146:149], v[190:193], v[112:115]
	v_mfma_f32_16x16x32_bf16 v[96:99], v[146:149], v[198:201], v[96:99]
	v_mfma_f32_16x16x32_bf16 v[92:95], v[158:161], v[198:201], v[92:95]
	v_mfma_f32_16x16x32_bf16 v[76:79], v[158:161], v[206:209], v[76:79]
	v_mfma_f32_16x16x32_bf16 v[80:83], v[146:149], v[206:209], v[80:83]
	s_setprio 0
	s_setprio 1
	v_mfma_f32_16x16x32_bf16 v[120:123], v[162:165], v[178:181], v[120:123]
	v_mfma_f32_16x16x32_bf16 v[116:119], v[170:173], v[178:181], v[116:119]
	v_mfma_f32_16x16x32_bf16 v[100:103], v[170:173], v[186:189], v[100:103]
	v_mfma_f32_16x16x32_bf16 v[104:107], v[162:165], v[186:189], v[104:107]
	v_mfma_f32_16x16x32_bf16 v[88:91], v[162:165], v[194:197], v[88:91]
	v_mfma_f32_16x16x32_bf16 v[84:87], v[170:173], v[194:197], v[84:87]
	v_mfma_f32_16x16x32_bf16 v[68:71], v[170:173], v[202:205], v[68:71]
	v_mfma_f32_16x16x32_bf16 v[72:75], v[162:165], v[202:205], v[72:75]
	v_mfma_f32_16x16x32_bf16 v[120:123], v[166:169], v[182:185], v[120:123]
	v_mfma_f32_16x16x32_bf16 v[116:119], v[174:177], v[182:185], v[116:119]
	v_mfma_f32_16x16x32_bf16 v[100:103], v[174:177], v[190:193], v[100:103]
	v_mfma_f32_16x16x32_bf16 v[104:107], v[166:169], v[190:193], v[104:107]
	v_mfma_f32_16x16x32_bf16 v[88:91], v[166:169], v[198:201], v[88:91]
	v_mfma_f32_16x16x32_bf16 v[84:87], v[174:177], v[198:201], v[84:87]
	v_mfma_f32_16x16x32_bf16 v[68:71], v[174:177], v[206:209], v[68:71]
	v_mfma_f32_16x16x32_bf16 v[72:75], v[166:169], v[206:209], v[72:75]
	s_barrier
	s_setprio 0
	s_add_i32 s61, s61, s9
	s_mov_b32 m0, s61
	ds_read_b128 v[178:181], v153 offset:16384
	ds_read_b128 v[182:185], v153 offset:17408
	ds_read_b128 v[186:189], v153 offset:18432
	ds_read_b128 v[190:193], v153 offset:19456
	ds_read_b128 v[194:197], v153 offset:20480
	ds_read_b128 v[198:201], v153 offset:21504
	ds_read_b128 v[202:205], v153 offset:22528
	ds_read_b128 v[206:209], v153 offset:23552
	global_load_lds_dwordx4 v2, s[0:1]
	s_add_i32 m0, s61, 0x2000
	s_add_u32 s62, s0, 0x100000
	s_addc_u32 s63, s1, 0
	s_add_i32 s61, s64, s9
	global_load_lds_dwordx4 v132, s[0:1]
	s_mov_b32 m0, s61
	s_nop 0
	global_load_lds_dwordx4 v2, s[62:63]
	s_add_i32 m0, s61, 0x2000
	s_nop 0
	global_load_lds_dwordx4 v132, s[62:63]
	s_mov_b32 m0, s10
	s_nop 0
	global_load_lds_dwordx4 v136, s[26:27]
	s_mov_b32 m0, s11
	s_nop 0
	global_load_lds_dwordx4 v134, s[26:27]
	s_add_u32 s100, s26, 0x80
	s_addc_u32 s101, s27, 0
	s_waitcnt vmcnt(8)
	s_waitcnt lgkmcnt(0)
	s_setprio 1
	s_barrier
	v_mfma_f32_16x16x32_bf16 v[64:67], v[142:145], v[178:181], v[64:67]
	v_mfma_f32_16x16x32_bf16 v[60:63], v[154:157], v[178:181], v[60:63]
	v_mfma_f32_16x16x32_bf16 v[44:47], v[154:157], v[186:189], v[44:47]
	v_mfma_f32_16x16x32_bf16 v[48:51], v[142:145], v[186:189], v[48:51]
	v_mfma_f32_16x16x32_bf16 v[32:35], v[142:145], v[194:197], v[32:35]
	v_mfma_f32_16x16x32_bf16 v[28:31], v[154:157], v[194:197], v[28:31]
	v_mfma_f32_16x16x32_bf16 v[12:15], v[154:157], v[202:205], v[12:15]
	v_mfma_f32_16x16x32_bf16 v[16:19], v[142:145], v[202:205], v[16:19]
	v_mfma_f32_16x16x32_bf16 v[64:67], v[146:149], v[182:185], v[64:67]
	v_mfma_f32_16x16x32_bf16 v[60:63], v[158:161], v[182:185], v[60:63]
	v_mfma_f32_16x16x32_bf16 v[44:47], v[158:161], v[190:193], v[44:47]
	v_mfma_f32_16x16x32_bf16 v[48:51], v[146:149], v[190:193], v[48:51]
	v_mfma_f32_16x16x32_bf16 v[32:35], v[146:149], v[198:201], v[32:35]
	v_mfma_f32_16x16x32_bf16 v[28:31], v[158:161], v[198:201], v[28:31]
	v_mfma_f32_16x16x32_bf16 v[12:15], v[158:161], v[206:209], v[12:15]
	v_mfma_f32_16x16x32_bf16 v[16:19], v[146:149], v[206:209], v[16:19]
	s_setprio 0
	s_setprio 1
	v_mfma_f32_16x16x32_bf16 v[56:59], v[162:165], v[178:181], v[56:59]
	v_mfma_f32_16x16x32_bf16 v[52:55], v[170:173], v[178:181], v[52:55]
	v_mfma_f32_16x16x32_bf16 v[36:39], v[170:173], v[186:189], v[36:39]
	v_mfma_f32_16x16x32_bf16 v[40:43], v[162:165], v[186:189], v[40:43]
	v_mfma_f32_16x16x32_bf16 v[24:27], v[162:165], v[194:197], v[24:27]
	v_mfma_f32_16x16x32_bf16 v[20:23], v[170:173], v[194:197], v[20:23]
	v_mfma_f32_16x16x32_bf16 v[4:7], v[170:173], v[202:205], v[4:7]
	v_mfma_f32_16x16x32_bf16 v[8:11], v[162:165], v[202:205], v[8:11]
	v_mfma_f32_16x16x32_bf16 v[56:59], v[166:169], v[182:185], v[56:59]
	v_mfma_f32_16x16x32_bf16 v[52:55], v[174:177], v[182:185], v[52:55]
	v_mfma_f32_16x16x32_bf16 v[36:39], v[174:177], v[190:193], v[36:39]
	v_mfma_f32_16x16x32_bf16 v[40:43], v[166:169], v[190:193], v[40:43]
	v_mfma_f32_16x16x32_bf16 v[24:27], v[166:169], v[198:201], v[24:27]
	v_mfma_f32_16x16x32_bf16 v[20:23], v[174:177], v[198:201], v[20:23]
	v_mfma_f32_16x16x32_bf16 v[4:7], v[174:177], v[206:209], v[4:7]
	v_mfma_f32_16x16x32_bf16 v[8:11], v[166:169], v[206:209], v[8:11]
	s_barrier
; #define PG8_STAGE(bufoff, gbase, voff) do { _Pragma("unroll") for (int _i = 0; _i < 2; ++_i) \
;         __builtin_amdgcn_global_load_lds((const unsigned*)((const char*)(gbase) + (voff)[_i]), (PG8_LAS unsigned*)(lds + (bufoff) + ldsw + _i * 8192), 16, 0, 0); } while (0)
; #define PG8_LDA(dst, b, h) do { _Pragma("unroll") for (int m = 0; m < 4; ++m) _Pragma("unroll") for (int k = 0; k < 2; ++k) dst[m][k] = *(const PG8_LAS bf16x8*)(lds + PG8_SA(b, h) + aoff + m * 2048 + k * 1024); } while (0)
; #define PG8_LDB(dst, b, h) do { _Pragma("unroll") for (int n = 0; n < 2; ++n) _Pragma("unroll") for (int k = 0; k < 2; ++k) dst[n][k] = *(const PG8_LAS bf16x8*)(lds + PG8_SB(b, h) + boff + n * 2048 + k * 1024); } while (0)
; #define PG8_MMA(ai, bj, At, Bt) do { __builtin_amdgcn_s_setprio(1); _Pragma("unroll") for (int m = 0; m < 4; ++m) _Pragma("unroll") for (int n = 0; n < 2; ++n) _Pragma("unroll") for (int k = 0; k < 2; ++k) \
;         acc[ai][bj][m][n] = __builtin_amdgcn_mfma_f32_16x16x32_bf16(Bt[n][k], At[m][k], acc[ai][bj][m][n], 0, 0, 0); __builtin_amdgcn_s_setprio(0); } while (0)
; #define PG8_WAIT_V(n) asm volatile("s_waitcnt vmcnt(" #n ")" ::: "memory")
; #define PG8_WAIT_L(n) asm volatile("s_waitcnt lgkmcnt(" #n ")" ::: "memory")
; #define PG8_BAR __builtin_amdgcn_s_barrier()
; #define PG8_SCHED __builtin_amdgcn_sched_barrier(0)
; template <class Epi, class Sched, bool ALIGN_EPI = false, bool SP2 = false>
; __device__ __forceinline__ void gemm_phase(PG8_LAS unsigned char* lds, const Gemm g, const Sched& S, const Epi& E) {
;     ...
;             PG8_LDB(B0, 1, 0); PG8_LDB(B1, 1, 1); PG8_SCHED; PG8_LDA(At, 1, 0); PG8_STAGE(PG8_SA(0, 1), a2 + hstep, voffA);
;             PG8_WAIT_V(8); PG8_WAIT_L(0); PG8_BAR; PG8_MMA(0, 0, At, B0); PG8_MMA(0, 1, At, B1); PG8_BAR; PG8_SCHED;
;             PG8_LDA(At, 1, 1); PG8_STAGE(PG8_SB(1, 0), b3, voffB); PG8_STAGE(PG8_SB(1, 1), b3 + hstep, voffB); PG8_STAGE(PG8_SA(1, 0), a3, voffA);
;             PG8_WAIT_V(8); PG8_WAIT_L(0); PG8_BAR; PG8_MMA(1, 0, At, B0); PG8_MMA(1, 1, At, B1); PG8_BAR; PG8_SCHED;
	s_setprio 0
	s_add_i32 s61, 0, 0x18000
	s_add_i32 s62, 0, 0x1c000
	ds_read_b128 v[142:145], v210 offset:32768
	ds_read_b128 v[146:149], v210 offset:33792
	ds_read_b128 v[154:157], v210 offset:34816
	ds_read_b128 v[158:161], v210 offset:35840
	ds_read_b128 v[162:165], v210 offset:49152
	ds_read_b128 v[166:169], v210 offset:50176
	ds_read_b128 v[170:173], v210 offset:51200
	ds_read_b128 v[174:177], v210 offset:52224
	s_add_u32 s26, s26, 0x100000
	s_addc_u32 s27, s27, 0
	s_mov_b32 m0, s52
	ds_read_b128 v[178:181], v153 offset:32768
	ds_read_b128 v[182:185], v153 offset:33792
	ds_read_b128 v[186:189], v153 offset:34816
	ds_read_b128 v[190:193], v153 offset:35840
	ds_read_b128 v[194:197], v153 offset:36864
	ds_read_b128 v[198:201], v153 offset:37888
	ds_read_b128 v[202:205], v153 offset:38912
	ds_read_b128 v[206:209], v153 offset:39936
	global_load_lds_dwordx4 v136, s[26:27]
	s_mov_b32 m0, s53
	s_nop 0
	global_load_lds_dwordx4 v134, s[26:27]
	s_waitcnt vmcnt(8)
	s_waitcnt lgkmcnt(0)
	s_setprio 1
	s_barrier
	v_mfma_f32_16x16x32_bf16 v[128:131], v[142:145], v[178:181], v[128:131]
	v_mfma_f32_16x16x32_bf16 v[124:127], v[154:157], v[178:181], v[124:127]
	v_mfma_f32_16x16x32_bf16 v[108:111], v[154:157], v[186:189], v[108:111]
	v_mfma_f32_16x16x32_bf16 v[112:115], v[142:145], v[186:189], v[112:115]
	v_mfma_f32_16x16x32_bf16 v[96:99], v[142:145], v[194:197], v[96:99]
	v_mfma_f32_16x16x32_bf16 v[92:95], v[154:157], v[194:197], v[92:95]
	v_mfma_f32_16x16x32_bf16 v[76:79], v[154:157], v[202:205], v[76:79]
	v_mfma_f32_16x16x32_bf16 v[80:83], v[142:145], v[202:205], v[80:83]
	v_mfma_f32_16x16x32_bf16 v[128:131], v[146:149], v[182:185], v[128:131]
	v_mfma_f32_16x16x32_bf16 v[124:127], v[158:161], v[182:185], v[124:127]
	v_mfma_f32_16x16x32_bf16 v[108:111], v[158:161], v[190:193], v[108:111]
	v_mfma_f32_16x16x32_bf16 v[112:115], v[146:149], v[190:193], v[112:115]
	v_mfma_f32_16x16x32_bf16 v[96:99], v[146:149], v[198:201], v[96:99]
	v_mfma_f32_16x16x32_bf16 v[92:95], v[158:161], v[198:201], v[92:95]
	v_mfma_f32_16x16x32_bf16 v[76:79], v[158:161], v[206:209], v[76:79]
	v_mfma_f32_16x16x32_bf16 v[80:83], v[146:149], v[206:209], v[80:83]
	s_setprio 0
	s_setprio 1
	v_mfma_f32_16x16x32_bf16 v[120:123], v[162:165], v[178:181], v[120:123]
	v_mfma_f32_16x16x32_bf16 v[116:119], v[170:173], v[178:181], v[116:119]
	v_mfma_f32_16x16x32_bf16 v[100:103], v[170:173], v[186:189], v[100:103]
	v_mfma_f32_16x16x32_bf16 v[104:107], v[162:165], v[186:189], v[104:107]
	v_mfma_f32_16x16x32_bf16 v[88:91], v[162:165], v[194:197], v[88:91]
	v_mfma_f32_16x16x32_bf16 v[84:87], v[170:173], v[194:197], v[84:87]
	v_mfma_f32_16x16x32_bf16 v[68:71], v[170:173], v[202:205], v[68:71]
	v_mfma_f32_16x16x32_bf16 v[72:75], v[162:165], v[202:205], v[72:75]
	v_mfma_f32_16x16x32_bf16 v[120:123], v[166:169], v[182:185], v[120:123]
	v_mfma_f32_16x16x32_bf16 v[116:119], v[174:177], v[182:185], v[116:119]
	v_mfma_f32_16x16x32_bf16 v[100:103], v[174:177], v[190:193], v[100:103]
	v_mfma_f32_16x16x32_bf16 v[104:107], v[166:169], v[190:193], v[104:107]
	v_mfma_f32_16x16x32_bf16 v[88:91], v[166:169], v[198:201], v[88:91]
	v_mfma_f32_16x16x32_bf16 v[84:87], v[174:177], v[198:201], v[84:87]
	v_mfma_f32_16x16x32_bf16 v[68:71], v[174:177], v[206:209], v[68:71]
	v_mfma_f32_16x16x32_bf16 v[72:75], v[166:169], v[206:209], v[72:75]
	s_barrier
	s_setprio 0
	s_add_i32 s26, s61, s9
	s_mov_b32 m0, s26
	ds_read_b128 v[178:181], v153 offset:49152
	ds_read_b128 v[182:185], v153 offset:50176
	ds_read_b128 v[186:189], v153 offset:51200
	ds_read_b128 v[190:193], v153 offset:52224
	ds_read_b128 v[194:197], v153 offset:53248
	ds_read_b128 v[198:201], v153 offset:54272
	ds_read_b128 v[202:205], v153 offset:55296
	ds_read_b128 v[206:209], v153 offset:56320
	s_add_u32 s0, s0, 0x80
	s_addc_u32 s1, s1, 0
	global_load_lds_dwordx4 v2, s[0:1]
	s_add_i32 m0, s26, 0x2000
	s_add_i32 s26, s62, s9
	global_load_lds_dwordx4 v132, s[0:1]
	s_add_u32 s0, s0, 0x100000
	s_addc_u32 s1, s1, 0
	s_mov_b32 m0, s26
	s_nop 0
	global_load_lds_dwordx4 v2, s[0:1]
	s_add_i32 m0, s26, 0x2000
	s_nop 0
	global_load_lds_dwordx4 v132, s[0:1]
	s_mov_b32 m0, s54
	s_nop 0
	global_load_lds_dwordx4 v136, s[100:101]
	s_mov_b32 m0, s55
	s_nop 0
	global_load_lds_dwordx4 v134, s[100:101]
	s_waitcnt vmcnt(8)
	s_waitcnt lgkmcnt(0)
	s_setprio 1
	s_barrier
	v_mfma_f32_16x16x32_bf16 v[64:67], v[142:145], v[178:181], v[64:67]
	v_mfma_f32_16x16x32_bf16 v[60:63], v[154:157], v[178:181], v[60:63]
	v_mfma_f32_16x16x32_bf16 v[44:47], v[154:157], v[186:189], v[44:47]
	v_mfma_f32_16x16x32_bf16 v[48:51], v[142:145], v[186:189], v[48:51]
	v_mfma_f32_16x16x32_bf16 v[32:35], v[142:145], v[194:197], v[32:35]
	v_mfma_f32_16x16x32_bf16 v[28:31], v[154:157], v[194:197], v[28:31]
	v_mfma_f32_16x16x32_bf16 v[12:15], v[154:157], v[202:205], v[12:15]
	v_mfma_f32_16x16x32_bf16 v[16:19], v[142:145], v[202:205], v[16:19]
	v_mfma_f32_16x16x32_bf16 v[64:67], v[146:149], v[182:185], v[64:67]
	v_mfma_f32_16x16x32_bf16 v[60:63], v[158:161], v[182:185], v[60:63]
	v_mfma_f32_16x16x32_bf16 v[44:47], v[158:161], v[190:193], v[44:47]
	v_mfma_f32_16x16x32_bf16 v[48:51], v[146:149], v[190:193], v[48:51]
	v_mfma_f32_16x16x32_bf16 v[32:35], v[146:149], v[198:201], v[32:35]
	v_mfma_f32_16x16x32_bf16 v[28:31], v[158:161], v[198:201], v[28:31]
	v_mfma_f32_16x16x32_bf16 v[12:15], v[158:161], v[206:209], v[12:15]
	v_mfma_f32_16x16x32_bf16 v[16:19], v[146:149], v[206:209], v[16:19]
	s_setprio 0
	s_setprio 1
	v_mfma_f32_16x16x32_bf16 v[56:59], v[162:165], v[178:181], v[56:59]
	v_mfma_f32_16x16x32_bf16 v[52:55], v[170:173], v[178:181], v[52:55]
	v_mfma_f32_16x16x32_bf16 v[36:39], v[170:173], v[186:189], v[36:39]
	v_mfma_f32_16x16x32_bf16 v[40:43], v[162:165], v[186:189], v[40:43]
	v_mfma_f32_16x16x32_bf16 v[24:27], v[162:165], v[194:197], v[24:27]
	v_mfma_f32_16x16x32_bf16 v[20:23], v[170:173], v[194:197], v[20:23]
	v_mfma_f32_16x16x32_bf16 v[4:7], v[170:173], v[202:205], v[4:7]
	v_mfma_f32_16x16x32_bf16 v[8:11], v[162:165], v[202:205], v[8:11]
	v_mfma_f32_16x16x32_bf16 v[56:59], v[166:169], v[182:185], v[56:59]
	v_mfma_f32_16x16x32_bf16 v[52:55], v[174:177], v[182:185], v[52:55]
	v_mfma_f32_16x16x32_bf16 v[36:39], v[174:177], v[190:193], v[36:39]
	v_mfma_f32_16x16x32_bf16 v[40:43], v[166:169], v[190:193], v[40:43]
	v_mfma_f32_16x16x32_bf16 v[24:27], v[166:169], v[198:201], v[24:27]
	v_mfma_f32_16x16x32_bf16 v[20:23], v[174:177], v[198:201], v[20:23]
	v_mfma_f32_16x16x32_bf16 v[4:7], v[174:177], v[206:209], v[4:7]
	v_mfma_f32_16x16x32_bf16 v[8:11], v[166:169], v[206:209], v[8:11]
	s_barrier
	s_setprio 0
	s_add_i32 s60, s60, 2
	s_add_u32 s50, s50, 0x100
	s_addc_u32 s51, s51, 0
	s_add_u32 s43, s43, 0x100
	s_addc_u32 s45, s45, 0
	s_cmp_gt_u32 s60, 61
	s_cbranch_scc0 .LBB0_2089
	s_and_b64 vcc, exec, s[40:41]
	s_cbranch_vccz .LBB0_2092
	s_barrier

; #define PG8_STAGE(bufoff, gbase, voff) do { _Pragma("unroll") for (int _i = 0; _i < 2; ++_i) \
;         __builtin_amdgcn_global_load_lds((const unsigned*)((const char*)(gbase) + (voff)[_i]), (PG8_LAS unsigned*)(lds + (bufoff) + ldsw + _i * 8192), 16, 0, 0); } while (0)
; #define PG8_LDA(dst, b, h) do { _Pragma("unroll") for (int m = 0; m < 4; ++m) _Pragma("unroll") for (int k = 0; k < 2; ++k) dst[m][k] = *(const PG8_LAS bf16x8*)(lds + PG8_SA(b, h) + aoff + m * 2048 + k * 1024); } while (0)
; #define PG8_LDB(dst, b, h) do { _Pragma("unroll") for (int n = 0; n < 2; ++n) _Pragma("unroll") for (int k = 0; k < 2; ++k) dst[n][k] = *(const PG8_LAS bf16x8*)(lds + PG8_SB(b, h) + boff + n * 2048 + k * 1024); } while (0)
; #define PG8_MMA(ai, bj, At, Bt) do { __builtin_amdgcn_s_setprio(1); _Pragma("unroll") for (int m = 0; m < 4; ++m) _Pragma("unroll") for (int n = 0; n < 2; ++n) _Pragma("unroll") for (int k = 0; k < 2; ++k) \
;         acc[ai][bj][m][n] = __builtin_amdgcn_mfma_f32_16x16x32_bf16(Bt[n][k], At[m][k], acc[ai][bj][m][n], 0, 0, 0); __builtin_amdgcn_s_setprio(0); } while (0)
; #define PG8_WAIT_V(n) asm volatile("s_waitcnt vmcnt(" #n ")" ::: "memory")
; #define PG8_WAIT_L(n) asm volatile("s_waitcnt lgkmcnt(" #n ")" ::: "memory")
; template <class Epi, class Sched, bool ALIGN_EPI = false, bool SP2 = false>
; __device__ __forceinline__ void gemm_phase(PG8_LAS unsigned char* lds, const Gemm g, const Sched& S, const Epi& E) {
;     ...
;             const bool last = (t == nt - 2);
;             const char* a1 = cA + (size_t)(t + 1) * kstep;
;             const char* a2 = last ? nA : cA + (size_t)(t + 2) * kstep; const char* b2 = last ? nB : cB + (size_t)(t + 2) * kstep;
;             const char* a3 = a2 + kstep; const char* b3 = b2 + kstep;
;             if (last && has_next) S.a_ready(nxt);
;             if constexpr (SP2) {
;             PG8_LDB(B0, 0, 0); PG8_LDB(B1, 0, 1); PG8_SCHED; PG8_LDA(At, 0, 0); PG8_STAGE(PG8_SA(1, 1), a1 + hstep, voffA);
;             PG8_WAIT_V(8); PG8_WAIT_L(0); PG8_BAR; PG8_MMA(0, 0, At, B0); PG8_MMA(0, 1, At, B1); PG8_BAR; PG8_SCHED;
;             PG8_LDA(At, 0, 1); PG8_STAGE(PG8_SB(0, 0), b2, voffB); PG8_STAGE(PG8_SB(0, 1), b2 + hstep, voffB); PG8_STAGE(PG8_SA(0, 0), a2, voffA);
;             PG8_WAIT_V(8); PG8_WAIT_L(0); PG8_BAR; PG8_MMA(1, 0, At, B0); PG8_MMA(1, 1, At, B1); PG8_BAR; PG8_SCHED;
.LBB0_2115:
	s_add_u32 s0, s40, 0xfff00080
	s_addc_u32 s1, s41, -1
	s_add_i32 s77, 0, 0x10000
	s_cmp_eq_u32 s76, 60
	s_cselect_b32 s27, s49, s1
	s_cselect_b32 s26, s57, s0
	s_cselect_b32 s1, s47, s59
	s_cselect_b32 s0, s73, s58
	s_add_i32 s80, 0, 0x14000
	s_waitcnt vmcnt(0)
	ds_read_b128 v[132:135], v188
	ds_read_b128 v[136:139], v188 offset:1024
	ds_read_b128 v[152:155], v188 offset:2048
	ds_read_b128 v[156:159], v188 offset:3072
	ds_read_b128 v[160:163], v188 offset:16384
	ds_read_b128 v[164:167], v188 offset:17408
	ds_read_b128 v[168:171], v188 offset:18432
	ds_read_b128 v[172:175], v188 offset:19456
	s_add_i32 m0, s11, 0xc000
	ds_read_b128 v[176:179], v194
	ds_read_b128 v[180:183], v194 offset:1024
	ds_read_b128 v[184:187], v194 offset:2048
	ds_read_b128 v[196:199], v194 offset:3072
	ds_read_b128 v[200:203], v194 offset:4096
	ds_read_b128 v[204:207], v194 offset:5120
	ds_read_b128 v[208:211], v194 offset:6144
	ds_read_b128 v[212:215], v194 offset:7168
	global_load_lds_dwordx4 v148, s[40:41]
	s_add_i32 m0, s11, 0xe000
	s_nop 0
	global_load_lds_dwordx4 v150, s[40:41]
	s_waitcnt vmcnt(8)
	s_waitcnt lgkmcnt(0)
	s_setprio 1
	s_barrier
	v_mfma_f32_16x16x32_bf16 v[128:131], v[132:135], v[176:179], v[128:131]
	v_mfma_f32_16x16x32_bf16 v[124:127], v[152:155], v[176:179], v[124:127]
	v_mfma_f32_16x16x32_bf16 v[108:111], v[152:155], v[184:187], v[108:111]
	v_mfma_f32_16x16x32_bf16 v[112:115], v[132:135], v[184:187], v[112:115]
	v_mfma_f32_16x16x32_bf16 v[96:99], v[132:135], v[200:203], v[96:99]
	v_mfma_f32_16x16x32_bf16 v[92:95], v[152:155], v[200:203], v[92:95]
	v_mfma_f32_16x16x32_bf16 v[76:79], v[152:155], v[208:211], v[76:79]
	v_mfma_f32_16x16x32_bf16 v[80:83], v[132:135], v[208:211], v[80:83]
	v_mfma_f32_16x16x32_bf16 v[128:131], v[136:139], v[180:183], v[128:131]
	v_mfma_f32_16x16x32_bf16 v[124:127], v[156:159], v[180:183], v[124:127]
	v_mfma_f32_16x16x32_bf16 v[108:111], v[156:159], v[196:199], v[108:111]
	v_mfma_f32_16x16x32_bf16 v[112:115], v[136:139], v[196:199], v[112:115]
	v_mfma_f32_16x16x32_bf16 v[96:99], v[136:139], v[204:207], v[96:99]
	v_mfma_f32_16x16x32_bf16 v[92:95], v[156:159], v[204:207], v[92:95]
	v_mfma_f32_16x16x32_bf16 v[76:79], v[156:159], v[212:215], v[76:79]
	v_mfma_f32_16x16x32_bf16 v[80:83], v[136:139], v[212:215], v[80:83]
	s_setprio 0
	s_setprio 1
	v_mfma_f32_16x16x32_bf16 v[120:123], v[160:163], v[176:179], v[120:123]
	v_mfma_f32_16x16x32_bf16 v[116:119], v[168:171], v[176:179], v[116:119]
	v_mfma_f32_16x16x32_bf16 v[100:103], v[168:171], v[184:187], v[100:103]
	v_mfma_f32_16x16x32_bf16 v[104:107], v[160:163], v[184:187], v[104:107]
	v_mfma_f32_16x16x32_bf16 v[88:91], v[160:163], v[200:203], v[88:91]
	v_mfma_f32_16x16x32_bf16 v[84:87], v[168:171], v[200:203], v[84:87]
	v_mfma_f32_16x16x32_bf16 v[68:71], v[168:171], v[208:211], v[68:71]
	v_mfma_f32_16x16x32_bf16 v[72:75], v[160:163], v[208:211], v[72:75]
	v_mfma_f32_16x16x32_bf16 v[120:123], v[164:167], v[180:183], v[120:123]
	v_mfma_f32_16x16x32_bf16 v[116:119], v[172:175], v[180:183], v[116:119]
	v_mfma_f32_16x16x32_bf16 v[100:103], v[172:175], v[196:199], v[100:103]
	v_mfma_f32_16x16x32_bf16 v[104:107], v[164:167], v[196:199], v[104:107]
	v_mfma_f32_16x16x32_bf16 v[88:91], v[164:167], v[204:207], v[88:91]
	v_mfma_f32_16x16x32_bf16 v[84:87], v[172:175], v[204:207], v[84:87]
	v_mfma_f32_16x16x32_bf16 v[68:71], v[172:175], v[212:215], v[68:71]
	v_mfma_f32_16x16x32_bf16 v[72:75], v[164:167], v[212:215], v[72:75]
	s_barrier
	s_setprio 0
	s_add_i32 s77, s77, s10
	s_mov_b32 m0, s77
	ds_read_b128 v[176:179], v194 offset:16384
	ds_read_b128 v[180:183], v194 offset:17408
	ds_read_b128 v[184:187], v194 offset:18432
	ds_read_b128 v[196:199], v194 offset:19456
	ds_read_b128 v[200:203], v194 offset:20480
	ds_read_b128 v[204:207], v194 offset:21504
	ds_read_b128 v[208:211], v194 offset:22528
	ds_read_b128 v[212:215], v194 offset:23552
	global_load_lds_dwordx4 v2, s[0:1]
	s_add_i32 m0, s77, 0x2000
	s_add_u32 s78, s0, 0x100000
	s_addc_u32 s79, s1, 0
	s_add_i32 s77, s80, s10
	global_load_lds_dwordx4 v144, s[0:1]
	s_mov_b32 m0, s77
	s_nop 0
	global_load_lds_dwordx4 v2, s[78:79]
	s_add_i32 m0, s77, 0x2000
	s_nop 0
	global_load_lds_dwordx4 v144, s[78:79]
	s_mov_b32 m0, s11
	s_nop 0
	global_load_lds_dwordx4 v140, s[26:27]
	s_mov_b32 m0, s55
	s_nop 0
	global_load_lds_dwordx4 v142, s[26:27]
	s_add_u32 s100, s26, 0x80
	s_addc_u32 s101, s27, 0
	s_waitcnt vmcnt(8)
	s_waitcnt lgkmcnt(0)
	s_setprio 1
	s_barrier
	v_mfma_f32_16x16x32_bf16 v[64:67], v[132:135], v[176:179], v[64:67]
	v_mfma_f32_16x16x32_bf16 v[60:63], v[152:155], v[176:179], v[60:63]
	v_mfma_f32_16x16x32_bf16 v[44:47], v[152:155], v[184:187], v[44:47]
	v_mfma_f32_16x16x32_bf16 v[48:51], v[132:135], v[184:187], v[48:51]
	v_mfma_f32_16x16x32_bf16 v[32:35], v[132:135], v[200:203], v[32:35]
	v_mfma_f32_16x16x32_bf16 v[28:31], v[152:155], v[200:203], v[28:31]
	v_mfma_f32_16x16x32_bf16 v[12:15], v[152:155], v[208:211], v[12:15]
	v_mfma_f32_16x16x32_bf16 v[16:19], v[132:135], v[208:211], v[16:19]
	v_mfma_f32_16x16x32_bf16 v[64:67], v[136:139], v[180:183], v[64:67]
	v_mfma_f32_16x16x32_bf16 v[60:63], v[156:159], v[180:183], v[60:63]
	v_mfma_f32_16x16x32_bf16 v[44:47], v[156:159], v[196:199], v[44:47]
	v_mfma_f32_16x16x32_bf16 v[48:51], v[136:139], v[196:199], v[48:51]
	v_mfma_f32_16x16x32_bf16 v[32:35], v[136:139], v[204:207], v[32:35]
	v_mfma_f32_16x16x32_bf16 v[28:31], v[156:159], v[204:207], v[28:31]
	v_mfma_f32_16x16x32_bf16 v[12:15], v[156:159], v[212:215], v[12:15]
	v_mfma_f32_16x16x32_bf16 v[16:19], v[136:139], v[212:215], v[16:19]
	s_setprio 0
	s_setprio 1
	v_mfma_f32_16x16x32_bf16 v[56:59], v[160:163], v[176:179], v[56:59]
	v_mfma_f32_16x16x32_bf16 v[52:55], v[168:171], v[176:179], v[52:55]
	v_mfma_f32_16x16x32_bf16 v[36:39], v[168:171], v[184:187], v[36:39]
	v_mfma_f32_16x16x32_bf16 v[40:43], v[160:163], v[184:187], v[40:43]
	v_mfma_f32_16x16x32_bf16 v[24:27], v[160:163], v[200:203], v[24:27]
	v_mfma_f32_16x16x32_bf16 v[20:23], v[168:171], v[200:203], v[20:23]
	v_mfma_f32_16x16x32_bf16 v[4:7], v[168:171], v[208:211], v[4:7]
	v_mfma_f32_16x16x32_bf16 v[8:11], v[160:163], v[208:211], v[8:11]
	v_mfma_f32_16x16x32_bf16 v[56:59], v[164:167], v[180:183], v[56:59]
	v_mfma_f32_16x16x32_bf16 v[52:55], v[172:175], v[180:183], v[52:55]
	v_mfma_f32_16x16x32_bf16 v[36:39], v[172:175], v[196:199], v[36:39]
	v_mfma_f32_16x16x32_bf16 v[40:43], v[164:167], v[196:199], v[40:43]
	v_mfma_f32_16x16x32_bf16 v[24:27], v[164:167], v[204:207], v[24:27]
	v_mfma_f32_16x16x32_bf16 v[20:23], v[172:175], v[204:207], v[20:23]
	v_mfma_f32_16x16x32_bf16 v[4:7], v[172:175], v[212:215], v[4:7]
	v_mfma_f32_16x16x32_bf16 v[8:11], v[164:167], v[212:215], v[8:11]
	s_barrier
; #define PG8_STAGE(bufoff, gbase, voff) do { _Pragma("unroll") for (int _i = 0; _i < 2; ++_i) \
;         __builtin_amdgcn_global_load_lds((const unsigned*)((const char*)(gbase) + (voff)[_i]), (PG8_LAS unsigned*)(lds + (bufoff) + ldsw + _i * 8192), 16, 0, 0); } while (0)
; #define PG8_LDA(dst, b, h) do { _Pragma("unroll") for (int m = 0; m < 4; ++m) _Pragma("unroll") for (int k = 0; k < 2; ++k) dst[m][k] = *(const PG8_LAS bf16x8*)(lds + PG8_SA(b, h) + aoff + m * 2048 + k * 1024); } while (0)
; #define PG8_LDB(dst, b, h) do { _Pragma("unroll") for (int n = 0; n < 2; ++n) _Pragma("unroll") for (int k = 0; k < 2; ++k) dst[n][k] = *(const PG8_LAS bf16x8*)(lds + PG8_SB(b, h) + boff + n * 2048 + k * 1024); } while (0)
; #define PG8_MMA(ai, bj, At, Bt) do { __builtin_amdgcn_s_setprio(1); _Pragma("unroll") for (int m = 0; m < 4; ++m) _Pragma("unroll") for (int n = 0; n < 2; ++n) _Pragma("unroll") for (int k = 0; k < 2; ++k) \
;         acc[ai][bj][m][n] = __builtin_amdgcn_mfma_f32_16x16x32_bf16(Bt[n][k], At[m][k], acc[ai][bj][m][n], 0, 0, 0); __builtin_amdgcn_s_setprio(0); } while (0)
; #define PG8_WAIT_V(n) asm volatile("s_waitcnt vmcnt(" #n ")" ::: "memory")
; #define PG8_WAIT_L(n) asm volatile("s_waitcnt lgkmcnt(" #n ")" ::: "memory")
; #define PG8_BAR __builtin_amdgcn_s_barrier()
; #define PG8_SCHED __builtin_amdgcn_sched_barrier(0)
; template <class Epi, class Sched, bool ALIGN_EPI = false, bool SP2 = false>
; __device__ __forceinline__ void gemm_phase(PG8_LAS unsigned char* lds, const Gemm g, const Sched& S, const Epi& E) {
;     ...
;             PG8_LDB(B0, 1, 0); PG8_LDB(B1, 1, 1); PG8_SCHED; PG8_LDA(At, 1, 0); PG8_STAGE(PG8_SA(0, 1), a2 + hstep, voffA);
;             PG8_WAIT_V(8); PG8_WAIT_L(0); PG8_BAR; PG8_MMA(0, 0, At, B0); PG8_MMA(0, 1, At, B1); PG8_BAR; PG8_SCHED;
;             PG8_LDA(At, 1, 1); PG8_STAGE(PG8_SB(1, 0), b3, voffB); PG8_STAGE(PG8_SB(1, 1), b3 + hstep, voffB); PG8_STAGE(PG8_SA(1, 0), a3, voffA);
;             PG8_WAIT_V(8); PG8_WAIT_L(0); PG8_BAR; PG8_MMA(1, 0, At, B0); PG8_MMA(1, 1, At, B1); PG8_BAR; PG8_SCHED;
	s_setprio 0
	s_add_i32 s77, 0, 0x18000
	s_add_i32 s78, 0, 0x1c000
	ds_read_b128 v[132:135], v188 offset:32768
	ds_read_b128 v[136:139], v188 offset:33792
	ds_read_b128 v[152:155], v188 offset:34816
	ds_read_b128 v[156:159], v188 offset:35840
	ds_read_b128 v[160:163], v188 offset:49152
	ds_read_b128 v[164:167], v188 offset:50176
	ds_read_b128 v[168:171], v188 offset:51200
	ds_read_b128 v[172:175], v188 offset:52224
	s_add_u32 s26, s26, 0x100000
	s_addc_u32 s27, s27, 0
	s_mov_b32 m0, s60
	ds_read_b128 v[176:179], v194 offset:32768
	ds_read_b128 v[180:183], v194 offset:33792
	ds_read_b128 v[184:187], v194 offset:34816
	ds_read_b128 v[196:199], v194 offset:35840
	ds_read_b128 v[200:203], v194 offset:36864
	ds_read_b128 v[204:207], v194 offset:37888
	ds_read_b128 v[208:211], v194 offset:38912
	ds_read_b128 v[212:215], v194 offset:39936
	global_load_lds_dwordx4 v140, s[26:27]
	s_mov_b32 m0, s61
	s_nop 0
	global_load_lds_dwordx4 v142, s[26:27]
	s_waitcnt vmcnt(8)
	s_waitcnt lgkmcnt(0)
	s_setprio 1
	s_barrier
	v_mfma_f32_16x16x32_bf16 v[128:131], v[132:135], v[176:179], v[128:131]
	v_mfma_f32_16x16x32_bf16 v[124:127], v[152:155], v[176:179], v[124:127]
	v_mfma_f32_16x16x32_bf16 v[108:111], v[152:155], v[184:187], v[108:111]
	v_mfma_f32_16x16x32_bf16 v[112:115], v[132:135], v[184:187], v[112:115]
	v_mfma_f32_16x16x32_bf16 v[96:99], v[132:135], v[200:203], v[96:99]
	v_mfma_f32_16x16x32_bf16 v[92:95], v[152:155], v[200:203], v[92:95]
	v_mfma_f32_16x16x32_bf16 v[76:79], v[152:155], v[208:211], v[76:79]
	v_mfma_f32_16x16x32_bf16 v[80:83], v[132:135], v[208:211], v[80:83]
	v_mfma_f32_16x16x32_bf16 v[128:131], v[136:139], v[180:183], v[128:131]
	v_mfma_f32_16x16x32_bf16 v[124:127], v[156:159], v[180:183], v[124:127]
	v_mfma_f32_16x16x32_bf16 v[108:111], v[156:159], v[196:199], v[108:111]
	v_mfma_f32_16x16x32_bf16 v[112:115], v[136:139], v[196:199], v[112:115]
	v_mfma_f32_16x16x32_bf16 v[96:99], v[136:139], v[204:207], v[96:99]
	v_mfma_f32_16x16x32_bf16 v[92:95], v[156:159], v[204:207], v[92:95]
	v_mfma_f32_16x16x32_bf16 v[76:79], v[156:159], v[212:215], v[76:79]
	v_mfma_f32_16x16x32_bf16 v[80:83], v[136:139], v[212:215], v[80:83]
	s_setprio 0
	s_setprio 1
	v_mfma_f32_16x16x32_bf16 v[120:123], v[160:163], v[176:179], v[120:123]
	v_mfma_f32_16x16x32_bf16 v[116:119], v[168:171], v[176:179], v[116:119]
	v_mfma_f32_16x16x32_bf16 v[100:103], v[168:171], v[184:187], v[100:103]
	v_mfma_f32_16x16x32_bf16 v[104:107], v[160:163], v[184:187], v[104:107]
	v_mfma_f32_16x16x32_bf16 v[88:91], v[160:163], v[200:203], v[88:91]
	v_mfma_f32_16x16x32_bf16 v[84:87], v[168:171], v[200:203], v[84:87]
	v_mfma_f32_16x16x32_bf16 v[68:71], v[168:171], v[208:211], v[68:71]
	v_mfma_f32_16x16x32_bf16 v[72:75], v[160:163], v[208:211], v[72:75]
	v_mfma_f32_16x16x32_bf16 v[120:123], v[164:167], v[180:183], v[120:123]
	v_mfma_f32_16x16x32_bf16 v[116:119], v[172:175], v[180:183], v[116:119]
	v_mfma_f32_16x16x32_bf16 v[100:103], v[172:175], v[196:199], v[100:103]
	v_mfma_f32_16x16x32_bf16 v[104:107], v[164:167], v[196:199], v[104:107]
	v_mfma_f32_16x16x32_bf16 v[88:91], v[164:167], v[204:207], v[88:91]
	v_mfma_f32_16x16x32_bf16 v[84:87], v[172:175], v[204:207], v[84:87]
	v_mfma_f32_16x16x32_bf16 v[68:71], v[172:175], v[212:215], v[68:71]
	v_mfma_f32_16x16x32_bf16 v[72:75], v[164:167], v[212:215], v[72:75]
	s_barrier
	s_setprio 0
	s_add_i32 s26, s77, s10
	s_mov_b32 m0, s26
	ds_read_b128 v[176:179], v194 offset:49152
	ds_read_b128 v[180:183], v194 offset:50176
	ds_read_b128 v[184:187], v194 offset:51200
	ds_read_b128 v[196:199], v194 offset:52224
	ds_read_b128 v[200:203], v194 offset:53248
	ds_read_b128 v[204:207], v194 offset:54272
	ds_read_b128 v[208:211], v194 offset:55296
	ds_read_b128 v[212:215], v194 offset:56320
	s_add_u32 s0, s0, 0x80
	s_addc_u32 s1, s1, 0
	global_load_lds_dwordx4 v2, s[0:1]
	s_add_i32 m0, s26, 0x2000
	s_add_i32 s26, s78, s10
	global_load_lds_dwordx4 v144, s[0:1]
	s_add_u32 s0, s0, 0x100000
	s_addc_u32 s1, s1, 0
	s_mov_b32 m0, s26
	s_nop 0
	global_load_lds_dwordx4 v2, s[0:1]
	s_add_i32 m0, s26, 0x2000
	s_nop 0
	global_load_lds_dwordx4 v144, s[0:1]
	s_mov_b32 m0, s62
	s_nop 0
	global_load_lds_dwordx4 v140, s[100:101]
	s_mov_b32 m0, s63
	s_nop 0
	global_load_lds_dwordx4 v142, s[100:101]
	s_waitcnt vmcnt(8)
	s_waitcnt lgkmcnt(0)
	s_setprio 1
	s_barrier
	v_mfma_f32_16x16x32_bf16 v[64:67], v[132:135], v[176:179], v[64:67]
	v_mfma_f32_16x16x32_bf16 v[60:63], v[152:155], v[176:179], v[60:63]
	v_mfma_f32_16x16x32_bf16 v[44:47], v[152:155], v[184:187], v[44:47]
	v_mfma_f32_16x16x32_bf16 v[48:51], v[132:135], v[184:187], v[48:51]
	v_mfma_f32_16x16x32_bf16 v[32:35], v[132:135], v[200:203], v[32:35]
	v_mfma_f32_16x16x32_bf16 v[28:31], v[152:155], v[200:203], v[28:31]
	v_mfma_f32_16x16x32_bf16 v[12:15], v[152:155], v[208:211], v[12:15]
	v_mfma_f32_16x16x32_bf16 v[16:19], v[132:135], v[208:211], v[16:19]
	v_mfma_f32_16x16x32_bf16 v[64:67], v[136:139], v[180:183], v[64:67]
	v_mfma_f32_16x16x32_bf16 v[60:63], v[156:159], v[180:183], v[60:63]
	v_mfma_f32_16x16x32_bf16 v[44:47], v[156:159], v[196:199], v[44:47]
	v_mfma_f32_16x16x32_bf16 v[48:51], v[136:139], v[196:199], v[48:51]
	v_mfma_f32_16x16x32_bf16 v[32:35], v[136:139], v[204:207], v[32:35]
	v_mfma_f32_16x16x32_bf16 v[28:31], v[156:159], v[204:207], v[28:31]
	v_mfma_f32_16x16x32_bf16 v[12:15], v[156:159], v[212:215], v[12:15]
	v_mfma_f32_16x16x32_bf16 v[16:19], v[136:139], v[212:215], v[16:19]
	s_setprio 0
	s_setprio 1
	v_mfma_f32_16x16x32_bf16 v[56:59], v[160:163], v[176:179], v[56:59]
	v_mfma_f32_16x16x32_bf16 v[52:55], v[168:171], v[176:179], v[52:55]
	v_mfma_f32_16x16x32_bf16 v[36:39], v[168:171], v[184:187], v[36:39]
	v_mfma_f32_16x16x32_bf16 v[40:43], v[160:163], v[184:187], v[40:43]
	v_mfma_f32_16x16x32_bf16 v[24:27], v[160:163], v[200:203], v[24:27]
	v_mfma_f32_16x16x32_bf16 v[20:23], v[168:171], v[200:203], v[20:23]
	v_mfma_f32_16x16x32_bf16 v[4:7], v[168:171], v[208:211], v[4:7]
	v_mfma_f32_16x16x32_bf16 v[8:11], v[160:163], v[208:211], v[8:11]
	v_mfma_f32_16x16x32_bf16 v[56:59], v[164:167], v[180:183], v[56:59]
	v_mfma_f32_16x16x32_bf16 v[52:55], v[172:175], v[180:183], v[52:55]
	v_mfma_f32_16x16x32_bf16 v[36:39], v[172:175], v[196:199], v[36:39]
	v_mfma_f32_16x16x32_bf16 v[40:43], v[164:167], v[196:199], v[40:43]
	v_mfma_f32_16x16x32_bf16 v[24:27], v[164:167], v[204:207], v[24:27]
	v_mfma_f32_16x16x32_bf16 v[20:23], v[172:175], v[204:207], v[20:23]
	v_mfma_f32_16x16x32_bf16 v[4:7], v[172:175], v[212:215], v[4:7]
	v_mfma_f32_16x16x32_bf16 v[8:11], v[164:167], v[212:215], v[8:11]
	s_barrier
	s_setprio 0
	s_add_i32 s76, s76, 2
	s_add_u32 s40, s40, 0x100
	s_addc_u32 s41, s41, 0
	s_add_u32 s58, s58, 0x100
	s_addc_u32 s59, s59, 0
	s_cmp_gt_u32 s76, 61
	s_cbranch_scc0 .LBB0_2115
	s_and_b64 vcc, exec, s[36:37]
	s_cbranch_vccz .LBB0_2118
	s_barrier

; #define PG8_STAGE(bufoff, gbase, voff) do { _Pragma("unroll") for (int _i = 0; _i < 2; ++_i) \
;         __builtin_amdgcn_global_load_lds((const unsigned*)((const char*)(gbase) + (voff)[_i]), (PG8_LAS unsigned*)(lds + (bufoff) + ldsw + _i * 8192), 16, 0, 0); } while (0)
; #define PG8_LDA(dst, b, h) do { _Pragma("unroll") for (int m = 0; m < 4; ++m) _Pragma("unroll") for (int k = 0; k < 2; ++k) dst[m][k] = *(const PG8_LAS bf16x8*)(lds + PG8_SA(b, h) + aoff + m * 2048 + k * 1024); } while (0)
; #define PG8_LDB(dst, b, h) do { _Pragma("unroll") for (int n = 0; n < 2; ++n) _Pragma("unroll") for (int k = 0; k < 2; ++k) dst[n][k] = *(const PG8_LAS bf16x8*)(lds + PG8_SB(b, h) + boff + n * 2048 + k * 1024); } while (0)
; #define PG8_MMA(ai, bj, At, Bt) do { __builtin_amdgcn_s_setprio(1); _Pragma("unroll") for (int m = 0; m < 4; ++m) _Pragma("unroll") for (int n = 0; n < 2; ++n) _Pragma("unroll") for (int k = 0; k < 2; ++k) \
;         acc[ai][bj][m][n] = __builtin_amdgcn_mfma_f32_16x16x32_bf16(Bt[n][k], At[m][k], acc[ai][bj][m][n], 0, 0, 0); __builtin_amdgcn_s_setprio(0); } while (0)
; #define PG8_WAIT_V(n) asm volatile("s_waitcnt vmcnt(" #n ")" ::: "memory")
; #define PG8_WAIT_L(n) asm volatile("s_waitcnt lgkmcnt(" #n ")" ::: "memory")
; template <class Epi, class Sched, bool ALIGN_EPI = false, bool SP2 = false>
; __device__ __forceinline__ void gemm_phase(PG8_LAS unsigned char* lds, const Gemm g, const Sched& S, const Epi& E) {
;     ...
;             const bool last = (t == nt - 2);
;             const char* a1 = cA + (size_t)(t + 1) * kstep;
;             const char* a2 = last ? nA : cA + (size_t)(t + 2) * kstep; const char* b2 = last ? nB : cB + (size_t)(t + 2) * kstep;
;             const char* a3 = a2 + kstep; const char* b3 = b2 + kstep;
;             if (last && has_next) S.a_ready(nxt);
;             if constexpr (SP2) {
;             PG8_LDB(B0, 0, 0); PG8_LDB(B1, 0, 1); PG8_SCHED; PG8_LDA(At, 0, 0); PG8_STAGE(PG8_SA(1, 1), a1 + hstep, voffA);
;             PG8_WAIT_V(8); PG8_WAIT_L(0); PG8_BAR; PG8_MMA(0, 0, At, B0); PG8_MMA(0, 1, At, B1); PG8_BAR; PG8_SCHED;
;             PG8_LDA(At, 0, 1); PG8_STAGE(PG8_SB(0, 0), b2, voffB); PG8_STAGE(PG8_SB(0, 1), b2 + hstep, voffB); PG8_STAGE(PG8_SA(0, 0), a2, voffA);
;             PG8_WAIT_V(8); PG8_WAIT_L(0); PG8_BAR; PG8_MMA(1, 0, At, B0); PG8_MMA(1, 1, At, B1); PG8_BAR; PG8_SCHED;
.LBB0_2692:
	s_add_u32 s0, s56, 0xfffe0080
	s_addc_u32 s1, s57, -1
	s_add_i32 s63, 0, 0x10000
	s_cmp_eq_u32 s62, 4
	s_cselect_b32 s27, s51, s1
	s_cselect_b32 s26, s50, s0
	s_cselect_b32 s1, s53, s49
	s_cselect_b32 s0, s52, s47
	s_add_i32 s66, 0, 0x14000
	ds_read_b128 v[142:145], v210
	ds_read_b128 v[150:153], v210 offset:1024
	ds_read_b128 v[154:157], v210 offset:2048
	ds_read_b128 v[158:161], v210 offset:3072
	ds_read_b128 v[162:165], v210 offset:16384
	ds_read_b128 v[166:169], v210 offset:17408
	ds_read_b128 v[170:173], v210 offset:18432
	ds_read_b128 v[174:177], v210 offset:19456
	s_add_i32 m0, s10, 0xc000
	ds_read_b128 v[178:181], v149
	ds_read_b128 v[182:185], v149 offset:1024
	ds_read_b128 v[186:189], v149 offset:2048
	ds_read_b128 v[190:193], v149 offset:3072
	ds_read_b128 v[194:197], v149 offset:4096
	ds_read_b128 v[198:201], v149 offset:5120
	ds_read_b128 v[202:205], v149 offset:6144
	ds_read_b128 v[206:209], v149 offset:7168
	global_load_lds_dwordx4 v138, s[56:57]
	s_add_i32 m0, s10, 0xe000
	s_nop 0
	global_load_lds_dwordx4 v140, s[56:57]
	s_waitcnt vmcnt(8)
	s_waitcnt lgkmcnt(0)
	s_setprio 1
	s_barrier
	v_mfma_f32_16x16x32_bf16 v[128:131], v[142:145], v[178:181], v[128:131]
	v_mfma_f32_16x16x32_bf16 v[124:127], v[154:157], v[178:181], v[124:127]
	v_mfma_f32_16x16x32_bf16 v[108:111], v[154:157], v[186:189], v[108:111]
	v_mfma_f32_16x16x32_bf16 v[112:115], v[142:145], v[186:189], v[112:115]
	v_mfma_f32_16x16x32_bf16 v[96:99], v[142:145], v[194:197], v[96:99]
	v_mfma_f32_16x16x32_bf16 v[92:95], v[154:157], v[194:197], v[92:95]
	v_mfma_f32_16x16x32_bf16 v[76:79], v[154:157], v[202:205], v[76:79]
	v_mfma_f32_16x16x32_bf16 v[80:83], v[142:145], v[202:205], v[80:83]
	v_mfma_f32_16x16x32_bf16 v[128:131], v[150:153], v[182:185], v[128:131]
	v_mfma_f32_16x16x32_bf16 v[124:127], v[158:161], v[182:185], v[124:127]
	v_mfma_f32_16x16x32_bf16 v[108:111], v[158:161], v[190:193], v[108:111]
	v_mfma_f32_16x16x32_bf16 v[112:115], v[150:153], v[190:193], v[112:115]
	v_mfma_f32_16x16x32_bf16 v[96:99], v[150:153], v[198:201], v[96:99]
	v_mfma_f32_16x16x32_bf16 v[92:95], v[158:161], v[198:201], v[92:95]
	v_mfma_f32_16x16x32_bf16 v[76:79], v[158:161], v[206:209], v[76:79]
	v_mfma_f32_16x16x32_bf16 v[80:83], v[150:153], v[206:209], v[80:83]
	s_setprio 0
	s_setprio 1
	v_mfma_f32_16x16x32_bf16 v[120:123], v[162:165], v[178:181], v[120:123]
	v_mfma_f32_16x16x32_bf16 v[116:119], v[170:173], v[178:181], v[116:119]
	v_mfma_f32_16x16x32_bf16 v[100:103], v[170:173], v[186:189], v[100:103]
	v_mfma_f32_16x16x32_bf16 v[104:107], v[162:165], v[186:189], v[104:107]
	v_mfma_f32_16x16x32_bf16 v[88:91], v[162:165], v[194:197], v[88:91]
	v_mfma_f32_16x16x32_bf16 v[84:87], v[170:173], v[194:197], v[84:87]
	v_mfma_f32_16x16x32_bf16 v[68:71], v[170:173], v[202:205], v[68:71]
	v_mfma_f32_16x16x32_bf16 v[72:75], v[162:165], v[202:205], v[72:75]
	v_mfma_f32_16x16x32_bf16 v[120:123], v[166:169], v[182:185], v[120:123]
	v_mfma_f32_16x16x32_bf16 v[116:119], v[174:177], v[182:185], v[116:119]
	v_mfma_f32_16x16x32_bf16 v[100:103], v[174:177], v[190:193], v[100:103]
	v_mfma_f32_16x16x32_bf16 v[104:107], v[166:169], v[190:193], v[104:107]
	v_mfma_f32_16x16x32_bf16 v[88:91], v[166:169], v[198:201], v[88:91]
	v_mfma_f32_16x16x32_bf16 v[84:87], v[174:177], v[198:201], v[84:87]
	v_mfma_f32_16x16x32_bf16 v[68:71], v[174:177], v[206:209], v[68:71]
	v_mfma_f32_16x16x32_bf16 v[72:75], v[166:169], v[206:209], v[72:75]
	s_barrier
	s_setprio 0
	s_add_i32 s63, s63, s9
	s_mov_b32 m0, s63
	ds_read_b128 v[178:181], v149 offset:16384
	ds_read_b128 v[182:185], v149 offset:17408
	ds_read_b128 v[186:189], v149 offset:18432
	ds_read_b128 v[190:193], v149 offset:19456
	ds_read_b128 v[194:197], v149 offset:20480
	ds_read_b128 v[198:201], v149 offset:21504
	ds_read_b128 v[202:205], v149 offset:22528
	ds_read_b128 v[206:209], v149 offset:23552
	global_load_lds_dwordx4 v2, s[0:1]
	s_add_i32 m0, s63, 0x2000
	s_add_u32 s64, s0, 0x20000
	s_addc_u32 s65, s1, 0
	s_add_i32 s63, s66, s9
	global_load_lds_dwordx4 v136, s[0:1]
	s_mov_b32 m0, s63
	s_nop 0
	global_load_lds_dwordx4 v2, s[64:65]
	s_add_i32 m0, s63, 0x2000
	s_nop 0
	global_load_lds_dwordx4 v136, s[64:65]
	s_mov_b32 m0, s10
	s_nop 0
	global_load_lds_dwordx4 v132, s[26:27]
	s_mov_b32 m0, s11
	s_nop 0
	global_load_lds_dwordx4 v134, s[26:27]
	s_add_u32 s100, s26, 0x80
	s_addc_u32 s101, s27, 0
	s_waitcnt vmcnt(8)
	s_waitcnt lgkmcnt(0)
	s_setprio 1
	s_barrier
	v_mfma_f32_16x16x32_bf16 v[64:67], v[142:145], v[178:181], v[64:67]
	v_mfma_f32_16x16x32_bf16 v[60:63], v[154:157], v[178:181], v[60:63]
	v_mfma_f32_16x16x32_bf16 v[44:47], v[154:157], v[186:189], v[44:47]
	v_mfma_f32_16x16x32_bf16 v[48:51], v[142:145], v[186:189], v[48:51]
	v_mfma_f32_16x16x32_bf16 v[32:35], v[142:145], v[194:197], v[32:35]
	v_mfma_f32_16x16x32_bf16 v[28:31], v[154:157], v[194:197], v[28:31]
	v_mfma_f32_16x16x32_bf16 v[12:15], v[154:157], v[202:205], v[12:15]
	v_mfma_f32_16x16x32_bf16 v[16:19], v[142:145], v[202:205], v[16:19]
	v_mfma_f32_16x16x32_bf16 v[64:67], v[150:153], v[182:185], v[64:67]
	v_mfma_f32_16x16x32_bf16 v[60:63], v[158:161], v[182:185], v[60:63]
	v_mfma_f32_16x16x32_bf16 v[44:47], v[158:161], v[190:193], v[44:47]
	v_mfma_f32_16x16x32_bf16 v[48:51], v[150:153], v[190:193], v[48:51]
	v_mfma_f32_16x16x32_bf16 v[32:35], v[150:153], v[198:201], v[32:35]
	v_mfma_f32_16x16x32_bf16 v[28:31], v[158:161], v[198:201], v[28:31]
	v_mfma_f32_16x16x32_bf16 v[12:15], v[158:161], v[206:209], v[12:15]
	v_mfma_f32_16x16x32_bf16 v[16:19], v[150:153], v[206:209], v[16:19]
	s_setprio 0
	s_setprio 1
	v_mfma_f32_16x16x32_bf16 v[56:59], v[162:165], v[178:181], v[56:59]
	v_mfma_f32_16x16x32_bf16 v[52:55], v[170:173], v[178:181], v[52:55]
	v_mfma_f32_16x16x32_bf16 v[36:39], v[170:173], v[186:189], v[36:39]
	v_mfma_f32_16x16x32_bf16 v[40:43], v[162:165], v[186:189], v[40:43]
	v_mfma_f32_16x16x32_bf16 v[24:27], v[162:165], v[194:197], v[24:27]
	v_mfma_f32_16x16x32_bf16 v[20:23], v[170:173], v[194:197], v[20:23]
	v_mfma_f32_16x16x32_bf16 v[4:7], v[170:173], v[202:205], v[4:7]
	v_mfma_f32_16x16x32_bf16 v[8:11], v[162:165], v[202:205], v[8:11]
	v_mfma_f32_16x16x32_bf16 v[56:59], v[166:169], v[182:185], v[56:59]
	v_mfma_f32_16x16x32_bf16 v[52:55], v[174:177], v[182:185], v[52:55]
	v_mfma_f32_16x16x32_bf16 v[36:39], v[174:177], v[190:193], v[36:39]
	v_mfma_f32_16x16x32_bf16 v[40:43], v[166:169], v[190:193], v[40:43]
	v_mfma_f32_16x16x32_bf16 v[24:27], v[166:169], v[198:201], v[24:27]
	v_mfma_f32_16x16x32_bf16 v[20:23], v[174:177], v[198:201], v[20:23]
	v_mfma_f32_16x16x32_bf16 v[4:7], v[174:177], v[206:209], v[4:7]
	v_mfma_f32_16x16x32_bf16 v[8:11], v[166:169], v[206:209], v[8:11]
	s_barrier
; #define PG8_STAGE(bufoff, gbase, voff) do { _Pragma("unroll") for (int _i = 0; _i < 2; ++_i) \
;         __builtin_amdgcn_global_load_lds((const unsigned*)((const char*)(gbase) + (voff)[_i]), (PG8_LAS unsigned*)(lds + (bufoff) + ldsw + _i * 8192), 16, 0, 0); } while (0)
; #define PG8_LDA(dst, b, h) do { _Pragma("unroll") for (int m = 0; m < 4; ++m) _Pragma("unroll") for (int k = 0; k < 2; ++k) dst[m][k] = *(const PG8_LAS bf16x8*)(lds + PG8_SA(b, h) + aoff + m * 2048 + k * 1024); } while (0)
; #define PG8_LDB(dst, b, h) do { _Pragma("unroll") for (int n = 0; n < 2; ++n) _Pragma("unroll") for (int k = 0; k < 2; ++k) dst[n][k] = *(const PG8_LAS bf16x8*)(lds + PG8_SB(b, h) + boff + n * 2048 + k * 1024); } while (0)
; #define PG8_MMA(ai, bj, At, Bt) do { __builtin_amdgcn_s_setprio(1); _Pragma("unroll") for (int m = 0; m < 4; ++m) _Pragma("unroll") for (int n = 0; n < 2; ++n) _Pragma("unroll") for (int k = 0; k < 2; ++k) \
;         acc[ai][bj][m][n] = __builtin_amdgcn_mfma_f32_16x16x32_bf16(Bt[n][k], At[m][k], acc[ai][bj][m][n], 0, 0, 0); __builtin_amdgcn_s_setprio(0); } while (0)
; #define PG8_WAIT_V(n) asm volatile("s_waitcnt vmcnt(" #n ")" ::: "memory")
; #define PG8_WAIT_L(n) asm volatile("s_waitcnt lgkmcnt(" #n ")" ::: "memory")
; #define PG8_BAR __builtin_amdgcn_s_barrier()
; #define PG8_SCHED __builtin_amdgcn_sched_barrier(0)
; template <class Epi, class Sched, bool ALIGN_EPI = false, bool SP2 = false>
; __device__ __forceinline__ void gemm_phase(PG8_LAS unsigned char* lds, const Gemm g, const Sched& S, const Epi& E) {
;     ...
;             PG8_LDB(B0, 1, 0); PG8_LDB(B1, 1, 1); PG8_SCHED; PG8_LDA(At, 1, 0); PG8_STAGE(PG8_SA(0, 1), a2 + hstep, voffA);
;             PG8_WAIT_V(8); PG8_WAIT_L(0); PG8_BAR; PG8_MMA(0, 0, At, B0); PG8_MMA(0, 1, At, B1); PG8_BAR; PG8_SCHED;
;             PG8_LDA(At, 1, 1); PG8_STAGE(PG8_SB(1, 0), b3, voffB); PG8_STAGE(PG8_SB(1, 1), b3 + hstep, voffB); PG8_STAGE(PG8_SA(1, 0), a3, voffA);
;             PG8_WAIT_V(8); PG8_WAIT_L(0); PG8_BAR; PG8_MMA(1, 0, At, B0); PG8_MMA(1, 1, At, B1); PG8_BAR; PG8_SCHED;
	s_setprio 0
	s_add_i32 s63, 0, 0x18000
	s_add_i32 s64, 0, 0x1c000
	ds_read_b128 v[142:145], v210 offset:32768
	ds_read_b128 v[150:153], v210 offset:33792
	ds_read_b128 v[154:157], v210 offset:34816
	ds_read_b128 v[158:161], v210 offset:35840
	ds_read_b128 v[162:165], v210 offset:49152
	ds_read_b128 v[166:169], v210 offset:50176
	ds_read_b128 v[170:173], v210 offset:51200
	ds_read_b128 v[174:177], v210 offset:52224
	s_add_u32 s26, s26, 0x20000
	s_addc_u32 s27, s27, 0
	s_mov_b32 m0, s25
	ds_read_b128 v[178:181], v149 offset:32768
	ds_read_b128 v[182:185], v149 offset:33792
	ds_read_b128 v[186:189], v149 offset:34816
	ds_read_b128 v[190:193], v149 offset:35840
	ds_read_b128 v[194:197], v149 offset:36864
	ds_read_b128 v[198:201], v149 offset:37888
	ds_read_b128 v[202:205], v149 offset:38912
	ds_read_b128 v[206:209], v149 offset:39936
	global_load_lds_dwordx4 v132, s[26:27]
	s_mov_b32 m0, s55
	s_nop 0
	global_load_lds_dwordx4 v134, s[26:27]
	s_waitcnt vmcnt(8)
	s_waitcnt lgkmcnt(0)
	s_setprio 1
	s_barrier
	v_mfma_f32_16x16x32_bf16 v[128:131], v[142:145], v[178:181], v[128:131]
	v_mfma_f32_16x16x32_bf16 v[124:127], v[154:157], v[178:181], v[124:127]
	v_mfma_f32_16x16x32_bf16 v[108:111], v[154:157], v[186:189], v[108:111]
	v_mfma_f32_16x16x32_bf16 v[112:115], v[142:145], v[186:189], v[112:115]
	v_mfma_f32_16x16x32_bf16 v[96:99], v[142:145], v[194:197], v[96:99]
	v_mfma_f32_16x16x32_bf16 v[92:95], v[154:157], v[194:197], v[92:95]
	v_mfma_f32_16x16x32_bf16 v[76:79], v[154:157], v[202:205], v[76:79]
	v_mfma_f32_16x16x32_bf16 v[80:83], v[142:145], v[202:205], v[80:83]
	v_mfma_f32_16x16x32_bf16 v[128:131], v[150:153], v[182:185], v[128:131]
	v_mfma_f32_16x16x32_bf16 v[124:127], v[158:161], v[182:185], v[124:127]
	v_mfma_f32_16x16x32_bf16 v[108:111], v[158:161], v[190:193], v[108:111]
	v_mfma_f32_16x16x32_bf16 v[112:115], v[150:153], v[190:193], v[112:115]
	v_mfma_f32_16x16x32_bf16 v[96:99], v[150:153], v[198:201], v[96:99]
	v_mfma_f32_16x16x32_bf16 v[92:95], v[158:161], v[198:201], v[92:95]
	v_mfma_f32_16x16x32_bf16 v[76:79], v[158:161], v[206:209], v[76:79]
	v_mfma_f32_16x16x32_bf16 v[80:83], v[150:153], v[206:209], v[80:83]
	s_setprio 0
	s_setprio 1
	v_mfma_f32_16x16x32_bf16 v[120:123], v[162:165], v[178:181], v[120:123]
	v_mfma_f32_16x16x32_bf16 v[116:119], v[170:173], v[178:181], v[116:119]
	v_mfma_f32_16x16x32_bf16 v[100:103], v[170:173], v[186:189], v[100:103]
	v_mfma_f32_16x16x32_bf16 v[104:107], v[162:165], v[186:189], v[104:107]
	v_mfma_f32_16x16x32_bf16 v[88:91], v[162:165], v[194:197], v[88:91]
	v_mfma_f32_16x16x32_bf16 v[84:87], v[170:173], v[194:197], v[84:87]
	v_mfma_f32_16x16x32_bf16 v[68:71], v[170:173], v[202:205], v[68:71]
	v_mfma_f32_16x16x32_bf16 v[72:75], v[162:165], v[202:205], v[72:75]
	v_mfma_f32_16x16x32_bf16 v[120:123], v[166:169], v[182:185], v[120:123]
	v_mfma_f32_16x16x32_bf16 v[116:119], v[174:177], v[182:185], v[116:119]
	v_mfma_f32_16x16x32_bf16 v[100:103], v[174:177], v[190:193], v[100:103]
	v_mfma_f32_16x16x32_bf16 v[104:107], v[166:169], v[190:193], v[104:107]
	v_mfma_f32_16x16x32_bf16 v[88:91], v[166:169], v[198:201], v[88:91]
	v_mfma_f32_16x16x32_bf16 v[84:87], v[174:177], v[198:201], v[84:87]
	v_mfma_f32_16x16x32_bf16 v[68:71], v[174:177], v[206:209], v[68:71]
	v_mfma_f32_16x16x32_bf16 v[72:75], v[166:169], v[206:209], v[72:75]
	s_barrier
	s_setprio 0
	s_add_i32 s26, s63, s9
	s_mov_b32 m0, s26
	ds_read_b128 v[178:181], v149 offset:49152
	ds_read_b128 v[182:185], v149 offset:50176
	ds_read_b128 v[186:189], v149 offset:51200
	ds_read_b128 v[190:193], v149 offset:52224
	ds_read_b128 v[194:197], v149 offset:53248
	ds_read_b128 v[198:201], v149 offset:54272
	ds_read_b128 v[202:205], v149 offset:55296
	ds_read_b128 v[206:209], v149 offset:56320
	s_add_u32 s0, s0, 0x80
	s_addc_u32 s1, s1, 0
	global_load_lds_dwordx4 v2, s[0:1]
	s_add_i32 m0, s26, 0x2000
	s_add_i32 s26, s64, s9
	global_load_lds_dwordx4 v136, s[0:1]
	s_add_u32 s0, s0, 0x20000
	s_addc_u32 s1, s1, 0
	s_mov_b32 m0, s26
	s_nop 0
	global_load_lds_dwordx4 v2, s[0:1]
	s_add_i32 m0, s26, 0x2000
	s_nop 0
	global_load_lds_dwordx4 v136, s[0:1]
	s_mov_b32 m0, s58
	s_nop 0
	global_load_lds_dwordx4 v132, s[100:101]
	s_mov_b32 m0, s59
	s_nop 0
	global_load_lds_dwordx4 v134, s[100:101]
	s_waitcnt vmcnt(8)
	s_waitcnt lgkmcnt(0)
	s_setprio 1
	s_barrier
	v_mfma_f32_16x16x32_bf16 v[64:67], v[142:145], v[178:181], v[64:67]
	v_mfma_f32_16x16x32_bf16 v[60:63], v[154:157], v[178:181], v[60:63]
	v_mfma_f32_16x16x32_bf16 v[44:47], v[154:157], v[186:189], v[44:47]
	v_mfma_f32_16x16x32_bf16 v[48:51], v[142:145], v[186:189], v[48:51]
	v_mfma_f32_16x16x32_bf16 v[32:35], v[142:145], v[194:197], v[32:35]
	v_mfma_f32_16x16x32_bf16 v[28:31], v[154:157], v[194:197], v[28:31]
	v_mfma_f32_16x16x32_bf16 v[12:15], v[154:157], v[202:205], v[12:15]
	v_mfma_f32_16x16x32_bf16 v[16:19], v[142:145], v[202:205], v[16:19]
	v_mfma_f32_16x16x32_bf16 v[64:67], v[150:153], v[182:185], v[64:67]
	v_mfma_f32_16x16x32_bf16 v[60:63], v[158:161], v[182:185], v[60:63]
	v_mfma_f32_16x16x32_bf16 v[44:47], v[158:161], v[190:193], v[44:47]
	v_mfma_f32_16x16x32_bf16 v[48:51], v[150:153], v[190:193], v[48:51]
	v_mfma_f32_16x16x32_bf16 v[32:35], v[150:153], v[198:201], v[32:35]
	v_mfma_f32_16x16x32_bf16 v[28:31], v[158:161], v[198:201], v[28:31]
	v_mfma_f32_16x16x32_bf16 v[12:15], v[158:161], v[206:209], v[12:15]
	v_mfma_f32_16x16x32_bf16 v[16:19], v[150:153], v[206:209], v[16:19]
	s_setprio 0
	s_setprio 1
	v_mfma_f32_16x16x32_bf16 v[56:59], v[162:165], v[178:181], v[56:59]
	v_mfma_f32_16x16x32_bf16 v[52:55], v[170:173], v[178:181], v[52:55]
	v_mfma_f32_16x16x32_bf16 v[36:39], v[170:173], v[186:189], v[36:39]
	v_mfma_f32_16x16x32_bf16 v[40:43], v[162:165], v[186:189], v[40:43]
	v_mfma_f32_16x16x32_bf16 v[24:27], v[162:165], v[194:197], v[24:27]
	v_mfma_f32_16x16x32_bf16 v[20:23], v[170:173], v[194:197], v[20:23]
	v_mfma_f32_16x16x32_bf16 v[4:7], v[170:173], v[202:205], v[4:7]
	v_mfma_f32_16x16x32_bf16 v[8:11], v[162:165], v[202:205], v[8:11]
	v_mfma_f32_16x16x32_bf16 v[56:59], v[166:169], v[182:185], v[56:59]
	v_mfma_f32_16x16x32_bf16 v[52:55], v[174:177], v[182:185], v[52:55]
	v_mfma_f32_16x16x32_bf16 v[36:39], v[174:177], v[190:193], v[36:39]
	v_mfma_f32_16x16x32_bf16 v[40:43], v[166:169], v[190:193], v[40:43]
	v_mfma_f32_16x16x32_bf16 v[24:27], v[166:169], v[198:201], v[24:27]
	v_mfma_f32_16x16x32_bf16 v[20:23], v[174:177], v[198:201], v[20:23]
	v_mfma_f32_16x16x32_bf16 v[4:7], v[174:177], v[206:209], v[4:7]
	v_mfma_f32_16x16x32_bf16 v[8:11], v[166:169], v[206:209], v[8:11]
	s_barrier
	s_setprio 0
	s_add_i32 s62, s62, 2
	s_add_u32 s56, s56, 0x100
	s_addc_u32 s57, s57, 0
	s_add_u32 s47, s47, 0x100
	s_addc_u32 s49, s49, 0
	s_cmp_gt_u32 s62, 5
	s_cbranch_scc0 .LBB0_2692
	s_and_b64 vcc, exec, s[44:45]
	s_cbranch_vccz .LBB0_2695
	s_barrier

; #define PG8_STAGE(bufoff, gbase, voff) do { _Pragma("unroll") for (int _i = 0; _i < 2; ++_i) \
;         __builtin_amdgcn_global_load_lds((const unsigned*)((const char*)(gbase) + (voff)[_i]), (PG8_LAS unsigned*)(lds + (bufoff) + ldsw + _i * 8192), 16, 0, 0); } while (0)
; #define PG8_LDA(dst, b, h) do { _Pragma("unroll") for (int m = 0; m < 4; ++m) _Pragma("unroll") for (int k = 0; k < 2; ++k) dst[m][k] = *(const PG8_LAS bf16x8*)(lds + PG8_SA(b, h) + aoff + m * 2048 + k * 1024); } while (0)
; #define PG8_LDB(dst, b, h) do { _Pragma("unroll") for (int n = 0; n < 2; ++n) _Pragma("unroll") for (int k = 0; k < 2; ++k) dst[n][k] = *(const PG8_LAS bf16x8*)(lds + PG8_SB(b, h) + boff + n * 2048 + k * 1024); } while (0)
; #define PG8_MMA(ai, bj, At, Bt) do { __builtin_amdgcn_s_setprio(1); _Pragma("unroll") for (int m = 0; m < 4; ++m) _Pragma("unroll") for (int n = 0; n < 2; ++n) _Pragma("unroll") for (int k = 0; k < 2; ++k) \
;         acc[ai][bj][m][n] = __builtin_amdgcn_mfma_f32_16x16x32_bf16(Bt[n][k], At[m][k], acc[ai][bj][m][n], 0, 0, 0); __builtin_amdgcn_s_setprio(0); } while (0)
; #define PG8_WAIT_V(n) asm volatile("s_waitcnt vmcnt(" #n ")" ::: "memory")
; #define PG8_WAIT_L(n) asm volatile("s_waitcnt lgkmcnt(" #n ")" ::: "memory")
; template <class Epi, class Sched, bool ALIGN_EPI = false, bool SP2 = false>
; __device__ __forceinline__ void gemm_phase(PG8_LAS unsigned char* lds, const Gemm g, const Sched& S, const Epi& E) {
;     ...
;             const bool last = (t == nt - 2);
;             const char* a1 = cA + (size_t)(t + 1) * kstep;
;             const char* a2 = last ? nA : cA + (size_t)(t + 2) * kstep; const char* b2 = last ? nB : cB + (size_t)(t + 2) * kstep;
;             const char* a3 = a2 + kstep; const char* b3 = b2 + kstep;
;             if (last && has_next) S.a_ready(nxt);
;             if constexpr (SP2) {
;             PG8_LDB(B0, 0, 0); PG8_LDB(B1, 0, 1); PG8_SCHED; PG8_LDA(At, 0, 0); PG8_STAGE(PG8_SA(1, 1), a1 + hstep, voffA);
;             PG8_WAIT_V(8); PG8_WAIT_L(0); PG8_BAR; PG8_MMA(0, 0, At, B0); PG8_MMA(0, 1, At, B1); PG8_BAR; PG8_SCHED;
;             PG8_LDA(At, 0, 1); PG8_STAGE(PG8_SB(0, 0), b2, voffB); PG8_STAGE(PG8_SB(0, 1), b2 + hstep, voffB); PG8_STAGE(PG8_SA(0, 0), a2, voffA);
;             PG8_WAIT_V(8); PG8_WAIT_L(0); PG8_BAR; PG8_MMA(1, 0, At, B0); PG8_MMA(1, 1, At, B1); PG8_BAR; PG8_SCHED;
.LBB0_3159:
	s_add_u32 s0, s24, 0xfff00080
	s_addc_u32 s1, s25, -1
	s_add_i32 s65, 0, 0x10000
	s_cmp_eq_u32 s64, 60
	s_cselect_b32 s27, s51, s1
	s_cselect_b32 s26, s60, s0
	s_cselect_b32 s1, s49, s63
	s_cselect_b32 s0, s61, s62
	s_add_i32 s70, 0, 0x14000
	ds_read_b128 v[142:145], v146
	ds_read_b128 v[152:155], v146 offset:1024
	ds_read_b128 v[156:159], v146 offset:2048
	ds_read_b128 v[160:163], v146 offset:3072
	ds_read_b128 v[164:167], v146 offset:16384
	ds_read_b128 v[168:171], v146 offset:17408
	ds_read_b128 v[172:175], v146 offset:18432
	ds_read_b128 v[176:179], v146 offset:19456
	s_add_i32 m0, s34, 0xc000
	ds_read_b128 v[180:183], v151
	ds_read_b128 v[184:187], v151 offset:1024
	ds_read_b128 v[188:191], v151 offset:2048
	ds_read_b128 v[192:195], v151 offset:3072
	ds_read_b128 v[196:199], v151 offset:4096
	ds_read_b128 v[200:203], v151 offset:5120
	ds_read_b128 v[204:207], v151 offset:6144
	ds_read_b128 v[208:211], v151 offset:7168
	global_load_lds_dwordx4 v138, s[24:25]
	s_add_i32 m0, s34, 0xe000
	s_nop 0
	global_load_lds_dwordx4 v140, s[24:25]
	s_waitcnt vmcnt(8)
	s_waitcnt lgkmcnt(0)
	s_setprio 1
	s_barrier
	v_mfma_f32_16x16x32_bf16 v[128:131], v[142:145], v[180:183], v[128:131]
	v_mfma_f32_16x16x32_bf16 v[124:127], v[156:159], v[180:183], v[124:127]
	v_mfma_f32_16x16x32_bf16 v[108:111], v[156:159], v[188:191], v[108:111]
	v_mfma_f32_16x16x32_bf16 v[112:115], v[142:145], v[188:191], v[112:115]
	v_mfma_f32_16x16x32_bf16 v[96:99], v[142:145], v[196:199], v[96:99]
	v_mfma_f32_16x16x32_bf16 v[92:95], v[156:159], v[196:199], v[92:95]
	v_mfma_f32_16x16x32_bf16 v[76:79], v[156:159], v[204:207], v[76:79]
	v_mfma_f32_16x16x32_bf16 v[80:83], v[142:145], v[204:207], v[80:83]
	v_mfma_f32_16x16x32_bf16 v[128:131], v[152:155], v[184:187], v[128:131]
	v_mfma_f32_16x16x32_bf16 v[124:127], v[160:163], v[184:187], v[124:127]
	v_mfma_f32_16x16x32_bf16 v[108:111], v[160:163], v[192:195], v[108:111]
	v_mfma_f32_16x16x32_bf16 v[112:115], v[152:155], v[192:195], v[112:115]
	v_mfma_f32_16x16x32_bf16 v[96:99], v[152:155], v[200:203], v[96:99]
	v_mfma_f32_16x16x32_bf16 v[92:95], v[160:163], v[200:203], v[92:95]
	v_mfma_f32_16x16x32_bf16 v[76:79], v[160:163], v[208:211], v[76:79]
	v_mfma_f32_16x16x32_bf16 v[80:83], v[152:155], v[208:211], v[80:83]
	s_setprio 0
	s_setprio 1
	v_mfma_f32_16x16x32_bf16 v[120:123], v[164:167], v[180:183], v[120:123]
	v_mfma_f32_16x16x32_bf16 v[116:119], v[172:175], v[180:183], v[116:119]
	v_mfma_f32_16x16x32_bf16 v[100:103], v[172:175], v[188:191], v[100:103]
	v_mfma_f32_16x16x32_bf16 v[104:107], v[164:167], v[188:191], v[104:107]
	v_mfma_f32_16x16x32_bf16 v[88:91], v[164:167], v[196:199], v[88:91]
	v_mfma_f32_16x16x32_bf16 v[84:87], v[172:175], v[196:199], v[84:87]
	v_mfma_f32_16x16x32_bf16 v[68:71], v[172:175], v[204:207], v[68:71]
	v_mfma_f32_16x16x32_bf16 v[72:75], v[164:167], v[204:207], v[72:75]
	v_mfma_f32_16x16x32_bf16 v[120:123], v[168:171], v[184:187], v[120:123]
	v_mfma_f32_16x16x32_bf16 v[116:119], v[176:179], v[184:187], v[116:119]
	v_mfma_f32_16x16x32_bf16 v[100:103], v[176:179], v[192:195], v[100:103]
	v_mfma_f32_16x16x32_bf16 v[104:107], v[168:171], v[192:195], v[104:107]
	v_mfma_f32_16x16x32_bf16 v[88:91], v[168:171], v[200:203], v[88:91]
	v_mfma_f32_16x16x32_bf16 v[84:87], v[176:179], v[200:203], v[84:87]
	v_mfma_f32_16x16x32_bf16 v[68:71], v[176:179], v[208:211], v[68:71]
	v_mfma_f32_16x16x32_bf16 v[72:75], v[168:171], v[208:211], v[72:75]
	s_barrier
	s_setprio 0
	s_add_i32 s65, s65, s9
	s_mov_b32 m0, s65
	ds_read_b128 v[180:183], v151 offset:16384
	ds_read_b128 v[184:187], v151 offset:17408
	ds_read_b128 v[188:191], v151 offset:18432
	ds_read_b128 v[192:195], v151 offset:19456
	ds_read_b128 v[196:199], v151 offset:20480
	ds_read_b128 v[200:203], v151 offset:21504
	ds_read_b128 v[204:207], v151 offset:22528
	ds_read_b128 v[208:211], v151 offset:23552
	global_load_lds_dwordx4 v2, s[0:1]
	s_add_i32 m0, s65, 0x2000
	s_add_u32 s66, s0, 0x100000
	s_addc_u32 s67, s1, 0
	s_add_i32 s65, s70, s9
	global_load_lds_dwordx4 v132, s[0:1]
	s_mov_b32 m0, s65
	s_nop 0
	global_load_lds_dwordx4 v2, s[66:67]
	s_add_i32 m0, s65, 0x2000
	s_nop 0
	global_load_lds_dwordx4 v132, s[66:67]
	s_mov_b32 m0, s34
	s_nop 0
	global_load_lds_dwordx4 v136, s[26:27]
	s_mov_b32 m0, s35
	s_nop 0
	global_load_lds_dwordx4 v134, s[26:27]
	s_add_u32 s100, s26, 0x80
	s_addc_u32 s101, s27, 0
	s_waitcnt vmcnt(8)
	s_waitcnt lgkmcnt(0)
	s_setprio 1
	s_barrier
	v_mfma_f32_16x16x32_bf16 v[64:67], v[142:145], v[180:183], v[64:67]
	v_mfma_f32_16x16x32_bf16 v[60:63], v[156:159], v[180:183], v[60:63]
	v_mfma_f32_16x16x32_bf16 v[44:47], v[156:159], v[188:191], v[44:47]
	v_mfma_f32_16x16x32_bf16 v[48:51], v[142:145], v[188:191], v[48:51]
	v_mfma_f32_16x16x32_bf16 v[32:35], v[142:145], v[196:199], v[32:35]
	v_mfma_f32_16x16x32_bf16 v[28:31], v[156:159], v[196:199], v[28:31]
	v_mfma_f32_16x16x32_bf16 v[12:15], v[156:159], v[204:207], v[12:15]
	v_mfma_f32_16x16x32_bf16 v[16:19], v[142:145], v[204:207], v[16:19]
	v_mfma_f32_16x16x32_bf16 v[64:67], v[152:155], v[184:187], v[64:67]
	v_mfma_f32_16x16x32_bf16 v[60:63], v[160:163], v[184:187], v[60:63]
	v_mfma_f32_16x16x32_bf16 v[44:47], v[160:163], v[192:195], v[44:47]
	v_mfma_f32_16x16x32_bf16 v[48:51], v[152:155], v[192:195], v[48:51]
	v_mfma_f32_16x16x32_bf16 v[32:35], v[152:155], v[200:203], v[32:35]
	v_mfma_f32_16x16x32_bf16 v[28:31], v[160:163], v[200:203], v[28:31]
	v_mfma_f32_16x16x32_bf16 v[12:15], v[160:163], v[208:211], v[12:15]
	v_mfma_f32_16x16x32_bf16 v[16:19], v[152:155], v[208:211], v[16:19]
	s_setprio 0
	s_setprio 1
	v_mfma_f32_16x16x32_bf16 v[56:59], v[164:167], v[180:183], v[56:59]
	v_mfma_f32_16x16x32_bf16 v[52:55], v[172:175], v[180:183], v[52:55]
	v_mfma_f32_16x16x32_bf16 v[36:39], v[172:175], v[188:191], v[36:39]
	v_mfma_f32_16x16x32_bf16 v[40:43], v[164:167], v[188:191], v[40:43]
	v_mfma_f32_16x16x32_bf16 v[24:27], v[164:167], v[196:199], v[24:27]
	v_mfma_f32_16x16x32_bf16 v[20:23], v[172:175], v[196:199], v[20:23]
	v_mfma_f32_16x16x32_bf16 v[4:7], v[172:175], v[204:207], v[4:7]
	v_mfma_f32_16x16x32_bf16 v[8:11], v[164:167], v[204:207], v[8:11]
	v_mfma_f32_16x16x32_bf16 v[56:59], v[168:171], v[184:187], v[56:59]
	v_mfma_f32_16x16x32_bf16 v[52:55], v[176:179], v[184:187], v[52:55]
	v_mfma_f32_16x16x32_bf16 v[36:39], v[176:179], v[192:195], v[36:39]
	v_mfma_f32_16x16x32_bf16 v[40:43], v[168:171], v[192:195], v[40:43]
	v_mfma_f32_16x16x32_bf16 v[24:27], v[168:171], v[200:203], v[24:27]
	v_mfma_f32_16x16x32_bf16 v[20:23], v[176:179], v[200:203], v[20:23]
	v_mfma_f32_16x16x32_bf16 v[4:7], v[176:179], v[208:211], v[4:7]
	v_mfma_f32_16x16x32_bf16 v[8:11], v[168:171], v[208:211], v[8:11]
	s_barrier
; #define PG8_STAGE(bufoff, gbase, voff) do { _Pragma("unroll") for (int _i = 0; _i < 2; ++_i) \
;         __builtin_amdgcn_global_load_lds((const unsigned*)((const char*)(gbase) + (voff)[_i]), (PG8_LAS unsigned*)(lds + (bufoff) + ldsw + _i * 8192), 16, 0, 0); } while (0)
; #define PG8_LDA(dst, b, h) do { _Pragma("unroll") for (int m = 0; m < 4; ++m) _Pragma("unroll") for (int k = 0; k < 2; ++k) dst[m][k] = *(const PG8_LAS bf16x8*)(lds + PG8_SA(b, h) + aoff + m * 2048 + k * 1024); } while (0)
; #define PG8_LDB(dst, b, h) do { _Pragma("unroll") for (int n = 0; n < 2; ++n) _Pragma("unroll") for (int k = 0; k < 2; ++k) dst[n][k] = *(const PG8_LAS bf16x8*)(lds + PG8_SB(b, h) + boff + n * 2048 + k * 1024); } while (0)
; #define PG8_MMA(ai, bj, At, Bt) do { __builtin_amdgcn_s_setprio(1); _Pragma("unroll") for (int m = 0; m < 4; ++m) _Pragma("unroll") for (int n = 0; n < 2; ++n) _Pragma("unroll") for (int k = 0; k < 2; ++k) \
;         acc[ai][bj][m][n] = __builtin_amdgcn_mfma_f32_16x16x32_bf16(Bt[n][k], At[m][k], acc[ai][bj][m][n], 0, 0, 0); __builtin_amdgcn_s_setprio(0); } while (0)
; #define PG8_WAIT_V(n) asm volatile("s_waitcnt vmcnt(" #n ")" ::: "memory")
; #define PG8_WAIT_L(n) asm volatile("s_waitcnt lgkmcnt(" #n ")" ::: "memory")
; #define PG8_BAR __builtin_amdgcn_s_barrier()
; #define PG8_SCHED __builtin_amdgcn_sched_barrier(0)
; template <class Epi, class Sched, bool ALIGN_EPI = false, bool SP2 = false>
; __device__ __forceinline__ void gemm_phase(PG8_LAS unsigned char* lds, const Gemm g, const Sched& S, const Epi& E) {
;     ...
;             PG8_LDB(B0, 1, 0); PG8_LDB(B1, 1, 1); PG8_SCHED; PG8_LDA(At, 1, 0); PG8_STAGE(PG8_SA(0, 1), a2 + hstep, voffA);
;             PG8_WAIT_V(8); PG8_WAIT_L(0); PG8_BAR; PG8_MMA(0, 0, At, B0); PG8_MMA(0, 1, At, B1); PG8_BAR; PG8_SCHED;
;             PG8_LDA(At, 1, 1); PG8_STAGE(PG8_SB(1, 0), b3, voffB); PG8_STAGE(PG8_SB(1, 1), b3 + hstep, voffB); PG8_STAGE(PG8_SA(1, 0), a3, voffA);
;             PG8_WAIT_V(8); PG8_WAIT_L(0); PG8_BAR; PG8_MMA(1, 0, At, B0); PG8_MMA(1, 1, At, B1); PG8_BAR; PG8_SCHED;
;     ...
;         if constexpr (ALIGN_EPI) { if (wr == 0) PG8_BAR; }
	s_setprio 0
	s_add_i32 s65, 0, 0x18000
	s_add_i32 s66, 0, 0x1c000
	ds_read_b128 v[142:145], v146 offset:32768
	ds_read_b128 v[152:155], v146 offset:33792
	ds_read_b128 v[156:159], v146 offset:34816
	ds_read_b128 v[160:163], v146 offset:35840
	ds_read_b128 v[164:167], v146 offset:49152
	ds_read_b128 v[168:171], v146 offset:50176
	ds_read_b128 v[172:175], v146 offset:51200
	ds_read_b128 v[176:179], v146 offset:52224
	s_add_u32 s26, s26, 0x100000
	s_addc_u32 s27, s27, 0
	s_mov_b32 m0, s54
	ds_read_b128 v[180:183], v151 offset:32768
	ds_read_b128 v[184:187], v151 offset:33792
	ds_read_b128 v[188:191], v151 offset:34816
	ds_read_b128 v[192:195], v151 offset:35840
	ds_read_b128 v[196:199], v151 offset:36864
	ds_read_b128 v[200:203], v151 offset:37888
	ds_read_b128 v[204:207], v151 offset:38912
	ds_read_b128 v[208:211], v151 offset:39936
	global_load_lds_dwordx4 v136, s[26:27]
	s_mov_b32 m0, s55
	s_nop 0
	global_load_lds_dwordx4 v134, s[26:27]
	s_waitcnt vmcnt(8)
	s_waitcnt lgkmcnt(0)
	s_setprio 1
	s_barrier
	v_mfma_f32_16x16x32_bf16 v[128:131], v[142:145], v[180:183], v[128:131]
	v_mfma_f32_16x16x32_bf16 v[124:127], v[156:159], v[180:183], v[124:127]
	v_mfma_f32_16x16x32_bf16 v[108:111], v[156:159], v[188:191], v[108:111]
	v_mfma_f32_16x16x32_bf16 v[112:115], v[142:145], v[188:191], v[112:115]
	v_mfma_f32_16x16x32_bf16 v[96:99], v[142:145], v[196:199], v[96:99]
	v_mfma_f32_16x16x32_bf16 v[92:95], v[156:159], v[196:199], v[92:95]
	v_mfma_f32_16x16x32_bf16 v[76:79], v[156:159], v[204:207], v[76:79]
	v_mfma_f32_16x16x32_bf16 v[80:83], v[142:145], v[204:207], v[80:83]
	v_mfma_f32_16x16x32_bf16 v[128:131], v[152:155], v[184:187], v[128:131]
	v_mfma_f32_16x16x32_bf16 v[124:127], v[160:163], v[184:187], v[124:127]
	v_mfma_f32_16x16x32_bf16 v[108:111], v[160:163], v[192:195], v[108:111]
	v_mfma_f32_16x16x32_bf16 v[112:115], v[152:155], v[192:195], v[112:115]
	v_mfma_f32_16x16x32_bf16 v[96:99], v[152:155], v[200:203], v[96:99]
	v_mfma_f32_16x16x32_bf16 v[92:95], v[160:163], v[200:203], v[92:95]
	v_mfma_f32_16x16x32_bf16 v[76:79], v[160:163], v[208:211], v[76:79]
	v_mfma_f32_16x16x32_bf16 v[80:83], v[152:155], v[208:211], v[80:83]
	s_setprio 0
	s_setprio 1
	v_mfma_f32_16x16x32_bf16 v[120:123], v[164:167], v[180:183], v[120:123]
	v_mfma_f32_16x16x32_bf16 v[116:119], v[172:175], v[180:183], v[116:119]
	v_mfma_f32_16x16x32_bf16 v[100:103], v[172:175], v[188:191], v[100:103]
	v_mfma_f32_16x16x32_bf16 v[104:107], v[164:167], v[188:191], v[104:107]
	v_mfma_f32_16x16x32_bf16 v[88:91], v[164:167], v[196:199], v[88:91]
	v_mfma_f32_16x16x32_bf16 v[84:87], v[172:175], v[196:199], v[84:87]
	v_mfma_f32_16x16x32_bf16 v[68:71], v[172:175], v[204:207], v[68:71]
	v_mfma_f32_16x16x32_bf16 v[72:75], v[164:167], v[204:207], v[72:75]
	v_mfma_f32_16x16x32_bf16 v[120:123], v[168:171], v[184:187], v[120:123]
	v_mfma_f32_16x16x32_bf16 v[116:119], v[176:179], v[184:187], v[116:119]
	v_mfma_f32_16x16x32_bf16 v[100:103], v[176:179], v[192:195], v[100:103]
	v_mfma_f32_16x16x32_bf16 v[104:107], v[168:171], v[192:195], v[104:107]
	v_mfma_f32_16x16x32_bf16 v[88:91], v[168:171], v[200:203], v[88:91]
	v_mfma_f32_16x16x32_bf16 v[84:87], v[176:179], v[200:203], v[84:87]
	v_mfma_f32_16x16x32_bf16 v[68:71], v[176:179], v[208:211], v[68:71]
	v_mfma_f32_16x16x32_bf16 v[72:75], v[168:171], v[208:211], v[72:75]
	s_barrier
	s_setprio 0
	s_add_i32 s26, s65, s9
	s_mov_b32 m0, s26
	ds_read_b128 v[180:183], v151 offset:49152
	ds_read_b128 v[184:187], v151 offset:50176
	ds_read_b128 v[188:191], v151 offset:51200
	ds_read_b128 v[192:195], v151 offset:52224
	ds_read_b128 v[196:199], v151 offset:53248
	ds_read_b128 v[200:203], v151 offset:54272
	ds_read_b128 v[204:207], v151 offset:55296
	ds_read_b128 v[208:211], v151 offset:56320
	s_add_u32 s0, s0, 0x80
	s_addc_u32 s1, s1, 0
	global_load_lds_dwordx4 v2, s[0:1]
	s_add_i32 m0, s26, 0x2000
	s_add_i32 s26, s66, s9
	global_load_lds_dwordx4 v132, s[0:1]
	s_add_u32 s0, s0, 0x100000
	s_addc_u32 s1, s1, 0
	s_mov_b32 m0, s26
	s_nop 0
	global_load_lds_dwordx4 v2, s[0:1]
	s_add_i32 m0, s26, 0x2000
	s_nop 0
	global_load_lds_dwordx4 v132, s[0:1]
	s_mov_b32 m0, s56
	s_nop 0
	global_load_lds_dwordx4 v136, s[100:101]
	s_mov_b32 m0, s57
	s_nop 0
	global_load_lds_dwordx4 v134, s[100:101]
	s_waitcnt vmcnt(8)
	s_waitcnt lgkmcnt(0)
	s_setprio 1
	s_barrier
	v_mfma_f32_16x16x32_bf16 v[64:67], v[142:145], v[180:183], v[64:67]
	v_mfma_f32_16x16x32_bf16 v[60:63], v[156:159], v[180:183], v[60:63]
	v_mfma_f32_16x16x32_bf16 v[44:47], v[156:159], v[188:191], v[44:47]
	v_mfma_f32_16x16x32_bf16 v[48:51], v[142:145], v[188:191], v[48:51]
	v_mfma_f32_16x16x32_bf16 v[32:35], v[142:145], v[196:199], v[32:35]
	v_mfma_f32_16x16x32_bf16 v[28:31], v[156:159], v[196:199], v[28:31]
	v_mfma_f32_16x16x32_bf16 v[12:15], v[156:159], v[204:207], v[12:15]
	v_mfma_f32_16x16x32_bf16 v[16:19], v[142:145], v[204:207], v[16:19]
	v_mfma_f32_16x16x32_bf16 v[64:67], v[152:155], v[184:187], v[64:67]
	v_mfma_f32_16x16x32_bf16 v[60:63], v[160:163], v[184:187], v[60:63]
	v_mfma_f32_16x16x32_bf16 v[44:47], v[160:163], v[192:195], v[44:47]
	v_mfma_f32_16x16x32_bf16 v[48:51], v[152:155], v[192:195], v[48:51]
	v_mfma_f32_16x16x32_bf16 v[32:35], v[152:155], v[200:203], v[32:35]
	v_mfma_f32_16x16x32_bf16 v[28:31], v[160:163], v[200:203], v[28:31]
	v_mfma_f32_16x16x32_bf16 v[12:15], v[160:163], v[208:211], v[12:15]
	v_mfma_f32_16x16x32_bf16 v[16:19], v[152:155], v[208:211], v[16:19]
	s_setprio 0
	s_setprio 1
	v_mfma_f32_16x16x32_bf16 v[56:59], v[164:167], v[180:183], v[56:59]
	v_mfma_f32_16x16x32_bf16 v[52:55], v[172:175], v[180:183], v[52:55]
	v_mfma_f32_16x16x32_bf16 v[36:39], v[172:175], v[188:191], v[36:39]
	v_mfma_f32_16x16x32_bf16 v[40:43], v[164:167], v[188:191], v[40:43]
	v_mfma_f32_16x16x32_bf16 v[24:27], v[164:167], v[196:199], v[24:27]
	v_mfma_f32_16x16x32_bf16 v[20:23], v[172:175], v[196:199], v[20:23]
	v_mfma_f32_16x16x32_bf16 v[4:7], v[172:175], v[204:207], v[4:7]
	v_mfma_f32_16x16x32_bf16 v[8:11], v[164:167], v[204:207], v[8:11]
	v_mfma_f32_16x16x32_bf16 v[56:59], v[168:171], v[184:187], v[56:59]
	v_mfma_f32_16x16x32_bf16 v[52:55], v[176:179], v[184:187], v[52:55]
	v_mfma_f32_16x16x32_bf16 v[36:39], v[176:179], v[192:195], v[36:39]
	v_mfma_f32_16x16x32_bf16 v[40:43], v[168:171], v[192:195], v[40:43]
	v_mfma_f32_16x16x32_bf16 v[24:27], v[168:171], v[200:203], v[24:27]
	v_mfma_f32_16x16x32_bf16 v[20:23], v[176:179], v[200:203], v[20:23]
	v_mfma_f32_16x16x32_bf16 v[4:7], v[176:179], v[208:211], v[4:7]
	v_mfma_f32_16x16x32_bf16 v[8:11], v[168:171], v[208:211], v[8:11]
	s_barrier
	s_setprio 0
	s_add_i32 s64, s64, 2
	s_add_u32 s24, s24, 0x100
	s_addc_u32 s25, s25, 0
	s_add_u32 s62, s62, 0x100
	s_addc_u32 s63, s63, 0
	s_cmp_gt_u32 s64, 61
	s_cbranch_scc0 .LBB0_3159
	s_and_b64 vcc, exec, s[46:47]
	s_cbranch_vccz .LBB0_3162
	s_barrier

; #define PG8_STAGE(bufoff, gbase, voff) do { _Pragma("unroll") for (int _i = 0; _i < 2; ++_i) \
;         __builtin_amdgcn_global_load_lds((const unsigned*)((const char*)(gbase) + (voff)[_i]), (PG8_LAS unsigned*)(lds + (bufoff) + ldsw + _i * 8192), 16, 0, 0); } while (0)
; #define PG8_LDA(dst, b, h) do { _Pragma("unroll") for (int m = 0; m < 4; ++m) _Pragma("unroll") for (int k = 0; k < 2; ++k) dst[m][k] = *(const PG8_LAS bf16x8*)(lds + PG8_SA(b, h) + aoff + m * 2048 + k * 1024); } while (0)
; #define PG8_LDB(dst, b, h) do { _Pragma("unroll") for (int n = 0; n < 2; ++n) _Pragma("unroll") for (int k = 0; k < 2; ++k) dst[n][k] = *(const PG8_LAS bf16x8*)(lds + PG8_SB(b, h) + boff + n * 2048 + k * 1024); } while (0)
; #define PG8_MMA(ai, bj, At, Bt) do { __builtin_amdgcn_s_setprio(1); _Pragma("unroll") for (int m = 0; m < 4; ++m) _Pragma("unroll") for (int n = 0; n < 2; ++n) _Pragma("unroll") for (int k = 0; k < 2; ++k) \
;         acc[ai][bj][m][n] = __builtin_amdgcn_mfma_f32_16x16x32_bf16(Bt[n][k], At[m][k], acc[ai][bj][m][n], 0, 0, 0); __builtin_amdgcn_s_setprio(0); } while (0)
; #define PG8_WAIT_V(n) asm volatile("s_waitcnt vmcnt(" #n ")" ::: "memory")
; #define PG8_BAR __builtin_amdgcn_s_barrier()
; template <class Epi, class Sched, bool ALIGN_EPI = false, bool SP2 = false>
; __device__ __forceinline__ void gemm_phase(PG8_LAS unsigned char* lds, const Gemm g, const Sched& S, const Epi& E) {
;     ...
;         for (int t = 0; t < nt; t += 2) {
;             const bool last = (t == nt - 2);
;             const char* a1 = cA + (size_t)(t + 1) * kstep;
;             const char* a2 = last ? nA : cA + (size_t)(t + 2) * kstep; const char* b2 = last ? nB : cB + (size_t)(t + 2) * kstep;
;             const char* a3 = a2 + kstep; const char* b3 = b2 + kstep;
;             if (last && has_next) S.a_ready(nxt);
;             if constexpr (SP2) {
;             PG8_LDB(B0, 0, 0); PG8_LDB(B1, 0, 1); PG8_SCHED; PG8_LDA(At, 0, 0); PG8_STAGE(PG8_SA(1, 1), a1 + hstep, voffA);
;             PG8_WAIT_V(8); PG8_WAIT_L(0); PG8_BAR; PG8_MMA(0, 0, At, B0); PG8_MMA(0, 1, At, B1); PG8_BAR; PG8_SCHED;
;             PG8_LDA(At, 0, 1); PG8_STAGE(PG8_SB(0, 0), b2, voffB); PG8_STAGE(PG8_SB(0, 1), b2 + hstep, voffB); PG8_STAGE(PG8_SA(0, 0), a2, voffA);
;             PG8_WAIT_V(8); PG8_WAIT_L(0); PG8_BAR; PG8_MMA(1, 0, At, B0); PG8_MMA(1, 1, At, B1); PG8_BAR; PG8_SCHED;
.LBB0_3627:
	s_add_i32 s72, s26, 2
	s_add_u32 s0, s24, 0x100
	s_addc_u32 s1, s25, 0
	s_add_i32 s73, 0, 0x10000
	s_cmp_eq_u32 s44, s26
	s_cselect_b32 s35, s79, s1
	s_cselect_b32 s34, s78, s0
	s_cselect_b32 s27, s81, s47
	s_cselect_b32 s26, s80, s45
	s_add_i32 vcc_lo, 0, 0x14000
	s_waitcnt lgkmcnt(0)
	ds_read_b128 v[132:135], v162
	ds_read_b128 v[136:139], v162 offset:1024
	ds_read_b128 v[140:143], v162 offset:2048
	ds_read_b128 v[154:157], v162 offset:3072
	ds_read_b128 v[158:161], v162 offset:16384
	ds_read_b128 v[170:173], v162 offset:17408
	ds_read_b128 v[174:177], v162 offset:18432
	ds_read_b128 v[178:181], v162 offset:19456
	s_add_i32 m0, s92, 0xc000
	ds_read_b128 v[182:185], v169
	ds_read_b128 v[186:189], v169 offset:1024
	ds_read_b128 v[190:193], v169 offset:2048
	ds_read_b128 v[194:197], v169 offset:3072
	ds_read_b128 v[198:201], v169 offset:4096
	ds_read_b128 v[202:205], v169 offset:5120
	ds_read_b128 v[206:209], v169 offset:6144
	ds_read_b128 v[210:213], v169 offset:7168
	global_load_lds_dwordx4 v150, s[24:25]
	s_add_i32 m0, s92, 0xe000
	s_nop 0
	global_load_lds_dwordx4 v152, s[24:25]
	s_waitcnt vmcnt(8)
	s_waitcnt lgkmcnt(0)
	s_setprio 1
	s_barrier
	v_mfma_f32_16x16x32_bf16 v[128:131], v[132:135], v[182:185], v[128:131]
	v_mfma_f32_16x16x32_bf16 v[124:127], v[140:143], v[182:185], v[124:127]
	v_mfma_f32_16x16x32_bf16 v[116:119], v[140:143], v[190:193], v[116:119]
	v_mfma_f32_16x16x32_bf16 v[120:123], v[132:135], v[190:193], v[120:123]
	v_mfma_f32_16x16x32_bf16 v[112:115], v[132:135], v[198:201], v[112:115]
	v_mfma_f32_16x16x32_bf16 v[108:111], v[140:143], v[198:201], v[108:111]
	v_mfma_f32_16x16x32_bf16 v[100:103], v[140:143], v[206:209], v[100:103]
	v_mfma_f32_16x16x32_bf16 v[104:107], v[132:135], v[206:209], v[104:107]
	v_mfma_f32_16x16x32_bf16 v[128:131], v[136:139], v[186:189], v[128:131]
	v_mfma_f32_16x16x32_bf16 v[124:127], v[154:157], v[186:189], v[124:127]
	v_mfma_f32_16x16x32_bf16 v[116:119], v[154:157], v[194:197], v[116:119]
	v_mfma_f32_16x16x32_bf16 v[120:123], v[136:139], v[194:197], v[120:123]
	v_mfma_f32_16x16x32_bf16 v[112:115], v[136:139], v[202:205], v[112:115]
	v_mfma_f32_16x16x32_bf16 v[108:111], v[154:157], v[202:205], v[108:111]
	v_mfma_f32_16x16x32_bf16 v[100:103], v[154:157], v[210:213], v[100:103]
	v_mfma_f32_16x16x32_bf16 v[104:107], v[136:139], v[210:213], v[104:107]
	s_setprio 0
	s_setprio 1
	v_mfma_f32_16x16x32_bf16 v[96:99], v[158:161], v[182:185], v[96:99]
	v_mfma_f32_16x16x32_bf16 v[92:95], v[174:177], v[182:185], v[92:95]
	v_mfma_f32_16x16x32_bf16 v[84:87], v[174:177], v[190:193], v[84:87]
	v_mfma_f32_16x16x32_bf16 v[88:91], v[158:161], v[190:193], v[88:91]
	v_mfma_f32_16x16x32_bf16 v[80:83], v[158:161], v[198:201], v[80:83]
	v_mfma_f32_16x16x32_bf16 v[76:79], v[174:177], v[198:201], v[76:79]
	v_mfma_f32_16x16x32_bf16 v[68:71], v[174:177], v[206:209], v[68:71]
	v_mfma_f32_16x16x32_bf16 v[72:75], v[158:161], v[206:209], v[72:75]
	v_mfma_f32_16x16x32_bf16 v[96:99], v[170:173], v[186:189], v[96:99]
	v_mfma_f32_16x16x32_bf16 v[92:95], v[178:181], v[186:189], v[92:95]
	v_mfma_f32_16x16x32_bf16 v[84:87], v[178:181], v[194:197], v[84:87]
	v_mfma_f32_16x16x32_bf16 v[88:91], v[170:173], v[194:197], v[88:91]
	v_mfma_f32_16x16x32_bf16 v[80:83], v[170:173], v[202:205], v[80:83]
	v_mfma_f32_16x16x32_bf16 v[76:79], v[178:181], v[202:205], v[76:79]
	v_mfma_f32_16x16x32_bf16 v[68:71], v[178:181], v[210:213], v[68:71]
	v_mfma_f32_16x16x32_bf16 v[72:75], v[170:173], v[210:213], v[72:75]
	s_barrier
	s_setprio 0
	s_add_i32 s24, s73, s83
	s_mov_b32 m0, s24
	ds_read_b128 v[182:185], v169 offset:16384
	ds_read_b128 v[186:189], v169 offset:17408
	ds_read_b128 v[190:193], v169 offset:18432
	ds_read_b128 v[194:197], v169 offset:19456
	ds_read_b128 v[198:201], v169 offset:20480
	ds_read_b128 v[202:205], v169 offset:21504
	ds_read_b128 v[206:209], v169 offset:22528
	ds_read_b128 v[210:213], v169 offset:23552
	global_load_lds_dwordx4 v2, s[26:27]
	s_add_i32 m0, s24, 0x2000
	s_add_u32 s24, s26, 0x2b0000
	s_addc_u32 s25, s27, 0
	s_add_i32 s73, vcc_lo, s83
	global_load_lds_dwordx4 v148, s[26:27]
	s_mov_b32 m0, s73
	s_nop 0
	global_load_lds_dwordx4 v2, s[24:25]
	s_add_i32 m0, s73, 0x2000
	s_nop 0
	global_load_lds_dwordx4 v148, s[24:25]
	s_mov_b32 m0, s92
	s_nop 0
	global_load_lds_dwordx4 v144, s[34:35]
	s_mov_b32 m0, s93
	s_nop 0
	global_load_lds_dwordx4 v146, s[34:35]
	s_waitcnt vmcnt(8)
	s_waitcnt lgkmcnt(0)
	s_setprio 1
	s_barrier
	v_mfma_f32_16x16x32_bf16 v[64:67], v[132:135], v[182:185], v[64:67]
	v_mfma_f32_16x16x32_bf16 v[60:63], v[140:143], v[182:185], v[60:63]
	v_mfma_f32_16x16x32_bf16 v[52:55], v[140:143], v[190:193], v[52:55]
	v_mfma_f32_16x16x32_bf16 v[56:59], v[132:135], v[190:193], v[56:59]
	v_mfma_f32_16x16x32_bf16 v[48:51], v[132:135], v[198:201], v[48:51]
	v_mfma_f32_16x16x32_bf16 v[44:47], v[140:143], v[198:201], v[44:47]
	v_mfma_f32_16x16x32_bf16 v[36:39], v[140:143], v[206:209], v[36:39]
	v_mfma_f32_16x16x32_bf16 v[40:43], v[132:135], v[206:209], v[40:43]
	v_mfma_f32_16x16x32_bf16 v[64:67], v[136:139], v[186:189], v[64:67]
	v_mfma_f32_16x16x32_bf16 v[60:63], v[154:157], v[186:189], v[60:63]
	v_mfma_f32_16x16x32_bf16 v[52:55], v[154:157], v[194:197], v[52:55]
	v_mfma_f32_16x16x32_bf16 v[56:59], v[136:139], v[194:197], v[56:59]
	v_mfma_f32_16x16x32_bf16 v[48:51], v[136:139], v[202:205], v[48:51]
	v_mfma_f32_16x16x32_bf16 v[44:47], v[154:157], v[202:205], v[44:47]
	v_mfma_f32_16x16x32_bf16 v[36:39], v[154:157], v[210:213], v[36:39]
	v_mfma_f32_16x16x32_bf16 v[40:43], v[136:139], v[210:213], v[40:43]
	s_setprio 0
	s_setprio 1
	v_mfma_f32_16x16x32_bf16 v[32:35], v[158:161], v[182:185], v[32:35]
	v_mfma_f32_16x16x32_bf16 v[28:31], v[174:177], v[182:185], v[28:31]
	v_mfma_f32_16x16x32_bf16 v[20:23], v[174:177], v[190:193], v[20:23]
	v_mfma_f32_16x16x32_bf16 v[24:27], v[158:161], v[190:193], v[24:27]
	v_mfma_f32_16x16x32_bf16 v[16:19], v[158:161], v[198:201], v[16:19]
	v_mfma_f32_16x16x32_bf16 v[12:15], v[174:177], v[198:201], v[12:15]
	v_mfma_f32_16x16x32_bf16 v[4:7], v[174:177], v[206:209], v[4:7]
	v_mfma_f32_16x16x32_bf16 v[8:11], v[158:161], v[206:209], v[8:11]
	v_mfma_f32_16x16x32_bf16 v[32:35], v[170:173], v[186:189], v[32:35]
	v_mfma_f32_16x16x32_bf16 v[28:31], v[178:181], v[186:189], v[28:31]
	v_mfma_f32_16x16x32_bf16 v[20:23], v[178:181], v[194:197], v[20:23]
	v_mfma_f32_16x16x32_bf16 v[24:27], v[170:173], v[194:197], v[24:27]
	v_mfma_f32_16x16x32_bf16 v[16:19], v[170:173], v[202:205], v[16:19]
	v_mfma_f32_16x16x32_bf16 v[12:15], v[178:181], v[202:205], v[12:15]
	v_mfma_f32_16x16x32_bf16 v[4:7], v[178:181], v[210:213], v[4:7]
	v_mfma_f32_16x16x32_bf16 v[8:11], v[170:173], v[210:213], v[8:11]
	s_barrier
; #define PG8_STAGE(bufoff, gbase, voff) do { _Pragma("unroll") for (int _i = 0; _i < 2; ++_i) \
;         __builtin_amdgcn_global_load_lds((const unsigned*)((const char*)(gbase) + (voff)[_i]), (PG8_LAS unsigned*)(lds + (bufoff) + ldsw + _i * 8192), 16, 0, 0); } while (0)
; #define PG8_LDA(dst, b, h) do { _Pragma("unroll") for (int m = 0; m < 4; ++m) _Pragma("unroll") for (int k = 0; k < 2; ++k) dst[m][k] = *(const PG8_LAS bf16x8*)(lds + PG8_SA(b, h) + aoff + m * 2048 + k * 1024); } while (0)
; #define PG8_LDB(dst, b, h) do { _Pragma("unroll") for (int n = 0; n < 2; ++n) _Pragma("unroll") for (int k = 0; k < 2; ++k) dst[n][k] = *(const PG8_LAS bf16x8*)(lds + PG8_SB(b, h) + boff + n * 2048 + k * 1024); } while (0)
; #define PG8_MMA(ai, bj, At, Bt) do { __builtin_amdgcn_s_setprio(1); _Pragma("unroll") for (int m = 0; m < 4; ++m) _Pragma("unroll") for (int n = 0; n < 2; ++n) _Pragma("unroll") for (int k = 0; k < 2; ++k) \
;         acc[ai][bj][m][n] = __builtin_amdgcn_mfma_f32_16x16x32_bf16(Bt[n][k], At[m][k], acc[ai][bj][m][n], 0, 0, 0); __builtin_amdgcn_s_setprio(0); } while (0)
; #define PG8_WAIT_V(n) asm volatile("s_waitcnt vmcnt(" #n ")" ::: "memory")
; #define PG8_WAIT_L(n) asm volatile("s_waitcnt lgkmcnt(" #n ")" ::: "memory")
; #define PG8_BAR __builtin_amdgcn_s_barrier()
; #define PG8_SCHED __builtin_amdgcn_sched_barrier(0)
; template <class Epi, class Sched, bool ALIGN_EPI = false, bool SP2 = false>
; __device__ __forceinline__ void gemm_phase(PG8_LAS unsigned char* lds, const Gemm g, const Sched& S, const Epi& E) {
;     ...
;             PG8_LDB(B0, 1, 0); PG8_LDB(B1, 1, 1); PG8_SCHED; PG8_LDA(At, 1, 0); PG8_STAGE(PG8_SA(0, 1), a2 + hstep, voffA);
;             PG8_WAIT_V(8); PG8_WAIT_L(0); PG8_BAR; PG8_MMA(0, 0, At, B0); PG8_MMA(0, 1, At, B1); PG8_BAR; PG8_SCHED;
;             PG8_LDA(At, 1, 1); PG8_STAGE(PG8_SB(1, 0), b3, voffB); PG8_STAGE(PG8_SB(1, 1), b3 + hstep, voffB); PG8_STAGE(PG8_SA(1, 0), a3, voffA);
;             PG8_WAIT_V(8); PG8_WAIT_L(0); PG8_BAR; PG8_MMA(1, 0, At, B0); PG8_MMA(1, 1, At, B1); PG8_BAR; PG8_SCHED;
;     ...
;         if constexpr (ALIGN_EPI) { if (wr == 0) PG8_BAR; }
	s_setprio 0
	s_add_i32 s73, 0, 0x18000
	s_add_i32 vcc_lo, 0, 0x1c000
	ds_read_b128 v[132:135], v162 offset:32768
	ds_read_b128 v[136:139], v162 offset:33792
	ds_read_b128 v[140:143], v162 offset:34816
	ds_read_b128 v[154:157], v162 offset:35840
	ds_read_b128 v[158:161], v162 offset:49152
	ds_read_b128 v[170:173], v162 offset:50176
	ds_read_b128 v[174:177], v162 offset:51200
	ds_read_b128 v[178:181], v162 offset:52224
	s_add_u32 s24, s34, 0x2b0000
	s_addc_u32 s25, s35, 0
	s_mov_b32 m0, s94
	ds_read_b128 v[182:185], v169 offset:32768
	ds_read_b128 v[186:189], v169 offset:33792
	ds_read_b128 v[190:193], v169 offset:34816
	ds_read_b128 v[194:197], v169 offset:35840
	ds_read_b128 v[198:201], v169 offset:36864
	ds_read_b128 v[202:205], v169 offset:37888
	ds_read_b128 v[206:209], v169 offset:38912
	ds_read_b128 v[210:213], v169 offset:39936
	global_load_lds_dwordx4 v144, s[24:25]
	s_mov_b32 m0, s95
	s_nop 0
	global_load_lds_dwordx4 v146, s[24:25]
	s_waitcnt vmcnt(8)
	s_waitcnt lgkmcnt(0)
	s_setprio 1
	s_barrier
	v_mfma_f32_16x16x32_bf16 v[128:131], v[132:135], v[182:185], v[128:131]
	v_mfma_f32_16x16x32_bf16 v[124:127], v[140:143], v[182:185], v[124:127]
	v_mfma_f32_16x16x32_bf16 v[116:119], v[140:143], v[190:193], v[116:119]
	v_mfma_f32_16x16x32_bf16 v[120:123], v[132:135], v[190:193], v[120:123]
	v_mfma_f32_16x16x32_bf16 v[112:115], v[132:135], v[198:201], v[112:115]
	v_mfma_f32_16x16x32_bf16 v[108:111], v[140:143], v[198:201], v[108:111]
	v_mfma_f32_16x16x32_bf16 v[100:103], v[140:143], v[206:209], v[100:103]
	v_mfma_f32_16x16x32_bf16 v[104:107], v[132:135], v[206:209], v[104:107]
	v_mfma_f32_16x16x32_bf16 v[128:131], v[136:139], v[186:189], v[128:131]
	v_mfma_f32_16x16x32_bf16 v[124:127], v[154:157], v[186:189], v[124:127]
	v_mfma_f32_16x16x32_bf16 v[116:119], v[154:157], v[194:197], v[116:119]
	v_mfma_f32_16x16x32_bf16 v[120:123], v[136:139], v[194:197], v[120:123]
	v_mfma_f32_16x16x32_bf16 v[112:115], v[136:139], v[202:205], v[112:115]
	v_mfma_f32_16x16x32_bf16 v[108:111], v[154:157], v[202:205], v[108:111]
	v_mfma_f32_16x16x32_bf16 v[100:103], v[154:157], v[210:213], v[100:103]
	v_mfma_f32_16x16x32_bf16 v[104:107], v[136:139], v[210:213], v[104:107]
	s_setprio 0
	s_setprio 1
	v_mfma_f32_16x16x32_bf16 v[96:99], v[158:161], v[182:185], v[96:99]
	v_mfma_f32_16x16x32_bf16 v[92:95], v[174:177], v[182:185], v[92:95]
	v_mfma_f32_16x16x32_bf16 v[84:87], v[174:177], v[190:193], v[84:87]
	v_mfma_f32_16x16x32_bf16 v[88:91], v[158:161], v[190:193], v[88:91]
	v_mfma_f32_16x16x32_bf16 v[80:83], v[158:161], v[198:201], v[80:83]
	v_mfma_f32_16x16x32_bf16 v[76:79], v[174:177], v[198:201], v[76:79]
	v_mfma_f32_16x16x32_bf16 v[68:71], v[174:177], v[206:209], v[68:71]
	v_mfma_f32_16x16x32_bf16 v[72:75], v[158:161], v[206:209], v[72:75]
	v_mfma_f32_16x16x32_bf16 v[96:99], v[170:173], v[186:189], v[96:99]
	v_mfma_f32_16x16x32_bf16 v[92:95], v[178:181], v[186:189], v[92:95]
	v_mfma_f32_16x16x32_bf16 v[84:87], v[178:181], v[194:197], v[84:87]
	v_mfma_f32_16x16x32_bf16 v[88:91], v[170:173], v[194:197], v[88:91]
	v_mfma_f32_16x16x32_bf16 v[80:83], v[170:173], v[202:205], v[80:83]
	v_mfma_f32_16x16x32_bf16 v[76:79], v[178:181], v[202:205], v[76:79]
	v_mfma_f32_16x16x32_bf16 v[68:71], v[178:181], v[210:213], v[68:71]
	v_mfma_f32_16x16x32_bf16 v[72:75], v[170:173], v[210:213], v[72:75]
	s_barrier
	s_setprio 0
	s_add_i32 s24, s73, s83
	s_add_u32 s100, s26, 0x80
	s_addc_u32 s101, s27, 0
	s_mov_b32 m0, s24
	ds_read_b128 v[182:185], v169 offset:49152
	ds_read_b128 v[186:189], v169 offset:50176
	ds_read_b128 v[190:193], v169 offset:51200
	ds_read_b128 v[194:197], v169 offset:52224
	ds_read_b128 v[198:201], v169 offset:53248
	ds_read_b128 v[202:205], v169 offset:54272
	ds_read_b128 v[206:209], v169 offset:55296
	ds_read_b128 v[210:213], v169 offset:56320
	global_load_lds_dwordx4 v2, s[100:101]
	s_add_i32 m0, s24, 0x2000
	s_add_u32 s24, s26, 0x2b0080
	s_addc_u32 s25, s27, 0
	s_add_i32 s26, vcc_lo, s83
	global_load_lds_dwordx4 v148, s[100:101]
	s_mov_b32 m0, s26
	s_nop 0
	global_load_lds_dwordx4 v2, s[24:25]
	s_add_i32 m0, s26, 0x2000
	s_nop 0
	global_load_lds_dwordx4 v148, s[24:25]
	s_add_u32 s100, s34, 0x80
	s_addc_u32 s101, s35, 0
	s_mov_b32 m0, s65
	s_nop 0
	global_load_lds_dwordx4 v144, s[100:101]
	s_mov_b32 m0, s4
	s_nop 0
	global_load_lds_dwordx4 v146, s[100:101]
	s_waitcnt vmcnt(8)
	s_waitcnt lgkmcnt(0)
	s_setprio 1
	s_barrier
	v_mfma_f32_16x16x32_bf16 v[64:67], v[132:135], v[182:185], v[64:67]
	v_mfma_f32_16x16x32_bf16 v[60:63], v[140:143], v[182:185], v[60:63]
	v_mfma_f32_16x16x32_bf16 v[52:55], v[140:143], v[190:193], v[52:55]
	v_mfma_f32_16x16x32_bf16 v[56:59], v[132:135], v[190:193], v[56:59]
	v_mfma_f32_16x16x32_bf16 v[48:51], v[132:135], v[198:201], v[48:51]
	v_mfma_f32_16x16x32_bf16 v[44:47], v[140:143], v[198:201], v[44:47]
	v_mfma_f32_16x16x32_bf16 v[36:39], v[140:143], v[206:209], v[36:39]
	v_mfma_f32_16x16x32_bf16 v[40:43], v[132:135], v[206:209], v[40:43]
	v_mfma_f32_16x16x32_bf16 v[64:67], v[136:139], v[186:189], v[64:67]
	v_mfma_f32_16x16x32_bf16 v[60:63], v[154:157], v[186:189], v[60:63]
	v_mfma_f32_16x16x32_bf16 v[52:55], v[154:157], v[194:197], v[52:55]
	v_mfma_f32_16x16x32_bf16 v[56:59], v[136:139], v[194:197], v[56:59]
	v_mfma_f32_16x16x32_bf16 v[48:51], v[136:139], v[202:205], v[48:51]
	v_mfma_f32_16x16x32_bf16 v[44:47], v[154:157], v[202:205], v[44:47]
	v_mfma_f32_16x16x32_bf16 v[36:39], v[154:157], v[210:213], v[36:39]
	v_mfma_f32_16x16x32_bf16 v[40:43], v[136:139], v[210:213], v[40:43]
	s_setprio 0
	s_setprio 1
	v_mfma_f32_16x16x32_bf16 v[32:35], v[158:161], v[182:185], v[32:35]
	v_mfma_f32_16x16x32_bf16 v[28:31], v[174:177], v[182:185], v[28:31]
	v_mfma_f32_16x16x32_bf16 v[20:23], v[174:177], v[190:193], v[20:23]
	v_mfma_f32_16x16x32_bf16 v[24:27], v[158:161], v[190:193], v[24:27]
	v_mfma_f32_16x16x32_bf16 v[16:19], v[158:161], v[198:201], v[16:19]
	v_mfma_f32_16x16x32_bf16 v[12:15], v[174:177], v[198:201], v[12:15]
	v_mfma_f32_16x16x32_bf16 v[4:7], v[174:177], v[206:209], v[4:7]
	v_mfma_f32_16x16x32_bf16 v[8:11], v[158:161], v[206:209], v[8:11]
	v_mfma_f32_16x16x32_bf16 v[32:35], v[170:173], v[186:189], v[32:35]
	v_mfma_f32_16x16x32_bf16 v[28:31], v[178:181], v[186:189], v[28:31]
	v_mfma_f32_16x16x32_bf16 v[20:23], v[178:181], v[194:197], v[20:23]
	v_mfma_f32_16x16x32_bf16 v[24:27], v[170:173], v[194:197], v[24:27]
	v_mfma_f32_16x16x32_bf16 v[16:19], v[170:173], v[202:205], v[16:19]
	v_mfma_f32_16x16x32_bf16 v[12:15], v[178:181], v[202:205], v[12:15]
	v_mfma_f32_16x16x32_bf16 v[4:7], v[178:181], v[210:213], v[4:7]
	v_mfma_f32_16x16x32_bf16 v[8:11], v[170:173], v[210:213], v[8:11]
	s_barrier
	s_setprio 0
	s_add_u32 s45, s45, 0x100
	s_addc_u32 s47, s47, 0
	s_cmp_ge_i32 s72, s46
	s_mov_b64 s[24:25], s[0:1]
	s_mov_b32 s26, s72
	s_cbranch_scc0 .LBB0_3627
	s_and_b64 vcc, exec, s[50:51]
	s_cbranch_vccz .LBB0_3630
	s_barrier
